# MLA loop code placement: instruction order/encodings chosen so that every 8-byte instruction (MFMA, DS, VOP3) starts 8-byte aligned
# baseline (speedup 1.0000x reference)
; template <int VAR>
; __device__ __forceinline__ void attn_phase(LAS unsigned char* lds, const AttnP P, int vcu, int G, int wave_s) {
;     ...
;         for (int t = 0; t < nt; ++t) {
;             const bool hn = (t + 1 < nt);
;     ...
;                 if (ND0 == 6) {
;                     KR1(0); KR1(1); KR1(2); KR1(3); SB();
;                     QK1(0, negm); EX2(pc0, 0, w0.x); KR1(4); SB();
;                     QK1(1, negm); EX2(pc0, 2, w0.y); KR1(5); SB();
;                     QK1(2, pn0); EX2(pc0, 4, w0.z); KR1(6); SB();
;                     QK1(3, pn1); EX2(pc0, 6, w0.w); KR1(7); SB();
;                     QK1(4, pn0); EX2(pc0, 8, w1.x); KR1(8); SB();
;                     QK1(5, pn1); EX2(pc0, 10, w1.y); KR1(9); SB();
;                     QK1(6, pn0); EX2(pc0, 12, w1.z); KR1(10); SB();
;                     QK1(7, pn1); EX2(pc0, 14, w1.w); KR1(11); SB();
;                     QK1(8, pn0); EX2(pc1, 0, w2.x); VR1(0); SB();
;                     QK1(9, pn1); EX2(pc1, 2, w2.y); VR1(1); SB();
;                     QK1(10, pn0); EX2(pc1, 4, w2.z); VR1(2); SB();
;                     QK1(11, pn1); EX2(pc1, 6, w2.w); VR1(3); SB();
;                 } else {
;                     KR1(0); KR1(1); KR1(2); KR1(3); SB();
;                     QK1(0, negm); EX2(pc0, 0, w0.x); EX2(pc0, 2, w0.y); KR1(4); SB();
;                     QK1(1, negm); EX2(pc0, 4, w0.z); EX2(pc0, 6, w0.w); KR1(5); SB();
;                     QK1(2, pn0); EX2(pc0, 8, w1.x); EX2(pc0, 10, w1.y); KR1(6); SB();
;                     QK1(3, pn1); EX2(pc0, 12, w1.z); EX2(pc0, 14, w1.w); KR1(7); SB();
;                     QK1(4, pn0); EX2(pc1, 0, w2.x); VR1(0); SB();
;                     QK1(5, pn1); EX2(pc1, 2, w2.y); VR1(1); SB();
;                     QK1(6, pn0); EX2(pc1, 4, w2.z); VR1(2); SB();
;                     QK1(7, pn1); EX2(pc1, 6, w2.w); VR1(3); SB();
;                 }
;                 PV1(0, w0); EX2(pc1, 8, w3.x); VR1(4); SB();
;                 PV1(1, w0); EX2(pc1, 10, w3.y); VR1(5); SB();
;                 PV1(2, w1); EX2(pc1, 12, w3.z); VR1(6); SB();
;                 PV1(3, w1); EX2(pc1, 14, w3.w); VR1(7); SB();
;                 lrun += sacc;
;                 PV1(4, w2); MASK_TILE(pn0, pn1, t + 1); SB();
;                 PV1(5, w2); SB();
;                 PV1(6, w3); SB();
;                 PV1(7, w3); rmn = rowmax32(pn0, pn1); if (!USE_NEGM) rmn -= mref; SB();
.Lmla_p0_go:
	v_exp_f32_e32 v222, v34
	v_exp_f32_e32 v223, v35
	v_add_f32_e32 v164, 0, v222
	v_add_f32_e32 v164, v223, v164
	v_cvt_pk_bf16_f32 v206, v222, v223
	v_exp_f32_e32 v224, v36
	v_exp_f32_e32 v225, v37
	v_add_f32_e32 v164, v224, v164
	v_add_f32_e32 v164, v225, v164
	v_cvt_pk_bf16_f32 v207, v224, v225
	v_exp_f32_e32 v222, v38
	s_waitcnt lgkmcnt(3)
	v_mfma_f32_32x32x16_bf16 v[82:97], v[182:185], v[114:117], v[66:81]
	ds_read_b128 v[198:201], v174 offset:22592
	v_exp_f32_e32 v223, v39
	v_add_f32_e32 v164, v222, v164
	v_cvt_pk_bf16_f32 v208, v222, v223
	v_add_f32_e64 v164, v223, v164
	v_exp_f32_e32 v224, v40
	s_waitcnt lgkmcnt(3)
	v_mfma_f32_32x32x16_bf16 v[98:113], v[186:189], v[114:117], v[66:81]
	ds_read_b128 v[182:185], v174 offset:29248
	v_exp_f32_e32 v225, v41
	v_add_f32_e32 v164, v224, v164
	v_cvt_pk_bf16_f32 v209, v224, v225
	v_add_f32_e64 v164, v225, v164
	v_exp_f32_e32 v222, v42
	s_waitcnt lgkmcnt(3)
	v_mfma_f32_32x32x16_bf16 v[82:97], v[190:193], v[118:121], v[82:97]
	ds_read_b128 v[186:189], v174 offset:22624
	v_exp_f32_e32 v223, v43
	v_add_f32_e32 v164, v222, v164
	v_cvt_pk_bf16_f32 v210, v222, v223
	v_add_f32_e64 v164, v223, v164
	v_exp_f32_e32 v224, v44
	s_waitcnt lgkmcnt(3)
	v_mfma_f32_32x32x16_bf16 v[98:113], v[194:197], v[118:121], v[98:113]
	ds_read_b128 v[190:193], v174 offset:29280
	v_exp_f32_e32 v225, v45
	v_add_f32_e32 v164, v224, v164
	v_cvt_pk_bf16_f32 v211, v224, v225
	v_add_f32_e64 v164, v225, v164
	v_exp_f32_e32 v222, v46
	s_waitcnt lgkmcnt(3)
	v_mfma_f32_32x32x16_bf16 v[82:97], v[198:201], v[122:125], v[82:97]
	ds_read_b128 v[194:197], v174 offset:22656
	v_exp_f32_e32 v223, v47
	v_add_f32_e32 v164, v222, v164
	v_cvt_pk_bf16_f32 v212, v222, v223
	v_add_f32_e64 v164, v223, v164
	v_exp_f32_e32 v224, v48
	s_waitcnt lgkmcnt(3)
	v_mfma_f32_32x32x16_bf16 v[98:113], v[182:185], v[122:125], v[98:113]
	ds_read_b128 v[198:201], v174 offset:29312
	v_exp_f32_e32 v225, v49
	v_add_f32_e32 v164, v224, v164
	v_cvt_pk_bf16_f32 v213, v224, v225
	v_add_f32_e64 v164, v225, v164
	v_exp_f32_e32 v222, v50
	s_waitcnt lgkmcnt(3)
	v_mfma_f32_32x32x16_bf16 v[82:97], v[186:189], v[126:129], v[82:97]
	ds_read_b128 v[182:185], v174 offset:22688
	v_exp_f32_e32 v223, v51
	v_add_f32_e32 v164, v222, v164
	v_cvt_pk_bf16_f32 v214, v222, v223
	v_add_f32_e64 v164, v223, v164
	v_exp_f32_e32 v224, v52
	s_waitcnt lgkmcnt(3)
	v_mfma_f32_32x32x16_bf16 v[98:113], v[190:193], v[126:129], v[98:113]
	ds_read_b128 v[186:189], v174 offset:29344
	v_exp_f32_e32 v225, v53
	v_add_f32_e32 v164, v224, v164
	v_cvt_pk_bf16_f32 v215, v224, v225
	v_add_f32_e64 v164, v225, v164
	v_exp_f32_e32 v222, v54
	s_waitcnt lgkmcnt(3)
	v_mfma_f32_32x32x16_bf16 v[82:97], v[194:197], v[130:133], v[82:97]
	ds_read_b128 v[190:193], v228 offset:13312
	v_exp_f32_e32 v223, v55
	v_add_f32_e32 v164, v222, v164
	v_cvt_pk_bf16_f32 v216, v222, v223
	v_add_f32_e64 v164, v223, v164
	v_exp_f32_e32 v224, v56
	s_waitcnt lgkmcnt(3)
	v_mfma_f32_32x32x16_bf16 v[98:113], v[198:201], v[130:133], v[98:113]
	ds_read_b128 v[194:197], v228 offset:17920
	v_exp_f32_e32 v225, v57
	v_add_f32_e32 v164, v224, v164
	v_cvt_pk_bf16_f32 v217, v224, v225
	v_add_f32_e64 v164, v225, v164
	v_exp_f32_e32 v222, v58
	s_waitcnt lgkmcnt(3)
	v_mfma_f32_32x32x16_bf16 v[82:97], v[182:185], v[134:137], v[82:97]
	ds_read_b128 v[198:201], v228 offset:13344
	v_exp_f32_e32 v223, v59
	v_add_f32_e32 v164, v222, v164
	v_cvt_pk_bf16_f32 v218, v222, v223
	v_add_f32_e64 v164, v223, v164
	v_exp_f32_e32 v224, v60
	s_waitcnt lgkmcnt(3)
	v_mfma_f32_32x32x16_bf16 v[98:113], v[186:189], v[134:137], v[98:113]
	ds_read_b128 v[182:185], v228 offset:17952
	v_exp_f32_e32 v225, v61
	v_add_f32_e32 v164, v224, v164
	v_cvt_pk_bf16_f32 v219, v224, v225
	v_add_f32_e64 v164, v225, v164
	v_exp_f32_e32 v222, v62
	s_waitcnt lgkmcnt(3)
	v_mfma_f32_32x32x16_bf16 v[2:17], v[190:193], v[206:209], v[2:17]
	ds_read_b128 v[186:189], v228 offset:13376
	v_exp_f32_e32 v223, v63
	v_add_f32_e32 v164, v222, v164
	v_cvt_pk_bf16_f32 v220, v222, v223
	v_add_f32_e64 v164, v223, v164
	v_exp_f32_e32 v224, v64
	s_waitcnt lgkmcnt(3)
	v_mfma_f32_32x32x16_bf16 v[18:33], v[194:197], v[206:209], v[18:33]
	ds_read_b128 v[190:193], v228 offset:17984
	v_exp_f32_e32 v225, v65
	v_add_f32_e32 v164, v224, v164
	v_cvt_pk_bf16_f32 v221, v224, v225
	v_add_f32_e64 v164, v225, v164
	s_mov_b32 s13, s20
	s_mov_b32 s20, s19
	s_add_i32 s19, s19, 1
	s_cmp_eq_u32 s19, s9
	s_cselect_b32 s19, 0, s19
	s_nop 0
	s_waitcnt lgkmcnt(3)
	s_waitcnt vmcnt(2)
	v_mfma_f32_32x32x16_bf16 v[2:17], v[198:201], v[210:213], v[2:17]
	ds_read_b128 v[194:197], v228 offset:13408
	v_max3_f32 v224, v82, v83, v84
	v_max3_f32 v225, v98, v99, v100
	v_max3_f32 v224, v224, v85, v86
	v_max3_f32 v225, v225, v101, v102
	v_add_u32_e32 v222, 0xb000, v172
	ds_write_b128 v222, v[146:149] offset:26624
	v_lshl_add_u32 v222, s19, 17, v178
	global_load_dwordx4 v[146:149], v222, s[52:53]
	s_waitcnt lgkmcnt(4)
	s_and_b64 vcc, exec, s[2:3]
	v_mfma_f32_32x32x16_bf16 v[18:33], v[182:185], v[210:213], v[18:33]
	ds_read_b128 v[198:201], v228 offset:18016
	v_max3_f32 v224, v224, v87, v88
	v_max3_f32 v225, v225, v103, v104
	v_max3_f32 v224, v224, v89, v90
	v_max3_f32 v225, v225, v105, v106
	s_cbranch_vccz .Lmla_p0_nope
	s_nop 0
	v_add_u32_e32 v222, 0xb000, v176
	ds_write_b128 v222, v[138:141] offset:26752
	v_lshl_add_u32 v222, s19, 12, v179
	global_load_dwordx4 v[138:141], v222, s[62:63]
.Lmla_p0_nope:
	s_waitcnt lgkmcnt(4)
	s_nop 0
	v_mfma_f32_32x32x16_bf16 v[2:17], v[186:189], v[214:217], v[2:17]
	ds_read_b128 v[182:185], v174 offset:45056
	v_max3_f32 v224, v224, v91, v92
	v_max3_f32 v225, v225, v107, v108
	v_max3_f32 v224, v224, v93, v94
	v_max3_f32 v225, v225, v109, v110
	v_add_u32_e32 v222, 0xb000, v173
	ds_write_b128 v222, v[142:145] offset:39936
	v_lshl_add_u32 v222, s13, 7, v168
	global_load_dwordx4 v[142:145], v222, s[56:57]
	s_waitcnt lgkmcnt(5)
	s_nop 0
	v_mfma_f32_32x32x16_bf16 v[18:33], v[190:193], v[214:217], v[18:33]
	ds_read_b128 v[186:189], v174 offset:51712
	v_max3_f32 v224, v224, v95, v96
	v_max3_f32 v225, v225, v111, v112
	v_max3_f32 v224, v224, v97, v113
	v_max_f32_e64 v224, v224, v225
	s_waitcnt lgkmcnt(5)
	v_mov_b32_e32 v225, v224
	v_mfma_f32_32x32x16_bf16 v[2:17], v[194:197], v[218:221], v[2:17]
	ds_read_b128 v[190:193], v174 offset:45088
	v_add_f32_e32 v1, v1, v164
	s_add_i32 s11, s11, 1
	v_permlane32_swap_b32_e32 v224, v225
	s_cmp_eq_u32 s9, s11
	v_max_f32_e64 v167, v224, v225
	v_cmp_lt_f32_e32 vcc, s66, v167
	s_waitcnt lgkmcnt(4)
	v_mfma_f32_32x32x16_bf16 v[18:33], v[198:201], v[218:221], v[18:33]
	ds_read_b128 v[194:197], v174 offset:51744
	s_cbranch_scc1 .Lmla_exit_p0

; template <int VAR>
; __device__ __forceinline__ void attn_phase(LAS unsigned char* lds, const AttnP P, int vcu, int G, int wave_s) {
;     ...
;         for (int t = 0; t < nt; ++t) {
;             const bool hn = (t + 1 < nt);
;     ...
;                 if (ND0 == 6) {
;                     KR1(0); KR1(1); KR1(2); KR1(3); SB();
;                     QK1(0, negm); EX2(pc0, 0, w0.x); KR1(4); SB();
;                     QK1(1, negm); EX2(pc0, 2, w0.y); KR1(5); SB();
;                     QK1(2, pn0); EX2(pc0, 4, w0.z); KR1(6); SB();
;                     QK1(3, pn1); EX2(pc0, 6, w0.w); KR1(7); SB();
;                     QK1(4, pn0); EX2(pc0, 8, w1.x); KR1(8); SB();
;                     QK1(5, pn1); EX2(pc0, 10, w1.y); KR1(9); SB();
;                     QK1(6, pn0); EX2(pc0, 12, w1.z); KR1(10); SB();
;                     QK1(7, pn1); EX2(pc0, 14, w1.w); KR1(11); SB();
;                     QK1(8, pn0); EX2(pc1, 0, w2.x); VR1(0); SB();
;                     QK1(9, pn1); EX2(pc1, 2, w2.y); VR1(1); SB();
;                     QK1(10, pn0); EX2(pc1, 4, w2.z); VR1(2); SB();
;                     QK1(11, pn1); EX2(pc1, 6, w2.w); VR1(3); SB();
;                 } else {
;                     KR1(0); KR1(1); KR1(2); KR1(3); SB();
;                     QK1(0, negm); EX2(pc0, 0, w0.x); EX2(pc0, 2, w0.y); KR1(4); SB();
;                     QK1(1, negm); EX2(pc0, 4, w0.z); EX2(pc0, 6, w0.w); KR1(5); SB();
;                     QK1(2, pn0); EX2(pc0, 8, w1.x); EX2(pc0, 10, w1.y); KR1(6); SB();
;                     QK1(3, pn1); EX2(pc0, 12, w1.z); EX2(pc0, 14, w1.w); KR1(7); SB();
;                     QK1(4, pn0); EX2(pc1, 0, w2.x); VR1(0); SB();
;                     QK1(5, pn1); EX2(pc1, 2, w2.y); VR1(1); SB();
;                     QK1(6, pn0); EX2(pc1, 4, w2.z); VR1(2); SB();
;                     QK1(7, pn1); EX2(pc1, 6, w2.w); VR1(3); SB();
;                 }
;                 PV1(0, w0); EX2(pc1, 8, w3.x); VR1(4); SB();
;                 PV1(1, w0); EX2(pc1, 10, w3.y); VR1(5); SB();
;                 PV1(2, w1); EX2(pc1, 12, w3.z); VR1(6); SB();
;                 PV1(3, w1); EX2(pc1, 14, w3.w); VR1(7); SB();
;                 lrun += sacc;
;                 PV1(4, w2); MASK_TILE(pn0, pn1, t + 1); SB();
;                 PV1(5, w2); SB();
;                 PV1(6, w3); SB();
;                 PV1(7, w3); rmn = rowmax32(pn0, pn1); if (!USE_NEGM) rmn -= mref; SB();
.Lmla_p1_go:
	v_exp_f32_e32 v222, v82
	v_exp_f32_e32 v223, v83
	v_add_f32_e32 v164, 0, v222
	v_add_f32_e32 v164, v223, v164
	v_cvt_pk_bf16_f32 v206, v222, v223
	v_exp_f32_e32 v224, v84
	v_exp_f32_e32 v225, v85
	v_add_f32_e32 v164, v224, v164
	v_add_f32_e32 v164, v225, v164
	v_cvt_pk_bf16_f32 v207, v224, v225
	v_exp_f32_e32 v222, v86
	s_waitcnt lgkmcnt(4)
	v_mfma_f32_32x32x16_bf16 v[34:49], v[182:185], v[114:117], v[66:81]
	ds_read_b128 v[198:201], v174 offset:45120
	v_exp_f32_e32 v223, v87
	v_add_f32_e32 v164, v222, v164
	v_cvt_pk_bf16_f32 v208, v222, v223
	v_add_f32_e64 v164, v223, v164
	v_exp_f32_e32 v224, v88
	s_waitcnt lgkmcnt(3)
	v_mfma_f32_32x32x16_bf16 v[50:65], v[186:189], v[114:117], v[66:81]
	ds_read_b128 v[182:185], v174 offset:51776
	v_exp_f32_e32 v225, v89
	v_add_f32_e32 v164, v224, v164
	v_cvt_pk_bf16_f32 v209, v224, v225
	v_add_f32_e64 v164, v225, v164
	v_exp_f32_e32 v222, v90
	s_waitcnt lgkmcnt(3)
	v_mfma_f32_32x32x16_bf16 v[34:49], v[190:193], v[118:121], v[34:49]
	ds_read_b128 v[186:189], v174 offset:45152
	v_exp_f32_e32 v223, v91
	v_add_f32_e32 v164, v222, v164
	v_cvt_pk_bf16_f32 v210, v222, v223
	v_add_f32_e64 v164, v223, v164
	v_exp_f32_e32 v224, v92
	s_waitcnt lgkmcnt(3)
	v_mfma_f32_32x32x16_bf16 v[50:65], v[194:197], v[118:121], v[50:65]
	ds_read_b128 v[190:193], v174 offset:51808
	v_exp_f32_e32 v225, v93
	v_add_f32_e32 v164, v224, v164
	v_cvt_pk_bf16_f32 v211, v224, v225
	v_add_f32_e64 v164, v225, v164
	v_exp_f32_e32 v222, v94
	s_waitcnt lgkmcnt(3)
	v_mfma_f32_32x32x16_bf16 v[34:49], v[198:201], v[122:125], v[34:49]
	ds_read_b128 v[194:197], v174 offset:45184
	v_exp_f32_e32 v223, v95
	v_add_f32_e32 v164, v222, v164
	v_cvt_pk_bf16_f32 v212, v222, v223
	v_add_f32_e64 v164, v223, v164
	v_exp_f32_e32 v224, v96
	s_waitcnt lgkmcnt(3)
	v_mfma_f32_32x32x16_bf16 v[50:65], v[182:185], v[122:125], v[50:65]
	ds_read_b128 v[198:201], v174 offset:51840
	v_exp_f32_e32 v225, v97
	v_add_f32_e32 v164, v224, v164
	v_cvt_pk_bf16_f32 v213, v224, v225
	v_add_f32_e64 v164, v225, v164
	v_exp_f32_e32 v222, v98
	s_waitcnt lgkmcnt(3)
	v_mfma_f32_32x32x16_bf16 v[34:49], v[186:189], v[126:129], v[34:49]
	ds_read_b128 v[182:185], v174 offset:45216
	v_exp_f32_e32 v223, v99
	v_add_f32_e32 v164, v222, v164
	v_cvt_pk_bf16_f32 v214, v222, v223
	v_add_f32_e64 v164, v223, v164
	v_exp_f32_e32 v224, v100
	s_waitcnt lgkmcnt(3)
	v_mfma_f32_32x32x16_bf16 v[50:65], v[190:193], v[126:129], v[50:65]
	ds_read_b128 v[186:189], v174 offset:51872
	v_exp_f32_e32 v225, v101
	v_add_f32_e32 v164, v224, v164
	v_cvt_pk_bf16_f32 v215, v224, v225
	v_add_f32_e64 v164, v225, v164
	v_exp_f32_e32 v222, v102
	s_waitcnt lgkmcnt(3)
	v_mfma_f32_32x32x16_bf16 v[34:49], v[194:197], v[130:133], v[34:49]
	ds_read_b128 v[190:193], v228 offset:35840
	v_exp_f32_e32 v223, v103
	v_add_f32_e32 v164, v222, v164
	v_cvt_pk_bf16_f32 v216, v222, v223
	v_add_f32_e64 v164, v223, v164
	v_exp_f32_e32 v224, v104
	s_waitcnt lgkmcnt(3)
	v_mfma_f32_32x32x16_bf16 v[50:65], v[198:201], v[130:133], v[50:65]
	ds_read_b128 v[194:197], v228 offset:40448
	v_exp_f32_e32 v225, v105
	v_add_f32_e32 v164, v224, v164
	v_cvt_pk_bf16_f32 v217, v224, v225
	v_add_f32_e64 v164, v225, v164
	v_exp_f32_e32 v222, v106
	s_waitcnt lgkmcnt(3)
	v_mfma_f32_32x32x16_bf16 v[34:49], v[182:185], v[134:137], v[34:49]
	ds_read_b128 v[198:201], v228 offset:35872
	v_exp_f32_e32 v223, v107
	v_add_f32_e32 v164, v222, v164
	v_cvt_pk_bf16_f32 v218, v222, v223
	v_add_f32_e64 v164, v223, v164
	v_exp_f32_e32 v224, v108
	s_waitcnt lgkmcnt(3)
	v_mfma_f32_32x32x16_bf16 v[50:65], v[186:189], v[134:137], v[50:65]
	ds_read_b128 v[182:185], v228 offset:40480
	v_exp_f32_e32 v225, v109
	v_add_f32_e32 v164, v224, v164
	v_cvt_pk_bf16_f32 v219, v224, v225
	v_add_f32_e64 v164, v225, v164
	v_exp_f32_e32 v222, v110
	s_waitcnt lgkmcnt(3)
	v_mfma_f32_32x32x16_bf16 v[2:17], v[190:193], v[206:209], v[2:17]
	ds_read_b128 v[186:189], v228 offset:35904
	v_exp_f32_e32 v223, v111
	v_add_f32_e32 v164, v222, v164
	v_cvt_pk_bf16_f32 v220, v222, v223
	v_add_f32_e64 v164, v223, v164
	v_exp_f32_e32 v224, v112
	s_waitcnt lgkmcnt(3)
	v_mfma_f32_32x32x16_bf16 v[18:33], v[194:197], v[206:209], v[18:33]
	ds_read_b128 v[190:193], v228 offset:40512
	v_exp_f32_e32 v225, v113
	v_add_f32_e32 v164, v224, v164
	v_cvt_pk_bf16_f32 v221, v224, v225
	v_add_f32_e64 v164, v225, v164
	s_mov_b32 s13, s20
	s_mov_b32 s20, s19
	s_add_i32 s19, s19, 1
	s_cmp_eq_u32 s19, s9
	s_cselect_b32 s19, 0, s19
	s_nop 0
	s_waitcnt lgkmcnt(3)
	s_waitcnt vmcnt(2)
	v_mfma_f32_32x32x16_bf16 v[2:17], v[198:201], v[210:213], v[2:17]
	ds_read_b128 v[194:197], v228 offset:35936
	v_max3_f32 v224, v34, v35, v36
	v_max3_f32 v225, v50, v51, v52
	v_max3_f32 v224, v224, v37, v38
	v_max3_f32 v225, v225, v53, v54
	ds_write_b128 v172, v[150:153]
	v_lshl_add_u32 v222, s19, 17, v178
	global_load_dwordx4 v[150:153], v222, s[52:53]
	s_waitcnt lgkmcnt(4)
	s_and_b64 vcc, exec, s[2:3]
	v_mfma_f32_32x32x16_bf16 v[18:33], v[182:185], v[210:213], v[18:33]
	ds_read_b128 v[198:201], v228 offset:40544
	v_max3_f32 v224, v224, v39, v40
	v_max3_f32 v225, v225, v55, v56
	v_max3_f32 v224, v224, v41, v42
	v_max3_f32 v225, v225, v57, v58
	s_cbranch_vccz .Lmla_p1_nope
	s_nop 0
	ds_write_b128 v176, v[160:163] offset:128
	v_lshl_add_u32 v222, s19, 12, v179
	global_load_dwordx4 v[160:163], v222, s[62:63]
.Lmla_p1_nope:
	s_waitcnt lgkmcnt(4)
	s_nop 0
	v_mfma_f32_32x32x16_bf16 v[2:17], v[186:189], v[214:217], v[2:17]
	ds_read_b128 v[182:185], v229 offset:13312
	v_max3_f32 v224, v224, v43, v44
	v_max3_f32 v225, v225, v59, v60
	v_max3_f32 v224, v224, v45, v46
	v_max3_f32 v225, v225, v61, v62
	v_add_u32_e32 v222, 0xb000, v173
	ds_write_b128 v222, v[202:205] offset:49152
	v_lshl_add_u32 v222, s13, 7, v168
	global_load_dwordx4 v[202:205], v222, s[56:57]
	s_waitcnt lgkmcnt(5)
	s_nop 0
	v_mfma_f32_32x32x16_bf16 v[18:33], v[190:193], v[214:217], v[18:33]
	ds_read_b128 v[186:189], v229 offset:19968
	v_max3_f32 v224, v224, v47, v48
	v_max3_f32 v225, v225, v63, v64
	v_max3_f32 v224, v224, v49, v65
	v_max_f32_e64 v224, v224, v225
	s_waitcnt lgkmcnt(5)
	v_mov_b32_e32 v225, v224
	v_mfma_f32_32x32x16_bf16 v[2:17], v[194:197], v[218:221], v[2:17]
	ds_read_b128 v[190:193], v229 offset:13344
	v_add_f32_e32 v1, v1, v164
	s_add_i32 s11, s11, 1
	v_permlane32_swap_b32_e32 v224, v225
	s_cmp_eq_u32 s9, s11
	v_max_f32_e64 v167, v224, v225
	v_cmp_lt_f32_e32 vcc, s66, v167
	s_waitcnt lgkmcnt(4)
	v_mfma_f32_32x32x16_bf16 v[18:33], v[198:201], v[218:221], v[18:33]
	ds_read_b128 v[194:197], v229 offset:20000
	s_waitcnt lgkmcnt(3)
	s_barrier
	s_cbranch_scc1 .Lmla_exit_p1

; template <int VAR>
; __device__ __forceinline__ void attn_phase(LAS unsigned char* lds, const AttnP P, int vcu, int G, int wave_s) {
;     ...
;         for (int t = 0; t < nt; ++t) {
;             const bool hn = (t + 1 < nt);
;     ...
;                 if (ND0 == 6) {
;                     KR1(0); KR1(1); KR1(2); KR1(3); SB();
;                     QK1(0, negm); EX2(pc0, 0, w0.x); KR1(4); SB();
;                     QK1(1, negm); EX2(pc0, 2, w0.y); KR1(5); SB();
;                     QK1(2, pn0); EX2(pc0, 4, w0.z); KR1(6); SB();
;                     QK1(3, pn1); EX2(pc0, 6, w0.w); KR1(7); SB();
;                     QK1(4, pn0); EX2(pc0, 8, w1.x); KR1(8); SB();
;                     QK1(5, pn1); EX2(pc0, 10, w1.y); KR1(9); SB();
;                     QK1(6, pn0); EX2(pc0, 12, w1.z); KR1(10); SB();
;                     QK1(7, pn1); EX2(pc0, 14, w1.w); KR1(11); SB();
;                     QK1(8, pn0); EX2(pc1, 0, w2.x); VR1(0); SB();
;                     QK1(9, pn1); EX2(pc1, 2, w2.y); VR1(1); SB();
;                     QK1(10, pn0); EX2(pc1, 4, w2.z); VR1(2); SB();
;                     QK1(11, pn1); EX2(pc1, 6, w2.w); VR1(3); SB();
;                 } else {
;                     KR1(0); KR1(1); KR1(2); KR1(3); SB();
;                     QK1(0, negm); EX2(pc0, 0, w0.x); EX2(pc0, 2, w0.y); KR1(4); SB();
;                     QK1(1, negm); EX2(pc0, 4, w0.z); EX2(pc0, 6, w0.w); KR1(5); SB();
;                     QK1(2, pn0); EX2(pc0, 8, w1.x); EX2(pc0, 10, w1.y); KR1(6); SB();
;                     QK1(3, pn1); EX2(pc0, 12, w1.z); EX2(pc0, 14, w1.w); KR1(7); SB();
;                     QK1(4, pn0); EX2(pc1, 0, w2.x); VR1(0); SB();
;                     QK1(5, pn1); EX2(pc1, 2, w2.y); VR1(1); SB();
;                     QK1(6, pn0); EX2(pc1, 4, w2.z); VR1(2); SB();
;                     QK1(7, pn1); EX2(pc1, 6, w2.w); VR1(3); SB();
;                 }
;                 PV1(0, w0); EX2(pc1, 8, w3.x); VR1(4); SB();
;                 PV1(1, w0); EX2(pc1, 10, w3.y); VR1(5); SB();
;                 PV1(2, w1); EX2(pc1, 12, w3.z); VR1(6); SB();
;                 PV1(3, w1); EX2(pc1, 14, w3.w); VR1(7); SB();
;                 lrun += sacc;
;                 PV1(4, w2); MASK_TILE(pn0, pn1, t + 1); SB();
;                 PV1(5, w2); SB();
;                 PV1(6, w3); SB();
;                 PV1(7, w3); rmn = rowmax32(pn0, pn1); if (!USE_NEGM) rmn -= mref; SB();
.Lmla_p2_go:
	v_exp_f32_e32 v222, v34
	v_exp_f32_e32 v223, v35
	v_add_f32_e32 v164, 0, v222
	v_add_f32_e32 v164, v223, v164
	v_cvt_pk_bf16_f32 v206, v222, v223
	v_exp_f32_e32 v224, v36
	v_exp_f32_e32 v225, v37
	v_add_f32_e32 v164, v224, v164
	v_add_f32_e32 v164, v225, v164
	v_cvt_pk_bf16_f32 v207, v224, v225
	v_exp_f32_e32 v222, v38
	s_waitcnt lgkmcnt(3)
	v_mfma_f32_32x32x16_bf16 v[82:97], v[182:185], v[114:117], v[66:81]
	ds_read_b128 v[198:201], v229 offset:13376
	v_exp_f32_e32 v223, v39
	v_add_f32_e32 v164, v222, v164
	v_cvt_pk_bf16_f32 v208, v222, v223
	v_add_f32_e64 v164, v223, v164
	v_exp_f32_e32 v224, v40
	s_waitcnt lgkmcnt(3)
	v_mfma_f32_32x32x16_bf16 v[98:113], v[186:189], v[114:117], v[66:81]
	ds_read_b128 v[182:185], v229 offset:20032
	v_exp_f32_e32 v225, v41
	v_add_f32_e32 v164, v224, v164
	v_cvt_pk_bf16_f32 v209, v224, v225
	v_add_f32_e64 v164, v225, v164
	v_exp_f32_e32 v222, v42
	s_waitcnt lgkmcnt(3)
	v_mfma_f32_32x32x16_bf16 v[82:97], v[190:193], v[118:121], v[82:97]
	ds_read_b128 v[186:189], v229 offset:13408
	v_exp_f32_e32 v223, v43
	v_add_f32_e32 v164, v222, v164
	v_cvt_pk_bf16_f32 v210, v222, v223
	v_add_f32_e64 v164, v223, v164
	v_exp_f32_e32 v224, v44
	s_waitcnt lgkmcnt(3)
	v_mfma_f32_32x32x16_bf16 v[98:113], v[194:197], v[118:121], v[98:113]
	ds_read_b128 v[190:193], v229 offset:20064
	v_exp_f32_e32 v225, v45
	v_add_f32_e32 v164, v224, v164
	v_cvt_pk_bf16_f32 v211, v224, v225
	v_add_f32_e64 v164, v225, v164
	v_exp_f32_e32 v222, v46
	s_waitcnt lgkmcnt(3)
	v_mfma_f32_32x32x16_bf16 v[82:97], v[198:201], v[122:125], v[82:97]
	ds_read_b128 v[194:197], v229 offset:13440
	v_exp_f32_e32 v223, v47
	v_add_f32_e32 v164, v222, v164
	v_cvt_pk_bf16_f32 v212, v222, v223
	v_add_f32_e64 v164, v223, v164
	v_exp_f32_e32 v224, v48
	s_waitcnt lgkmcnt(3)
	v_mfma_f32_32x32x16_bf16 v[98:113], v[182:185], v[122:125], v[98:113]
	ds_read_b128 v[198:201], v229 offset:20096
	v_exp_f32_e32 v225, v49
	v_add_f32_e32 v164, v224, v164
	v_cvt_pk_bf16_f32 v213, v224, v225
	v_add_f32_e64 v164, v225, v164
	v_exp_f32_e32 v222, v50
	s_waitcnt lgkmcnt(3)
	v_mfma_f32_32x32x16_bf16 v[82:97], v[186:189], v[126:129], v[82:97]
	ds_read_b128 v[182:185], v229 offset:13472
	v_exp_f32_e32 v223, v51
	v_add_f32_e32 v164, v222, v164
	v_cvt_pk_bf16_f32 v214, v222, v223
	v_add_f32_e64 v164, v223, v164
	v_exp_f32_e32 v224, v52
	s_waitcnt lgkmcnt(3)
	v_mfma_f32_32x32x16_bf16 v[98:113], v[190:193], v[126:129], v[98:113]
	ds_read_b128 v[186:189], v229 offset:20128
	v_exp_f32_e32 v225, v53
	v_add_f32_e32 v164, v224, v164
	v_cvt_pk_bf16_f32 v215, v224, v225
	v_add_f32_e64 v164, v225, v164
	v_exp_f32_e32 v222, v54
	s_waitcnt lgkmcnt(3)
	v_mfma_f32_32x32x16_bf16 v[82:97], v[194:197], v[130:133], v[82:97]
	ds_read_b128 v[190:193], v181 offset:39936
	v_exp_f32_e32 v223, v55
	v_add_f32_e32 v164, v222, v164
	v_cvt_pk_bf16_f32 v216, v222, v223
	v_add_f32_e64 v164, v223, v164
	v_exp_f32_e32 v224, v56
	s_waitcnt lgkmcnt(3)
	v_mfma_f32_32x32x16_bf16 v[98:113], v[198:201], v[130:133], v[98:113]
	ds_read_b128 v[194:197], v181 offset:44544
	v_exp_f32_e32 v225, v57
	v_add_f32_e32 v164, v224, v164
	v_cvt_pk_bf16_f32 v217, v224, v225
	v_add_f32_e64 v164, v225, v164
	v_exp_f32_e32 v222, v58
	s_waitcnt lgkmcnt(3)
	v_mfma_f32_32x32x16_bf16 v[82:97], v[182:185], v[134:137], v[82:97]
	ds_read_b128 v[198:201], v181 offset:39968
	v_exp_f32_e32 v223, v59
	v_add_f32_e32 v164, v222, v164
	v_cvt_pk_bf16_f32 v218, v222, v223
	v_add_f32_e64 v164, v223, v164
	v_exp_f32_e32 v224, v60
	s_waitcnt lgkmcnt(3)
	v_mfma_f32_32x32x16_bf16 v[98:113], v[186:189], v[134:137], v[98:113]
	ds_read_b128 v[182:185], v181 offset:44576
	v_exp_f32_e32 v225, v61
	v_add_f32_e32 v164, v224, v164
	v_cvt_pk_bf16_f32 v219, v224, v225
	v_add_f32_e64 v164, v225, v164
	v_exp_f32_e32 v222, v62
	s_waitcnt lgkmcnt(3)
	v_mfma_f32_32x32x16_bf16 v[2:17], v[190:193], v[206:209], v[2:17]
	ds_read_b128 v[186:189], v181 offset:40000
	v_exp_f32_e32 v223, v63
	v_add_f32_e32 v164, v222, v164
	v_cvt_pk_bf16_f32 v220, v222, v223
	v_add_f32_e64 v164, v223, v164
	v_exp_f32_e32 v224, v64
	s_waitcnt lgkmcnt(3)
	v_mfma_f32_32x32x16_bf16 v[18:33], v[194:197], v[206:209], v[18:33]
	ds_read_b128 v[190:193], v181 offset:44608
	v_exp_f32_e32 v225, v65
	v_add_f32_e32 v164, v224, v164
	v_cvt_pk_bf16_f32 v221, v224, v225
	v_add_f32_e64 v164, v225, v164
	s_mov_b32 s13, s20
	s_mov_b32 s20, s19
	s_add_i32 s19, s19, 1
	s_cmp_eq_u32 s19, s9
	s_cselect_b32 s19, 0, s19
	s_nop 0
	s_waitcnt lgkmcnt(3)
	s_waitcnt vmcnt(2)
	v_mfma_f32_32x32x16_bf16 v[2:17], v[198:201], v[210:213], v[2:17]
	ds_read_b128 v[194:197], v181 offset:40032
	v_max3_f32 v224, v82, v83, v84
	v_max3_f32 v225, v98, v99, v100
	v_max3_f32 v224, v224, v85, v86
	v_max3_f32 v225, v225, v101, v102
	ds_write_b128 v172, v[146:149] offset:22528
	v_lshl_add_u32 v222, s19, 17, v178
	global_load_dwordx4 v[146:149], v222, s[52:53]
	s_waitcnt lgkmcnt(4)
	s_and_b64 vcc, exec, s[2:3]
	v_mfma_f32_32x32x16_bf16 v[18:33], v[182:185], v[210:213], v[18:33]
	ds_read_b128 v[198:201], v181 offset:44640
	v_max3_f32 v224, v224, v87, v88
	v_max3_f32 v225, v225, v103, v104
	v_max3_f32 v224, v224, v89, v90
	v_max3_f32 v225, v225, v105, v106
	s_cbranch_vccz .Lmla_p2_nope
	s_nop 0
	ds_write_b128 v176, v[138:141] offset:22656
	v_lshl_add_u32 v222, s19, 12, v179
	global_load_dwordx4 v[138:141], v222, s[62:63]
.Lmla_p2_nope:
	s_waitcnt lgkmcnt(4)
	s_nop 0
	v_mfma_f32_32x32x16_bf16 v[2:17], v[186:189], v[214:217], v[2:17]
	ds_read_b128 v[182:185], v229 offset:26624
	v_max3_f32 v224, v224, v91, v92
	v_max3_f32 v225, v225, v107, v108
	v_max3_f32 v224, v224, v93, v94
	v_max3_f32 v225, v225, v109, v110
	ds_write_b128 v173, v[142:145] offset:13312
	v_lshl_add_u32 v222, s13, 7, v168
	global_load_dwordx4 v[142:145], v222, s[56:57]
	s_waitcnt lgkmcnt(5)
	s_nop 0
	v_mfma_f32_32x32x16_bf16 v[18:33], v[190:193], v[214:217], v[18:33]
	ds_read_b128 v[186:189], v229 offset:33280
	v_max3_f32 v224, v224, v95, v96
	v_max3_f32 v225, v225, v111, v112
	v_max3_f32 v224, v224, v97, v113
	v_max_f32_e64 v224, v224, v225
	s_waitcnt lgkmcnt(5)
	v_mov_b32_e32 v225, v224
	v_mfma_f32_32x32x16_bf16 v[2:17], v[194:197], v[218:221], v[2:17]
	ds_read_b128 v[190:193], v229 offset:26656
	v_add_f32_e32 v1, v1, v164
	s_add_i32 s11, s11, 1
	v_permlane32_swap_b32_e32 v224, v225
	s_cmp_eq_u32 s9, s11
	v_max_f32_e64 v167, v224, v225
	v_cmp_lt_f32_e32 vcc, s66, v167
	s_waitcnt lgkmcnt(4)
	v_mfma_f32_32x32x16_bf16 v[18:33], v[198:201], v[218:221], v[18:33]
	ds_read_b128 v[194:197], v229 offset:33312
	s_cbranch_scc1 .Lmla_exit_p2

; template <int VAR>
; __device__ __forceinline__ void attn_phase(LAS unsigned char* lds, const AttnP P, int vcu, int G, int wave_s) {
;     ...
;         for (int t = 0; t < nt; ++t) {
;             const bool hn = (t + 1 < nt);
;     ...
;                 if (ND0 == 6) {
;                     KR1(0); KR1(1); KR1(2); KR1(3); SB();
;                     QK1(0, negm); EX2(pc0, 0, w0.x); KR1(4); SB();
;                     QK1(1, negm); EX2(pc0, 2, w0.y); KR1(5); SB();
;                     QK1(2, pn0); EX2(pc0, 4, w0.z); KR1(6); SB();
;                     QK1(3, pn1); EX2(pc0, 6, w0.w); KR1(7); SB();
;                     QK1(4, pn0); EX2(pc0, 8, w1.x); KR1(8); SB();
;                     QK1(5, pn1); EX2(pc0, 10, w1.y); KR1(9); SB();
;                     QK1(6, pn0); EX2(pc0, 12, w1.z); KR1(10); SB();
;                     QK1(7, pn1); EX2(pc0, 14, w1.w); KR1(11); SB();
;                     QK1(8, pn0); EX2(pc1, 0, w2.x); VR1(0); SB();
;                     QK1(9, pn1); EX2(pc1, 2, w2.y); VR1(1); SB();
;                     QK1(10, pn0); EX2(pc1, 4, w2.z); VR1(2); SB();
;                     QK1(11, pn1); EX2(pc1, 6, w2.w); VR1(3); SB();
;                 } else {
;                     KR1(0); KR1(1); KR1(2); KR1(3); SB();
;                     QK1(0, negm); EX2(pc0, 0, w0.x); EX2(pc0, 2, w0.y); KR1(4); SB();
;                     QK1(1, negm); EX2(pc0, 4, w0.z); EX2(pc0, 6, w0.w); KR1(5); SB();
;                     QK1(2, pn0); EX2(pc0, 8, w1.x); EX2(pc0, 10, w1.y); KR1(6); SB();
;                     QK1(3, pn1); EX2(pc0, 12, w1.z); EX2(pc0, 14, w1.w); KR1(7); SB();
;                     QK1(4, pn0); EX2(pc1, 0, w2.x); VR1(0); SB();
;                     QK1(5, pn1); EX2(pc1, 2, w2.y); VR1(1); SB();
;                     QK1(6, pn0); EX2(pc1, 4, w2.z); VR1(2); SB();
;                     QK1(7, pn1); EX2(pc1, 6, w2.w); VR1(3); SB();
;                 }
;                 PV1(0, w0); EX2(pc1, 8, w3.x); VR1(4); SB();
;                 PV1(1, w0); EX2(pc1, 10, w3.y); VR1(5); SB();
;                 PV1(2, w1); EX2(pc1, 12, w3.z); VR1(6); SB();
;                 PV1(3, w1); EX2(pc1, 14, w3.w); VR1(7); SB();
;                 lrun += sacc;
;                 PV1(4, w2); MASK_TILE(pn0, pn1, t + 1); SB();
;                 PV1(5, w2); SB();
;                 PV1(6, w3); SB();
;                 PV1(7, w3); rmn = rowmax32(pn0, pn1); if (!USE_NEGM) rmn -= mref; SB();
.Lmla_p3_go:
	v_exp_f32_e32 v222, v82
	v_exp_f32_e32 v223, v83
	v_add_f32_e32 v164, 0, v222
	v_add_f32_e32 v164, v223, v164
	v_cvt_pk_bf16_f32 v206, v222, v223
	v_exp_f32_e32 v224, v84
	v_exp_f32_e32 v225, v85
	v_add_f32_e32 v164, v224, v164
	v_add_f32_e32 v164, v225, v164
	v_cvt_pk_bf16_f32 v207, v224, v225
	v_exp_f32_e32 v222, v86
	s_waitcnt lgkmcnt(4)
	v_mfma_f32_32x32x16_bf16 v[34:49], v[182:185], v[114:117], v[66:81]
	ds_read_b128 v[198:201], v229 offset:26688
	v_exp_f32_e32 v223, v87
	v_add_f32_e32 v164, v222, v164
	v_cvt_pk_bf16_f32 v208, v222, v223
	v_add_f32_e64 v164, v223, v164
	v_exp_f32_e32 v224, v88
	s_waitcnt lgkmcnt(3)
	v_mfma_f32_32x32x16_bf16 v[50:65], v[186:189], v[114:117], v[66:81]
	ds_read_b128 v[182:185], v229 offset:33344
	v_exp_f32_e32 v225, v89
	v_add_f32_e32 v164, v224, v164
	v_cvt_pk_bf16_f32 v209, v224, v225
	v_add_f32_e64 v164, v225, v164
	v_exp_f32_e32 v222, v90
	s_waitcnt lgkmcnt(3)
	v_mfma_f32_32x32x16_bf16 v[34:49], v[190:193], v[118:121], v[34:49]
	ds_read_b128 v[186:189], v229 offset:26720
	v_exp_f32_e32 v223, v91
	v_add_f32_e32 v164, v222, v164
	v_cvt_pk_bf16_f32 v210, v222, v223
	v_add_f32_e64 v164, v223, v164
	v_exp_f32_e32 v224, v92
	s_waitcnt lgkmcnt(3)
	v_mfma_f32_32x32x16_bf16 v[50:65], v[194:197], v[118:121], v[50:65]
	ds_read_b128 v[190:193], v229 offset:33376
	v_exp_f32_e32 v225, v93
	v_add_f32_e32 v164, v224, v164
	v_cvt_pk_bf16_f32 v211, v224, v225
	v_add_f32_e64 v164, v225, v164
	v_exp_f32_e32 v222, v94
	s_waitcnt lgkmcnt(3)
	v_mfma_f32_32x32x16_bf16 v[34:49], v[198:201], v[122:125], v[34:49]
	ds_read_b128 v[194:197], v229 offset:26752
	v_exp_f32_e32 v223, v95
	v_add_f32_e32 v164, v222, v164
	v_cvt_pk_bf16_f32 v212, v222, v223
	v_add_f32_e64 v164, v223, v164
	v_exp_f32_e32 v224, v96
	s_waitcnt lgkmcnt(3)
	v_mfma_f32_32x32x16_bf16 v[50:65], v[182:185], v[122:125], v[50:65]
	ds_read_b128 v[198:201], v229 offset:33408
	v_exp_f32_e32 v225, v97
	v_add_f32_e32 v164, v224, v164
	v_cvt_pk_bf16_f32 v213, v224, v225
	v_add_f32_e64 v164, v225, v164
	v_exp_f32_e32 v222, v98
	s_waitcnt lgkmcnt(3)
	v_mfma_f32_32x32x16_bf16 v[34:49], v[186:189], v[126:129], v[34:49]
	ds_read_b128 v[182:185], v229 offset:26784
	v_exp_f32_e32 v223, v99
	v_add_f32_e32 v164, v222, v164
	v_cvt_pk_bf16_f32 v214, v222, v223
	v_add_f32_e64 v164, v223, v164
	v_exp_f32_e32 v224, v100
	s_waitcnt lgkmcnt(3)
	v_mfma_f32_32x32x16_bf16 v[50:65], v[190:193], v[126:129], v[50:65]
	ds_read_b128 v[186:189], v229 offset:33440
	v_exp_f32_e32 v225, v101
	v_add_f32_e32 v164, v224, v164
	v_cvt_pk_bf16_f32 v215, v224, v225
	v_add_f32_e64 v164, v225, v164
	v_exp_f32_e32 v222, v102
	s_waitcnt lgkmcnt(3)
	v_mfma_f32_32x32x16_bf16 v[34:49], v[194:197], v[130:133], v[34:49]
	ds_read_b128 v[190:193], v181 offset:49152
	v_exp_f32_e32 v223, v103
	v_add_f32_e32 v164, v222, v164
	v_cvt_pk_bf16_f32 v216, v222, v223
	v_add_f32_e64 v164, v223, v164
	v_exp_f32_e32 v224, v104
	s_waitcnt lgkmcnt(3)
	v_mfma_f32_32x32x16_bf16 v[50:65], v[198:201], v[130:133], v[50:65]
	ds_read_b128 v[194:197], v181 offset:53760
	v_exp_f32_e32 v225, v105
	v_add_f32_e32 v164, v224, v164
	v_cvt_pk_bf16_f32 v217, v224, v225
	v_add_f32_e64 v164, v225, v164
	v_exp_f32_e32 v222, v106
	s_waitcnt lgkmcnt(3)
	v_mfma_f32_32x32x16_bf16 v[34:49], v[182:185], v[134:137], v[34:49]
	ds_read_b128 v[198:201], v181 offset:49184
	v_exp_f32_e32 v223, v107
	v_add_f32_e32 v164, v222, v164
	v_cvt_pk_bf16_f32 v218, v222, v223
	v_add_f32_e64 v164, v223, v164
	v_exp_f32_e32 v224, v108
	s_waitcnt lgkmcnt(3)
	v_mfma_f32_32x32x16_bf16 v[50:65], v[186:189], v[134:137], v[50:65]
	ds_read_b128 v[182:185], v181 offset:53792
	v_exp_f32_e32 v225, v109
	v_add_f32_e32 v164, v224, v164
	v_cvt_pk_bf16_f32 v219, v224, v225
	v_add_f32_e64 v164, v225, v164
	v_exp_f32_e32 v222, v110
	s_waitcnt lgkmcnt(3)
	v_mfma_f32_32x32x16_bf16 v[2:17], v[190:193], v[206:209], v[2:17]
	ds_read_b128 v[186:189], v181 offset:49216
	v_exp_f32_e32 v223, v111
	v_add_f32_e32 v164, v222, v164
	v_cvt_pk_bf16_f32 v220, v222, v223
	v_add_f32_e64 v164, v223, v164
	v_exp_f32_e32 v224, v112
	s_waitcnt lgkmcnt(3)
	v_mfma_f32_32x32x16_bf16 v[18:33], v[194:197], v[206:209], v[18:33]
	ds_read_b128 v[190:193], v181 offset:53824
	v_exp_f32_e32 v225, v113
	v_add_f32_e32 v164, v224, v164
	v_cvt_pk_bf16_f32 v221, v224, v225
	v_add_f32_e64 v164, v225, v164
	s_mov_b32 s13, s20
	s_mov_b32 s20, s19
	s_add_i32 s19, s19, 1
	s_cmp_eq_u32 s19, s9
	s_cselect_b32 s19, 0, s19
	s_nop 0
	s_waitcnt lgkmcnt(3)
	s_waitcnt vmcnt(2)
	v_mfma_f32_32x32x16_bf16 v[2:17], v[198:201], v[210:213], v[2:17]
	ds_read_b128 v[194:197], v181 offset:49248
	v_max3_f32 v224, v34, v35, v36
	v_max3_f32 v225, v50, v51, v52
	v_max3_f32 v224, v224, v37, v38
	v_max3_f32 v225, v225, v53, v54
	ds_write_b128 v172, v[150:153] offset:45056
	v_lshl_add_u32 v222, s19, 17, v178
	global_load_dwordx4 v[150:153], v222, s[52:53]
	s_waitcnt lgkmcnt(4)
	s_and_b64 vcc, exec, s[2:3]
	v_mfma_f32_32x32x16_bf16 v[18:33], v[182:185], v[210:213], v[18:33]
	ds_read_b128 v[198:201], v181 offset:53856
	v_max3_f32 v224, v224, v39, v40
	v_max3_f32 v225, v225, v55, v56
	v_max3_f32 v224, v224, v41, v42
	v_max3_f32 v225, v225, v57, v58
	s_cbranch_vccz .Lmla_p3_nope
	s_nop 0
	ds_write_b128 v176, v[160:163] offset:45184
	v_lshl_add_u32 v222, s19, 12, v179
	global_load_dwordx4 v[160:163], v222, s[62:63]
.Lmla_p3_nope:
	s_waitcnt lgkmcnt(4)
	s_nop 0
	v_mfma_f32_32x32x16_bf16 v[2:17], v[186:189], v[214:217], v[2:17]
	ds_read_b128 v[182:185], v174
	v_max3_f32 v224, v224, v43, v44
	v_max3_f32 v225, v225, v59, v60
	v_max3_f32 v224, v224, v45, v46
	v_max3_f32 v225, v225, v61, v62
	ds_write_b128 v173, v[202:205] offset:35840
	v_lshl_add_u32 v222, s13, 7, v168
	global_load_dwordx4 v[202:205], v222, s[56:57]
	s_waitcnt lgkmcnt(5)
	s_nop 0
	v_mfma_f32_32x32x16_bf16 v[18:33], v[190:193], v[214:217], v[18:33]
	ds_read_b128 v[186:189], v174 offset:6656
	v_max3_f32 v224, v224, v47, v48
	v_max3_f32 v225, v225, v63, v64
	v_max3_f32 v224, v224, v49, v65
	v_max_f32_e64 v224, v224, v225
	s_waitcnt lgkmcnt(5)
	v_mov_b32_e32 v225, v224
	v_mfma_f32_32x32x16_bf16 v[2:17], v[194:197], v[218:221], v[2:17]
	ds_read_b128 v[190:193], v174 offset:32
	v_add_f32_e32 v1, v1, v164
	s_add_i32 s11, s11, 1
	v_permlane32_swap_b32_e32 v224, v225
	s_cmp_eq_u32 s9, s11
	v_max_f32_e64 v167, v224, v225
	v_cmp_lt_f32_e32 vcc, s66, v167
	s_waitcnt lgkmcnt(4)
	v_mfma_f32_32x32x16_bf16 v[18:33], v[198:201], v[218:221], v[18:33]
	ds_read_b128 v[194:197], v174 offset:6688
	s_waitcnt lgkmcnt(3)
	s_barrier
	s_cbranch_scc1 .Lmla_exit_p3

; template <int VAR>
; __device__ __forceinline__ void attn_phase(LAS unsigned char* lds, const AttnP P, int vcu, int G, int wave_s) {
;     ...
;         for (int t = 0; t < nt; ++t) {
;             const bool hn = (t + 1 < nt);
;     ...
;                 if (ND0 == 6) {
;                     KR1(0); KR1(1); KR1(2); KR1(3); SB();
;                     QK1(0, negm); EX2(pc0, 0, w0.x); KR1(4); SB();
;                     QK1(1, negm); EX2(pc0, 2, w0.y); KR1(5); SB();
;                     QK1(2, pn0); EX2(pc0, 4, w0.z); KR1(6); SB();
;                     QK1(3, pn1); EX2(pc0, 6, w0.w); KR1(7); SB();
;                     QK1(4, pn0); EX2(pc0, 8, w1.x); KR1(8); SB();
;                     QK1(5, pn1); EX2(pc0, 10, w1.y); KR1(9); SB();
;                     QK1(6, pn0); EX2(pc0, 12, w1.z); KR1(10); SB();
;                     QK1(7, pn1); EX2(pc0, 14, w1.w); KR1(11); SB();
;                     QK1(8, pn0); EX2(pc1, 0, w2.x); VR1(0); SB();
;                     QK1(9, pn1); EX2(pc1, 2, w2.y); VR1(1); SB();
;                     QK1(10, pn0); EX2(pc1, 4, w2.z); VR1(2); SB();
;                     QK1(11, pn1); EX2(pc1, 6, w2.w); VR1(3); SB();
;                 } else {
;                     KR1(0); KR1(1); KR1(2); KR1(3); SB();
;                     QK1(0, negm); EX2(pc0, 0, w0.x); EX2(pc0, 2, w0.y); KR1(4); SB();
;                     QK1(1, negm); EX2(pc0, 4, w0.z); EX2(pc0, 6, w0.w); KR1(5); SB();
;                     QK1(2, pn0); EX2(pc0, 8, w1.x); EX2(pc0, 10, w1.y); KR1(6); SB();
;                     QK1(3, pn1); EX2(pc0, 12, w1.z); EX2(pc0, 14, w1.w); KR1(7); SB();
;                     QK1(4, pn0); EX2(pc1, 0, w2.x); VR1(0); SB();
;                     QK1(5, pn1); EX2(pc1, 2, w2.y); VR1(1); SB();
;                     QK1(6, pn0); EX2(pc1, 4, w2.z); VR1(2); SB();
;                     QK1(7, pn1); EX2(pc1, 6, w2.w); VR1(3); SB();
;                 }
;                 PV1(0, w0); EX2(pc1, 8, w3.x); VR1(4); SB();
;                 PV1(1, w0); EX2(pc1, 10, w3.y); VR1(5); SB();
;                 PV1(2, w1); EX2(pc1, 12, w3.z); VR1(6); SB();
;                 PV1(3, w1); EX2(pc1, 14, w3.w); VR1(7); SB();
;                 lrun += sacc;
;                 PV1(4, w2); MASK_TILE(pn0, pn1, t + 1); SB();
;                 PV1(5, w2); SB();
;                 PV1(6, w3); SB();
;                 PV1(7, w3); rmn = rowmax32(pn0, pn1); if (!USE_NEGM) rmn -= mref; SB();
.Lmla_p4_go:
	v_exp_f32_e32 v222, v34
	v_exp_f32_e32 v223, v35
	v_add_f32_e32 v164, 0, v222
	v_add_f32_e32 v164, v223, v164
	v_cvt_pk_bf16_f32 v206, v222, v223
	v_exp_f32_e32 v224, v36
	v_exp_f32_e32 v225, v37
	v_add_f32_e32 v164, v224, v164
	v_add_f32_e32 v164, v225, v164
	v_cvt_pk_bf16_f32 v207, v224, v225
	v_exp_f32_e32 v222, v38
	s_waitcnt lgkmcnt(3)
	v_mfma_f32_32x32x16_bf16 v[82:97], v[182:185], v[114:117], v[66:81]
	ds_read_b128 v[198:201], v174 offset:64
	v_exp_f32_e32 v223, v39
	v_add_f32_e32 v164, v222, v164
	v_cvt_pk_bf16_f32 v208, v222, v223
	v_add_f32_e64 v164, v223, v164
	v_exp_f32_e32 v224, v40
	s_waitcnt lgkmcnt(3)
	v_mfma_f32_32x32x16_bf16 v[98:113], v[186:189], v[114:117], v[66:81]
	ds_read_b128 v[182:185], v174 offset:6720
	v_exp_f32_e32 v225, v41
	v_add_f32_e32 v164, v224, v164
	v_cvt_pk_bf16_f32 v209, v224, v225
	v_add_f32_e64 v164, v225, v164
	v_exp_f32_e32 v222, v42
	s_waitcnt lgkmcnt(3)
	v_mfma_f32_32x32x16_bf16 v[82:97], v[190:193], v[118:121], v[82:97]
	ds_read_b128 v[186:189], v174 offset:96
	v_exp_f32_e32 v223, v43
	v_add_f32_e32 v164, v222, v164
	v_cvt_pk_bf16_f32 v210, v222, v223
	v_add_f32_e64 v164, v223, v164
	v_exp_f32_e32 v224, v44
	s_waitcnt lgkmcnt(3)
	v_mfma_f32_32x32x16_bf16 v[98:113], v[194:197], v[118:121], v[98:113]
	ds_read_b128 v[190:193], v174 offset:6752
	v_exp_f32_e32 v225, v45
	v_add_f32_e32 v164, v224, v164
	v_cvt_pk_bf16_f32 v211, v224, v225
	v_add_f32_e64 v164, v225, v164
	v_exp_f32_e32 v222, v46
	s_waitcnt lgkmcnt(3)
	v_mfma_f32_32x32x16_bf16 v[82:97], v[198:201], v[122:125], v[82:97]
	ds_read_b128 v[194:197], v174 offset:128
	v_exp_f32_e32 v223, v47
	v_add_f32_e32 v164, v222, v164
	v_cvt_pk_bf16_f32 v212, v222, v223
	v_add_f32_e64 v164, v223, v164
	v_exp_f32_e32 v224, v48
	s_waitcnt lgkmcnt(3)
	v_mfma_f32_32x32x16_bf16 v[98:113], v[182:185], v[122:125], v[98:113]
	ds_read_b128 v[198:201], v174 offset:6784
	v_exp_f32_e32 v225, v49
	v_add_f32_e32 v164, v224, v164
	v_cvt_pk_bf16_f32 v213, v224, v225
	v_add_f32_e64 v164, v225, v164
	v_exp_f32_e32 v222, v50
	s_waitcnt lgkmcnt(3)
	v_mfma_f32_32x32x16_bf16 v[82:97], v[186:189], v[126:129], v[82:97]
	ds_read_b128 v[182:185], v174 offset:160
	v_exp_f32_e32 v223, v51
	v_add_f32_e32 v164, v222, v164
	v_cvt_pk_bf16_f32 v214, v222, v223
	v_add_f32_e64 v164, v223, v164
	v_exp_f32_e32 v224, v52
	s_waitcnt lgkmcnt(3)
	v_mfma_f32_32x32x16_bf16 v[98:113], v[190:193], v[126:129], v[98:113]
	ds_read_b128 v[186:189], v174 offset:6816
	v_exp_f32_e32 v225, v53
	v_add_f32_e32 v164, v224, v164
	v_cvt_pk_bf16_f32 v215, v224, v225
	v_add_f32_e64 v164, v225, v164
	v_exp_f32_e32 v222, v54
	s_waitcnt lgkmcnt(3)
	v_mfma_f32_32x32x16_bf16 v[82:97], v[194:197], v[130:133], v[82:97]
	ds_read_b128 v[190:193], v228 offset:13312
	v_exp_f32_e32 v223, v55
	v_add_f32_e32 v164, v222, v164
	v_cvt_pk_bf16_f32 v216, v222, v223
	v_add_f32_e64 v164, v223, v164
	v_exp_f32_e32 v224, v56
	s_waitcnt lgkmcnt(3)
	v_mfma_f32_32x32x16_bf16 v[98:113], v[198:201], v[130:133], v[98:113]
	ds_read_b128 v[194:197], v228 offset:17920
	v_exp_f32_e32 v225, v57
	v_add_f32_e32 v164, v224, v164
	v_cvt_pk_bf16_f32 v217, v224, v225
	v_add_f32_e64 v164, v225, v164
	v_exp_f32_e32 v222, v58
	s_waitcnt lgkmcnt(3)
	v_mfma_f32_32x32x16_bf16 v[82:97], v[182:185], v[134:137], v[82:97]
	ds_read_b128 v[198:201], v228 offset:13344
	v_exp_f32_e32 v223, v59
	v_add_f32_e32 v164, v222, v164
	v_cvt_pk_bf16_f32 v218, v222, v223
	v_add_f32_e64 v164, v223, v164
	v_exp_f32_e32 v224, v60
	s_waitcnt lgkmcnt(3)
	v_mfma_f32_32x32x16_bf16 v[98:113], v[186:189], v[134:137], v[98:113]
	ds_read_b128 v[182:185], v228 offset:17952
	v_exp_f32_e32 v225, v61
	v_add_f32_e32 v164, v224, v164
	v_cvt_pk_bf16_f32 v219, v224, v225
	v_add_f32_e64 v164, v225, v164
	v_exp_f32_e32 v222, v62
	s_waitcnt lgkmcnt(3)
	v_mfma_f32_32x32x16_bf16 v[2:17], v[190:193], v[206:209], v[2:17]
	ds_read_b128 v[186:189], v228 offset:13376
	v_exp_f32_e32 v223, v63
	v_add_f32_e32 v164, v222, v164
	v_cvt_pk_bf16_f32 v220, v222, v223
	v_add_f32_e64 v164, v223, v164
	v_exp_f32_e32 v224, v64
	s_waitcnt lgkmcnt(3)
	v_mfma_f32_32x32x16_bf16 v[18:33], v[194:197], v[206:209], v[18:33]
	ds_read_b128 v[190:193], v228 offset:17984
	v_exp_f32_e32 v225, v65
	v_add_f32_e32 v164, v224, v164
	v_cvt_pk_bf16_f32 v221, v224, v225
	v_add_f32_e64 v164, v225, v164
	s_mov_b32 s13, s20
	s_mov_b32 s20, s19
	s_add_i32 s19, s19, 1
	s_cmp_eq_u32 s19, s9
	s_cselect_b32 s19, 0, s19
	s_nop 0
	s_waitcnt lgkmcnt(3)
	s_waitcnt vmcnt(2)
	v_mfma_f32_32x32x16_bf16 v[2:17], v[198:201], v[210:213], v[2:17]
	ds_read_b128 v[194:197], v228 offset:13408
	v_max3_f32 v224, v82, v83, v84
	v_max3_f32 v225, v98, v99, v100
	v_max3_f32 v224, v224, v85, v86
	v_max3_f32 v225, v225, v101, v102
	ds_write_b128 v172, v[146:149] offset:58368
	v_lshl_add_u32 v222, s19, 17, v178
	global_load_dwordx4 v[146:149], v222, s[52:53]
	s_waitcnt lgkmcnt(4)
	s_and_b64 vcc, exec, s[2:3]
	v_mfma_f32_32x32x16_bf16 v[18:33], v[182:185], v[210:213], v[18:33]
	ds_read_b128 v[198:201], v228 offset:18016
	v_max3_f32 v224, v224, v87, v88
	v_max3_f32 v225, v225, v103, v104
	v_max3_f32 v224, v224, v89, v90
	v_max3_f32 v225, v225, v105, v106
	s_cbranch_vccz .Lmla_p4_nope
	s_nop 0
	ds_write_b128 v176, v[138:141] offset:58496
	v_lshl_add_u32 v222, s19, 12, v179
	global_load_dwordx4 v[138:141], v222, s[62:63]
.Lmla_p4_nope:
	s_waitcnt lgkmcnt(4)
	s_nop 0
	v_mfma_f32_32x32x16_bf16 v[2:17], v[186:189], v[214:217], v[2:17]
	ds_read_b128 v[182:185], v174 offset:22528
	v_max3_f32 v224, v224, v91, v92
	v_max3_f32 v225, v225, v107, v108
	v_max3_f32 v224, v224, v93, v94
	v_max3_f32 v225, v225, v109, v110
	v_add_u32_e32 v222, 0xb000, v173
	ds_write_b128 v222, v[142:145] offset:39936
	v_lshl_add_u32 v222, s13, 7, v168
	global_load_dwordx4 v[142:145], v222, s[56:57]
	s_waitcnt lgkmcnt(5)
	s_nop 0
	v_mfma_f32_32x32x16_bf16 v[18:33], v[190:193], v[214:217], v[18:33]
	ds_read_b128 v[186:189], v174 offset:29184
	v_max3_f32 v224, v224, v95, v96
	v_max3_f32 v225, v225, v111, v112
	v_max3_f32 v224, v224, v97, v113
	v_max_f32_e64 v224, v224, v225
	s_waitcnt lgkmcnt(5)
	v_mov_b32_e32 v225, v224
	v_mfma_f32_32x32x16_bf16 v[2:17], v[194:197], v[218:221], v[2:17]
	ds_read_b128 v[190:193], v174 offset:22560
	v_add_f32_e32 v1, v1, v164
	s_add_i32 s11, s11, 1
	v_permlane32_swap_b32_e32 v224, v225
	s_cmp_eq_u32 s9, s11
	v_max_f32_e64 v167, v224, v225
	v_cmp_lt_f32_e32 vcc, s66, v167
	s_waitcnt lgkmcnt(4)
	v_mfma_f32_32x32x16_bf16 v[18:33], v[198:201], v[218:221], v[18:33]
	ds_read_b128 v[194:197], v174 offset:29216
	s_cbranch_scc1 .Lmla_exit_p4

; template <int VAR>
; __device__ __forceinline__ void attn_phase(LAS unsigned char* lds, const AttnP P, int vcu, int G, int wave_s) {
;     ...
;         for (int t = 0; t < nt; ++t) {
;             const bool hn = (t + 1 < nt);
;     ...
;                 if (ND0 == 6) {
;                     KR1(0); KR1(1); KR1(2); KR1(3); SB();
;                     QK1(0, negm); EX2(pc0, 0, w0.x); KR1(4); SB();
;                     QK1(1, negm); EX2(pc0, 2, w0.y); KR1(5); SB();
;                     QK1(2, pn0); EX2(pc0, 4, w0.z); KR1(6); SB();
;                     QK1(3, pn1); EX2(pc0, 6, w0.w); KR1(7); SB();
;                     QK1(4, pn0); EX2(pc0, 8, w1.x); KR1(8); SB();
;                     QK1(5, pn1); EX2(pc0, 10, w1.y); KR1(9); SB();
;                     QK1(6, pn0); EX2(pc0, 12, w1.z); KR1(10); SB();
;                     QK1(7, pn1); EX2(pc0, 14, w1.w); KR1(11); SB();
;                     QK1(8, pn0); EX2(pc1, 0, w2.x); VR1(0); SB();
;                     QK1(9, pn1); EX2(pc1, 2, w2.y); VR1(1); SB();
;                     QK1(10, pn0); EX2(pc1, 4, w2.z); VR1(2); SB();
;                     QK1(11, pn1); EX2(pc1, 6, w2.w); VR1(3); SB();
;                 } else {
;                     KR1(0); KR1(1); KR1(2); KR1(3); SB();
;                     QK1(0, negm); EX2(pc0, 0, w0.x); EX2(pc0, 2, w0.y); KR1(4); SB();
;                     QK1(1, negm); EX2(pc0, 4, w0.z); EX2(pc0, 6, w0.w); KR1(5); SB();
;                     QK1(2, pn0); EX2(pc0, 8, w1.x); EX2(pc0, 10, w1.y); KR1(6); SB();
;                     QK1(3, pn1); EX2(pc0, 12, w1.z); EX2(pc0, 14, w1.w); KR1(7); SB();
;                     QK1(4, pn0); EX2(pc1, 0, w2.x); VR1(0); SB();
;                     QK1(5, pn1); EX2(pc1, 2, w2.y); VR1(1); SB();
;                     QK1(6, pn0); EX2(pc1, 4, w2.z); VR1(2); SB();
;                     QK1(7, pn1); EX2(pc1, 6, w2.w); VR1(3); SB();
;                 }
;                 PV1(0, w0); EX2(pc1, 8, w3.x); VR1(4); SB();
;                 PV1(1, w0); EX2(pc1, 10, w3.y); VR1(5); SB();
;                 PV1(2, w1); EX2(pc1, 12, w3.z); VR1(6); SB();
;                 PV1(3, w1); EX2(pc1, 14, w3.w); VR1(7); SB();
;                 lrun += sacc;
;                 PV1(4, w2); MASK_TILE(pn0, pn1, t + 1); SB();
;                 PV1(5, w2); SB();
;                 PV1(6, w3); SB();
;                 PV1(7, w3); rmn = rowmax32(pn0, pn1); if (!USE_NEGM) rmn -= mref; SB();
.Lmla_p5_go:
	v_exp_f32_e32 v222, v82
	v_exp_f32_e32 v223, v83
	v_add_f32_e32 v164, 0, v222
	v_add_f32_e32 v164, v223, v164
	v_cvt_pk_bf16_f32 v206, v222, v223
	v_exp_f32_e32 v224, v84
	v_exp_f32_e32 v225, v85
	v_add_f32_e32 v164, v224, v164
	v_add_f32_e32 v164, v225, v164
	v_cvt_pk_bf16_f32 v207, v224, v225
	v_exp_f32_e32 v222, v86
	s_waitcnt lgkmcnt(4)
	v_mfma_f32_32x32x16_bf16 v[34:49], v[182:185], v[114:117], v[66:81]
	ds_read_b128 v[198:201], v174 offset:22592
	v_exp_f32_e32 v223, v87
	v_add_f32_e32 v164, v222, v164
	v_cvt_pk_bf16_f32 v208, v222, v223
	v_add_f32_e64 v164, v223, v164
	v_exp_f32_e32 v224, v88
	s_waitcnt lgkmcnt(3)
	v_mfma_f32_32x32x16_bf16 v[50:65], v[186:189], v[114:117], v[66:81]
	ds_read_b128 v[182:185], v174 offset:29248
	v_exp_f32_e32 v225, v89
	v_add_f32_e32 v164, v224, v164
	v_cvt_pk_bf16_f32 v209, v224, v225
	v_add_f32_e64 v164, v225, v164
	v_exp_f32_e32 v222, v90
	s_waitcnt lgkmcnt(3)
	v_mfma_f32_32x32x16_bf16 v[34:49], v[190:193], v[118:121], v[34:49]
	ds_read_b128 v[186:189], v174 offset:22624
	v_exp_f32_e32 v223, v91
	v_add_f32_e32 v164, v222, v164
	v_cvt_pk_bf16_f32 v210, v222, v223
	v_add_f32_e64 v164, v223, v164
	v_exp_f32_e32 v224, v92
	s_waitcnt lgkmcnt(3)
	v_mfma_f32_32x32x16_bf16 v[50:65], v[194:197], v[118:121], v[50:65]
	ds_read_b128 v[190:193], v174 offset:29280
	v_exp_f32_e32 v225, v93
	v_add_f32_e32 v164, v224, v164
	v_cvt_pk_bf16_f32 v211, v224, v225
	v_add_f32_e64 v164, v225, v164
	v_exp_f32_e32 v222, v94
	s_waitcnt lgkmcnt(3)
	v_mfma_f32_32x32x16_bf16 v[34:49], v[198:201], v[122:125], v[34:49]
	ds_read_b128 v[194:197], v174 offset:22656
	v_exp_f32_e32 v223, v95
	v_add_f32_e32 v164, v222, v164
	v_cvt_pk_bf16_f32 v212, v222, v223
	v_add_f32_e64 v164, v223, v164
	v_exp_f32_e32 v224, v96
	s_waitcnt lgkmcnt(3)
	v_mfma_f32_32x32x16_bf16 v[50:65], v[182:185], v[122:125], v[50:65]
	ds_read_b128 v[198:201], v174 offset:29312
	v_exp_f32_e32 v225, v97
	v_add_f32_e32 v164, v224, v164
	v_cvt_pk_bf16_f32 v213, v224, v225
	v_add_f32_e64 v164, v225, v164
	v_exp_f32_e32 v222, v98
	s_waitcnt lgkmcnt(3)
	v_mfma_f32_32x32x16_bf16 v[34:49], v[186:189], v[126:129], v[34:49]
	ds_read_b128 v[182:185], v174 offset:22688
	v_exp_f32_e32 v223, v99
	v_add_f32_e32 v164, v222, v164
	v_cvt_pk_bf16_f32 v214, v222, v223
	v_add_f32_e64 v164, v223, v164
	v_exp_f32_e32 v224, v100
	s_waitcnt lgkmcnt(3)
	v_mfma_f32_32x32x16_bf16 v[50:65], v[190:193], v[126:129], v[50:65]
	ds_read_b128 v[186:189], v174 offset:29344
	v_exp_f32_e32 v225, v101
	v_add_f32_e32 v164, v224, v164
	v_cvt_pk_bf16_f32 v215, v224, v225
	v_add_f32_e64 v164, v225, v164
	v_exp_f32_e32 v222, v102
	s_waitcnt lgkmcnt(3)
	v_mfma_f32_32x32x16_bf16 v[34:49], v[194:197], v[130:133], v[34:49]
	ds_read_b128 v[190:193], v228 offset:35840
	v_exp_f32_e32 v223, v103
	v_add_f32_e32 v164, v222, v164
	v_cvt_pk_bf16_f32 v216, v222, v223
	v_add_f32_e64 v164, v223, v164
	v_exp_f32_e32 v224, v104
	s_waitcnt lgkmcnt(3)
	v_mfma_f32_32x32x16_bf16 v[50:65], v[198:201], v[130:133], v[50:65]
	ds_read_b128 v[194:197], v228 offset:40448
	v_exp_f32_e32 v225, v105
	v_add_f32_e32 v164, v224, v164
	v_cvt_pk_bf16_f32 v217, v224, v225
	v_add_f32_e64 v164, v225, v164
	v_exp_f32_e32 v222, v106
	s_waitcnt lgkmcnt(3)
	v_mfma_f32_32x32x16_bf16 v[34:49], v[182:185], v[134:137], v[34:49]
	ds_read_b128 v[198:201], v228 offset:35872
	v_exp_f32_e32 v223, v107
	v_add_f32_e32 v164, v222, v164
	v_cvt_pk_bf16_f32 v218, v222, v223
	v_add_f32_e64 v164, v223, v164
	v_exp_f32_e32 v224, v108
	s_waitcnt lgkmcnt(3)
	v_mfma_f32_32x32x16_bf16 v[50:65], v[186:189], v[134:137], v[50:65]
	ds_read_b128 v[182:185], v228 offset:40480
	v_exp_f32_e32 v225, v109
	v_add_f32_e32 v164, v224, v164
	v_cvt_pk_bf16_f32 v219, v224, v225
	v_add_f32_e64 v164, v225, v164
	v_exp_f32_e32 v222, v110
	s_waitcnt lgkmcnt(3)
	v_mfma_f32_32x32x16_bf16 v[2:17], v[190:193], v[206:209], v[2:17]
	ds_read_b128 v[186:189], v228 offset:35904
	v_exp_f32_e32 v223, v111
	v_add_f32_e32 v164, v222, v164
	v_cvt_pk_bf16_f32 v220, v222, v223
	v_add_f32_e64 v164, v223, v164
	v_exp_f32_e32 v224, v112
	s_waitcnt lgkmcnt(3)
	v_mfma_f32_32x32x16_bf16 v[18:33], v[194:197], v[206:209], v[18:33]
	ds_read_b128 v[190:193], v228 offset:40512
	v_exp_f32_e32 v225, v113
	v_add_f32_e32 v164, v224, v164
	v_cvt_pk_bf16_f32 v221, v224, v225
	v_add_f32_e64 v164, v225, v164
	s_mov_b32 s13, s20
	s_mov_b32 s20, s19
	s_add_i32 s19, s19, 1
	s_cmp_eq_u32 s19, s9
	s_cselect_b32 s19, 0, s19
	s_nop 0
	s_waitcnt lgkmcnt(3)
	s_waitcnt vmcnt(2)
	v_mfma_f32_32x32x16_bf16 v[2:17], v[198:201], v[210:213], v[2:17]
	ds_read_b128 v[194:197], v228 offset:35936
	v_max3_f32 v224, v34, v35, v36
	v_max3_f32 v225, v50, v51, v52
	v_max3_f32 v224, v224, v37, v38
	v_max3_f32 v225, v225, v53, v54
	v_add_u32_e32 v222, 0xb000, v172
	ds_write_b128 v222, v[150:153] offset:26624
	v_lshl_add_u32 v222, s19, 17, v178
	global_load_dwordx4 v[150:153], v222, s[52:53]
	s_waitcnt lgkmcnt(4)
	s_and_b64 vcc, exec, s[2:3]
	v_mfma_f32_32x32x16_bf16 v[18:33], v[182:185], v[210:213], v[18:33]
	ds_read_b128 v[198:201], v228 offset:40544
	v_max3_f32 v224, v224, v39, v40
	v_max3_f32 v225, v225, v55, v56
	v_max3_f32 v224, v224, v41, v42
	v_max3_f32 v225, v225, v57, v58
	s_cbranch_vccz .Lmla_p5_nope
	s_nop 0
	v_add_u32_e32 v222, 0xb000, v176
	ds_write_b128 v222, v[160:163] offset:26752
	v_lshl_add_u32 v222, s19, 12, v179
	global_load_dwordx4 v[160:163], v222, s[62:63]
.Lmla_p5_nope:
	s_waitcnt lgkmcnt(4)
	s_nop 0
	v_mfma_f32_32x32x16_bf16 v[2:17], v[186:189], v[214:217], v[2:17]
	ds_read_b128 v[182:185], v174 offset:45056
	v_max3_f32 v224, v224, v43, v44
	v_max3_f32 v225, v225, v59, v60
	v_max3_f32 v224, v224, v45, v46
	v_max3_f32 v225, v225, v61, v62
	v_add_u32_e32 v222, 0xb000, v173
	ds_write_b128 v222, v[202:205] offset:49152
	v_lshl_add_u32 v222, s13, 7, v168
	global_load_dwordx4 v[202:205], v222, s[56:57]
	s_waitcnt lgkmcnt(5)
	s_nop 0
	v_mfma_f32_32x32x16_bf16 v[18:33], v[190:193], v[214:217], v[18:33]
	ds_read_b128 v[186:189], v174 offset:51712
	v_max3_f32 v224, v224, v47, v48
	v_max3_f32 v225, v225, v63, v64
	v_max3_f32 v224, v224, v49, v65
	v_max_f32_e64 v224, v224, v225
	s_waitcnt lgkmcnt(5)
	v_mov_b32_e32 v225, v224
	v_mfma_f32_32x32x16_bf16 v[2:17], v[194:197], v[218:221], v[2:17]
	ds_read_b128 v[190:193], v174 offset:45088
	v_add_f32_e32 v1, v1, v164
	s_add_i32 s11, s11, 1
	v_permlane32_swap_b32_e32 v224, v225
	s_cmp_eq_u32 s9, s11
	v_max_f32_e64 v167, v224, v225
	v_cmp_lt_f32_e32 vcc, s66, v167
	s_waitcnt lgkmcnt(4)
	v_mfma_f32_32x32x16_bf16 v[18:33], v[198:201], v[218:221], v[18:33]
	ds_read_b128 v[194:197], v174 offset:51744
	s_waitcnt lgkmcnt(3)
	s_barrier
	s_cbranch_scc1 .Lmla_exit_p5

; template <int VAR>
; __device__ __forceinline__ void attn_phase(LAS unsigned char* lds, const AttnP P, int vcu, int G, int wave_s) {
;     ...
;         for (int t = 0; t < nt; ++t) {
;             const bool hn = (t + 1 < nt);
;     ...
;                 if (ND0 == 6) {
;                     KR1(0); KR1(1); KR1(2); KR1(3); SB();
;                     QK1(0, negm); EX2(pc0, 0, w0.x); KR1(4); SB();
;                     QK1(1, negm); EX2(pc0, 2, w0.y); KR1(5); SB();
;                     QK1(2, pn0); EX2(pc0, 4, w0.z); KR1(6); SB();
;                     QK1(3, pn1); EX2(pc0, 6, w0.w); KR1(7); SB();
;                     QK1(4, pn0); EX2(pc0, 8, w1.x); KR1(8); SB();
;                     QK1(5, pn1); EX2(pc0, 10, w1.y); KR1(9); SB();
;                     QK1(6, pn0); EX2(pc0, 12, w1.z); KR1(10); SB();
;                     QK1(7, pn1); EX2(pc0, 14, w1.w); KR1(11); SB();
;                     QK1(8, pn0); EX2(pc1, 0, w2.x); VR1(0); SB();
;                     QK1(9, pn1); EX2(pc1, 2, w2.y); VR1(1); SB();
;                     QK1(10, pn0); EX2(pc1, 4, w2.z); VR1(2); SB();
;                     QK1(11, pn1); EX2(pc1, 6, w2.w); VR1(3); SB();
;                 } else {
;                     KR1(0); KR1(1); KR1(2); KR1(3); SB();
;                     QK1(0, negm); EX2(pc0, 0, w0.x); EX2(pc0, 2, w0.y); KR1(4); SB();
;                     QK1(1, negm); EX2(pc0, 4, w0.z); EX2(pc0, 6, w0.w); KR1(5); SB();
;                     QK1(2, pn0); EX2(pc0, 8, w1.x); EX2(pc0, 10, w1.y); KR1(6); SB();
;                     QK1(3, pn1); EX2(pc0, 12, w1.z); EX2(pc0, 14, w1.w); KR1(7); SB();
;                     QK1(4, pn0); EX2(pc1, 0, w2.x); VR1(0); SB();
;                     QK1(5, pn1); EX2(pc1, 2, w2.y); VR1(1); SB();
;                     QK1(6, pn0); EX2(pc1, 4, w2.z); VR1(2); SB();
;                     QK1(7, pn1); EX2(pc1, 6, w2.w); VR1(3); SB();
;                 }
;                 PV1(0, w0); EX2(pc1, 8, w3.x); VR1(4); SB();
;                 PV1(1, w0); EX2(pc1, 10, w3.y); VR1(5); SB();
;                 PV1(2, w1); EX2(pc1, 12, w3.z); VR1(6); SB();
;                 PV1(3, w1); EX2(pc1, 14, w3.w); VR1(7); SB();
;                 lrun += sacc;
;                 PV1(4, w2); MASK_TILE(pn0, pn1, t + 1); SB();
;                 PV1(5, w2); SB();
;                 PV1(6, w3); SB();
;                 PV1(7, w3); rmn = rowmax32(pn0, pn1); if (!USE_NEGM) rmn -= mref; SB();
.Lmla_p6_go:
	v_exp_f32_e32 v222, v34
	v_exp_f32_e32 v223, v35
	v_add_f32_e32 v164, 0, v222
	v_add_f32_e32 v164, v223, v164
	v_cvt_pk_bf16_f32 v206, v222, v223
	v_exp_f32_e32 v224, v36
	v_exp_f32_e32 v225, v37
	v_add_f32_e32 v164, v224, v164
	v_add_f32_e32 v164, v225, v164
	v_cvt_pk_bf16_f32 v207, v224, v225
	v_exp_f32_e32 v222, v38
	s_waitcnt lgkmcnt(3)
	v_mfma_f32_32x32x16_bf16 v[82:97], v[182:185], v[114:117], v[66:81]
	ds_read_b128 v[198:201], v174 offset:45120
	v_exp_f32_e32 v223, v39
	v_add_f32_e32 v164, v222, v164
	v_cvt_pk_bf16_f32 v208, v222, v223
	v_add_f32_e64 v164, v223, v164
	v_exp_f32_e32 v224, v40
	s_waitcnt lgkmcnt(3)
	v_mfma_f32_32x32x16_bf16 v[98:113], v[186:189], v[114:117], v[66:81]
	ds_read_b128 v[182:185], v174 offset:51776
	v_exp_f32_e32 v225, v41
	v_add_f32_e32 v164, v224, v164
	v_cvt_pk_bf16_f32 v209, v224, v225
	v_add_f32_e64 v164, v225, v164
	v_exp_f32_e32 v222, v42
	s_waitcnt lgkmcnt(3)
	v_mfma_f32_32x32x16_bf16 v[82:97], v[190:193], v[118:121], v[82:97]
	ds_read_b128 v[186:189], v174 offset:45152
	v_exp_f32_e32 v223, v43
	v_add_f32_e32 v164, v222, v164
	v_cvt_pk_bf16_f32 v210, v222, v223
	v_add_f32_e64 v164, v223, v164
	v_exp_f32_e32 v224, v44
	s_waitcnt lgkmcnt(3)
	v_mfma_f32_32x32x16_bf16 v[98:113], v[194:197], v[118:121], v[98:113]
	ds_read_b128 v[190:193], v174 offset:51808
	v_exp_f32_e32 v225, v45
	v_add_f32_e32 v164, v224, v164
	v_cvt_pk_bf16_f32 v211, v224, v225
	v_add_f32_e64 v164, v225, v164
	v_exp_f32_e32 v222, v46
	s_waitcnt lgkmcnt(3)
	v_mfma_f32_32x32x16_bf16 v[82:97], v[198:201], v[122:125], v[82:97]
	ds_read_b128 v[194:197], v174 offset:45184
	v_exp_f32_e32 v223, v47
	v_add_f32_e32 v164, v222, v164
	v_cvt_pk_bf16_f32 v212, v222, v223
	v_add_f32_e64 v164, v223, v164
	v_exp_f32_e32 v224, v48
	s_waitcnt lgkmcnt(3)
	v_mfma_f32_32x32x16_bf16 v[98:113], v[182:185], v[122:125], v[98:113]
	ds_read_b128 v[198:201], v174 offset:51840
	v_exp_f32_e32 v225, v49
	v_add_f32_e32 v164, v224, v164
	v_cvt_pk_bf16_f32 v213, v224, v225
	v_add_f32_e64 v164, v225, v164
	v_exp_f32_e32 v222, v50
	s_waitcnt lgkmcnt(3)
	v_mfma_f32_32x32x16_bf16 v[82:97], v[186:189], v[126:129], v[82:97]
	ds_read_b128 v[182:185], v174 offset:45216
	v_exp_f32_e32 v223, v51
	v_add_f32_e32 v164, v222, v164
	v_cvt_pk_bf16_f32 v214, v222, v223
	v_add_f32_e64 v164, v223, v164
	v_exp_f32_e32 v224, v52
	s_waitcnt lgkmcnt(3)
	v_mfma_f32_32x32x16_bf16 v[98:113], v[190:193], v[126:129], v[98:113]
	ds_read_b128 v[186:189], v174 offset:51872
	v_exp_f32_e32 v225, v53
	v_add_f32_e32 v164, v224, v164
	v_cvt_pk_bf16_f32 v215, v224, v225
	v_add_f32_e64 v164, v225, v164
	v_exp_f32_e32 v222, v54
	s_waitcnt lgkmcnt(3)
	v_mfma_f32_32x32x16_bf16 v[82:97], v[194:197], v[130:133], v[82:97]
	ds_read_b128 v[190:193], v181 offset:39936
	v_exp_f32_e32 v223, v55
	v_add_f32_e32 v164, v222, v164
	v_cvt_pk_bf16_f32 v216, v222, v223
	v_add_f32_e64 v164, v223, v164
	v_exp_f32_e32 v224, v56
	s_waitcnt lgkmcnt(3)
	v_mfma_f32_32x32x16_bf16 v[98:113], v[198:201], v[130:133], v[98:113]
	ds_read_b128 v[194:197], v181 offset:44544
	v_exp_f32_e32 v225, v57
	v_add_f32_e32 v164, v224, v164
	v_cvt_pk_bf16_f32 v217, v224, v225
	v_add_f32_e64 v164, v225, v164
	v_exp_f32_e32 v222, v58
	s_waitcnt lgkmcnt(3)
	v_mfma_f32_32x32x16_bf16 v[82:97], v[182:185], v[134:137], v[82:97]
	ds_read_b128 v[198:201], v181 offset:39968
	v_exp_f32_e32 v223, v59
	v_add_f32_e32 v164, v222, v164
	v_cvt_pk_bf16_f32 v218, v222, v223
	v_add_f32_e64 v164, v223, v164
	v_exp_f32_e32 v224, v60
	s_waitcnt lgkmcnt(3)
	v_mfma_f32_32x32x16_bf16 v[98:113], v[186:189], v[134:137], v[98:113]
	ds_read_b128 v[182:185], v181 offset:44576
	v_exp_f32_e32 v225, v61
	v_add_f32_e32 v164, v224, v164
	v_cvt_pk_bf16_f32 v219, v224, v225
	v_add_f32_e64 v164, v225, v164
	v_exp_f32_e32 v222, v62
	s_waitcnt lgkmcnt(3)
	v_mfma_f32_32x32x16_bf16 v[2:17], v[190:193], v[206:209], v[2:17]
	ds_read_b128 v[186:189], v181 offset:40000
	v_exp_f32_e32 v223, v63
	v_add_f32_e32 v164, v222, v164
	v_cvt_pk_bf16_f32 v220, v222, v223
	v_add_f32_e64 v164, v223, v164
	v_exp_f32_e32 v224, v64
	s_waitcnt lgkmcnt(3)
	v_mfma_f32_32x32x16_bf16 v[18:33], v[194:197], v[206:209], v[18:33]
	ds_read_b128 v[190:193], v181 offset:44608
	v_exp_f32_e32 v225, v65
	v_add_f32_e32 v164, v224, v164
	v_cvt_pk_bf16_f32 v221, v224, v225
	v_add_f32_e64 v164, v225, v164
	s_mov_b32 s13, s20
	s_mov_b32 s20, s19
	s_add_i32 s19, s19, 1
	s_cmp_eq_u32 s19, s9
	s_cselect_b32 s19, 0, s19
	s_nop 0
	s_waitcnt lgkmcnt(3)
	s_waitcnt vmcnt(2)
	v_mfma_f32_32x32x16_bf16 v[2:17], v[198:201], v[210:213], v[2:17]
	ds_read_b128 v[194:197], v181 offset:40032
	v_max3_f32 v224, v82, v83, v84
	v_max3_f32 v225, v98, v99, v100
	v_max3_f32 v224, v224, v85, v86
	v_max3_f32 v225, v225, v101, v102
	ds_write_b128 v172, v[146:149]
	v_lshl_add_u32 v222, s19, 17, v178
	global_load_dwordx4 v[146:149], v222, s[52:53]
	s_waitcnt lgkmcnt(4)
	s_and_b64 vcc, exec, s[2:3]
	v_mfma_f32_32x32x16_bf16 v[18:33], v[182:185], v[210:213], v[18:33]
	ds_read_b128 v[198:201], v181 offset:44640
	v_max3_f32 v224, v224, v87, v88
	v_max3_f32 v225, v225, v103, v104
	v_max3_f32 v224, v224, v89, v90
	v_max3_f32 v225, v225, v105, v106
	s_cbranch_vccz .Lmla_p6_nope
	s_nop 0
	ds_write_b128 v176, v[138:141] offset:128
	v_lshl_add_u32 v222, s19, 12, v179
	global_load_dwordx4 v[138:141], v222, s[62:63]
.Lmla_p6_nope:
	s_waitcnt lgkmcnt(4)
	s_nop 0
	v_mfma_f32_32x32x16_bf16 v[2:17], v[186:189], v[214:217], v[2:17]
	ds_read_b128 v[182:185], v229 offset:13312
	v_max3_f32 v224, v224, v91, v92
	v_max3_f32 v225, v225, v107, v108
	v_max3_f32 v224, v224, v93, v94
	v_max3_f32 v225, v225, v109, v110
	ds_write_b128 v173, v[142:145] offset:13312
	v_lshl_add_u32 v222, s13, 7, v168
	global_load_dwordx4 v[142:145], v222, s[56:57]
	s_waitcnt lgkmcnt(5)
	s_nop 0
	v_mfma_f32_32x32x16_bf16 v[18:33], v[190:193], v[214:217], v[18:33]
	ds_read_b128 v[186:189], v229 offset:19968
	v_max3_f32 v224, v224, v95, v96
	v_max3_f32 v225, v225, v111, v112
	v_max3_f32 v224, v224, v97, v113
	v_max_f32_e64 v224, v224, v225
	s_waitcnt lgkmcnt(5)
	v_mov_b32_e32 v225, v224
	v_mfma_f32_32x32x16_bf16 v[2:17], v[194:197], v[218:221], v[2:17]
	ds_read_b128 v[190:193], v229 offset:13344
	v_add_f32_e32 v1, v1, v164
	s_add_i32 s11, s11, 1
	v_permlane32_swap_b32_e32 v224, v225
	s_cmp_eq_u32 s9, s11
	v_max_f32_e64 v167, v224, v225
	v_cmp_lt_f32_e32 vcc, s66, v167
	s_waitcnt lgkmcnt(4)
	v_mfma_f32_32x32x16_bf16 v[18:33], v[198:201], v[218:221], v[18:33]
	ds_read_b128 v[194:197], v229 offset:20000
	s_cbranch_scc1 .Lmla_exit_p6

; template <int VAR>
; __device__ __forceinline__ void attn_phase(LAS unsigned char* lds, const AttnP P, int vcu, int G, int wave_s) {
;     ...
;         for (int t = 0; t < nt; ++t) {
;             const bool hn = (t + 1 < nt);
;     ...
;                 if (ND0 == 6) {
;                     KR1(0); KR1(1); KR1(2); KR1(3); SB();
;                     QK1(0, negm); EX2(pc0, 0, w0.x); KR1(4); SB();
;                     QK1(1, negm); EX2(pc0, 2, w0.y); KR1(5); SB();
;                     QK1(2, pn0); EX2(pc0, 4, w0.z); KR1(6); SB();
;                     QK1(3, pn1); EX2(pc0, 6, w0.w); KR1(7); SB();
;                     QK1(4, pn0); EX2(pc0, 8, w1.x); KR1(8); SB();
;                     QK1(5, pn1); EX2(pc0, 10, w1.y); KR1(9); SB();
;                     QK1(6, pn0); EX2(pc0, 12, w1.z); KR1(10); SB();
;                     QK1(7, pn1); EX2(pc0, 14, w1.w); KR1(11); SB();
;                     QK1(8, pn0); EX2(pc1, 0, w2.x); VR1(0); SB();
;                     QK1(9, pn1); EX2(pc1, 2, w2.y); VR1(1); SB();
;                     QK1(10, pn0); EX2(pc1, 4, w2.z); VR1(2); SB();
;                     QK1(11, pn1); EX2(pc1, 6, w2.w); VR1(3); SB();
;                 } else {
;                     KR1(0); KR1(1); KR1(2); KR1(3); SB();
;                     QK1(0, negm); EX2(pc0, 0, w0.x); EX2(pc0, 2, w0.y); KR1(4); SB();
;                     QK1(1, negm); EX2(pc0, 4, w0.z); EX2(pc0, 6, w0.w); KR1(5); SB();
;                     QK1(2, pn0); EX2(pc0, 8, w1.x); EX2(pc0, 10, w1.y); KR1(6); SB();
;                     QK1(3, pn1); EX2(pc0, 12, w1.z); EX2(pc0, 14, w1.w); KR1(7); SB();
;                     QK1(4, pn0); EX2(pc1, 0, w2.x); VR1(0); SB();
;                     QK1(5, pn1); EX2(pc1, 2, w2.y); VR1(1); SB();
;                     QK1(6, pn0); EX2(pc1, 4, w2.z); VR1(2); SB();
;                     QK1(7, pn1); EX2(pc1, 6, w2.w); VR1(3); SB();
;                 }
;                 PV1(0, w0); EX2(pc1, 8, w3.x); VR1(4); SB();
;                 PV1(1, w0); EX2(pc1, 10, w3.y); VR1(5); SB();
;                 PV1(2, w1); EX2(pc1, 12, w3.z); VR1(6); SB();
;                 PV1(3, w1); EX2(pc1, 14, w3.w); VR1(7); SB();
;                 lrun += sacc;
;                 PV1(4, w2); MASK_TILE(pn0, pn1, t + 1); SB();
;                 PV1(5, w2); SB();
;                 PV1(6, w3); SB();
;                 PV1(7, w3); rmn = rowmax32(pn0, pn1); if (!USE_NEGM) rmn -= mref; SB();
.Lmla_p7_go:
	v_exp_f32_e32 v222, v82
	v_exp_f32_e32 v223, v83
	v_add_f32_e32 v164, 0, v222
	v_add_f32_e32 v164, v223, v164
	v_cvt_pk_bf16_f32 v206, v222, v223
	v_exp_f32_e32 v224, v84
	v_exp_f32_e32 v225, v85
	v_add_f32_e32 v164, v224, v164
	v_add_f32_e32 v164, v225, v164
	v_cvt_pk_bf16_f32 v207, v224, v225
	v_exp_f32_e32 v222, v86
	s_waitcnt lgkmcnt(4)
	v_mfma_f32_32x32x16_bf16 v[34:49], v[182:185], v[114:117], v[66:81]
	ds_read_b128 v[198:201], v229 offset:13376
	v_exp_f32_e32 v223, v87
	v_add_f32_e32 v164, v222, v164
	v_cvt_pk_bf16_f32 v208, v222, v223
	v_add_f32_e64 v164, v223, v164
	v_exp_f32_e32 v224, v88
	s_waitcnt lgkmcnt(3)
	v_mfma_f32_32x32x16_bf16 v[50:65], v[186:189], v[114:117], v[66:81]
	ds_read_b128 v[182:185], v229 offset:20032
	v_exp_f32_e32 v225, v89
	v_add_f32_e32 v164, v224, v164
	v_cvt_pk_bf16_f32 v209, v224, v225
	v_add_f32_e64 v164, v225, v164
	v_exp_f32_e32 v222, v90
	s_waitcnt lgkmcnt(3)
	v_mfma_f32_32x32x16_bf16 v[34:49], v[190:193], v[118:121], v[34:49]
	ds_read_b128 v[186:189], v229 offset:13408
	v_exp_f32_e32 v223, v91
	v_add_f32_e32 v164, v222, v164
	v_cvt_pk_bf16_f32 v210, v222, v223
	v_add_f32_e64 v164, v223, v164
	v_exp_f32_e32 v224, v92
	s_waitcnt lgkmcnt(3)
	v_mfma_f32_32x32x16_bf16 v[50:65], v[194:197], v[118:121], v[50:65]
	ds_read_b128 v[190:193], v229 offset:20064
	v_exp_f32_e32 v225, v93
	v_add_f32_e32 v164, v224, v164
	v_cvt_pk_bf16_f32 v211, v224, v225
	v_add_f32_e64 v164, v225, v164
	v_exp_f32_e32 v222, v94
	s_waitcnt lgkmcnt(3)
	v_mfma_f32_32x32x16_bf16 v[34:49], v[198:201], v[122:125], v[34:49]
	ds_read_b128 v[194:197], v229 offset:13440
	v_exp_f32_e32 v223, v95
	v_add_f32_e32 v164, v222, v164
	v_cvt_pk_bf16_f32 v212, v222, v223
	v_add_f32_e64 v164, v223, v164
	v_exp_f32_e32 v224, v96
	s_waitcnt lgkmcnt(3)
	v_mfma_f32_32x32x16_bf16 v[50:65], v[182:185], v[122:125], v[50:65]
	ds_read_b128 v[198:201], v229 offset:20096
	v_exp_f32_e32 v225, v97
	v_add_f32_e32 v164, v224, v164
	v_cvt_pk_bf16_f32 v213, v224, v225
	v_add_f32_e64 v164, v225, v164
	v_exp_f32_e32 v222, v98
	s_waitcnt lgkmcnt(3)
	v_mfma_f32_32x32x16_bf16 v[34:49], v[186:189], v[126:129], v[34:49]
	ds_read_b128 v[182:185], v229 offset:13472
	v_exp_f32_e32 v223, v99
	v_add_f32_e32 v164, v222, v164
	v_cvt_pk_bf16_f32 v214, v222, v223
	v_add_f32_e64 v164, v223, v164
	v_exp_f32_e32 v224, v100
	s_waitcnt lgkmcnt(3)
	v_mfma_f32_32x32x16_bf16 v[50:65], v[190:193], v[126:129], v[50:65]
	ds_read_b128 v[186:189], v229 offset:20128
	v_exp_f32_e32 v225, v101
	v_add_f32_e32 v164, v224, v164
	v_cvt_pk_bf16_f32 v215, v224, v225
	v_add_f32_e64 v164, v225, v164
	v_exp_f32_e32 v222, v102
	s_waitcnt lgkmcnt(3)
	v_mfma_f32_32x32x16_bf16 v[34:49], v[194:197], v[130:133], v[34:49]
	ds_read_b128 v[190:193], v181 offset:49152
	v_exp_f32_e32 v223, v103
	v_add_f32_e32 v164, v222, v164
	v_cvt_pk_bf16_f32 v216, v222, v223
	v_add_f32_e64 v164, v223, v164
	v_exp_f32_e32 v224, v104
	s_waitcnt lgkmcnt(3)
	v_mfma_f32_32x32x16_bf16 v[50:65], v[198:201], v[130:133], v[50:65]
	ds_read_b128 v[194:197], v181 offset:53760
	v_exp_f32_e32 v225, v105
	v_add_f32_e32 v164, v224, v164
	v_cvt_pk_bf16_f32 v217, v224, v225
	v_add_f32_e64 v164, v225, v164
	v_exp_f32_e32 v222, v106
	s_waitcnt lgkmcnt(3)
	v_mfma_f32_32x32x16_bf16 v[34:49], v[182:185], v[134:137], v[34:49]
	ds_read_b128 v[198:201], v181 offset:49184
	v_exp_f32_e32 v223, v107
	v_add_f32_e32 v164, v222, v164
	v_cvt_pk_bf16_f32 v218, v222, v223
	v_add_f32_e64 v164, v223, v164
	v_exp_f32_e32 v224, v108
	s_waitcnt lgkmcnt(3)
	v_mfma_f32_32x32x16_bf16 v[50:65], v[186:189], v[134:137], v[50:65]
	ds_read_b128 v[182:185], v181 offset:53792
	v_exp_f32_e32 v225, v109
	v_add_f32_e32 v164, v224, v164
	v_cvt_pk_bf16_f32 v219, v224, v225
	v_add_f32_e64 v164, v225, v164
	v_exp_f32_e32 v222, v110
	s_waitcnt lgkmcnt(3)
	v_mfma_f32_32x32x16_bf16 v[2:17], v[190:193], v[206:209], v[2:17]
	ds_read_b128 v[186:189], v181 offset:49216
	v_exp_f32_e32 v223, v111
	v_add_f32_e32 v164, v222, v164
	v_cvt_pk_bf16_f32 v220, v222, v223
	v_add_f32_e64 v164, v223, v164
	v_exp_f32_e32 v224, v112
	s_waitcnt lgkmcnt(3)
	v_mfma_f32_32x32x16_bf16 v[18:33], v[194:197], v[206:209], v[18:33]
	ds_read_b128 v[190:193], v181 offset:53824
	v_exp_f32_e32 v225, v113
	v_add_f32_e32 v164, v224, v164
	v_cvt_pk_bf16_f32 v221, v224, v225
	v_add_f32_e64 v164, v225, v164
	s_mov_b32 s13, s20
	s_mov_b32 s20, s19
	s_add_i32 s19, s19, 1
	s_cmp_eq_u32 s19, s9
	s_cselect_b32 s19, 0, s19
	s_nop 0
	s_waitcnt lgkmcnt(3)
	s_waitcnt vmcnt(2)
	v_mfma_f32_32x32x16_bf16 v[2:17], v[198:201], v[210:213], v[2:17]
	ds_read_b128 v[194:197], v181 offset:49248
	v_max3_f32 v224, v34, v35, v36
	v_max3_f32 v225, v50, v51, v52
	v_max3_f32 v224, v224, v37, v38
	v_max3_f32 v225, v225, v53, v54
	ds_write_b128 v172, v[150:153] offset:22528
	v_lshl_add_u32 v222, s19, 17, v178
	global_load_dwordx4 v[150:153], v222, s[52:53]
	s_waitcnt lgkmcnt(4)
	s_and_b64 vcc, exec, s[2:3]
	v_mfma_f32_32x32x16_bf16 v[18:33], v[182:185], v[210:213], v[18:33]
	ds_read_b128 v[198:201], v181 offset:53856
	v_max3_f32 v224, v224, v39, v40
	v_max3_f32 v225, v225, v55, v56
	v_max3_f32 v224, v224, v41, v42
	v_max3_f32 v225, v225, v57, v58
	s_cbranch_vccz .Lmla_p7_nope
	s_nop 0
	ds_write_b128 v176, v[160:163] offset:22656
	v_lshl_add_u32 v222, s19, 12, v179
	global_load_dwordx4 v[160:163], v222, s[62:63]
.Lmla_p7_nope:
	s_waitcnt lgkmcnt(4)
	s_nop 0
	v_mfma_f32_32x32x16_bf16 v[2:17], v[186:189], v[214:217], v[2:17]
	ds_read_b128 v[182:185], v229 offset:26624
	v_max3_f32 v224, v224, v43, v44
	v_max3_f32 v225, v225, v59, v60
	v_max3_f32 v224, v224, v45, v46
	v_max3_f32 v225, v225, v61, v62
	ds_write_b128 v173, v[202:205] offset:35840
	v_lshl_add_u32 v222, s13, 7, v168
	global_load_dwordx4 v[202:205], v222, s[56:57]
	s_waitcnt lgkmcnt(5)
	s_nop 0
	v_mfma_f32_32x32x16_bf16 v[18:33], v[190:193], v[214:217], v[18:33]
	ds_read_b128 v[186:189], v229 offset:33280
	v_max3_f32 v224, v224, v47, v48
	v_max3_f32 v225, v225, v63, v64
	v_max3_f32 v224, v224, v49, v65
	v_max_f32_e64 v224, v224, v225
	s_waitcnt lgkmcnt(5)
	v_mov_b32_e32 v225, v224
	v_mfma_f32_32x32x16_bf16 v[2:17], v[194:197], v[218:221], v[2:17]
	ds_read_b128 v[190:193], v229 offset:26656
	v_add_f32_e32 v1, v1, v164
	s_add_i32 s11, s11, 1
	v_permlane32_swap_b32_e32 v224, v225
	s_cmp_eq_u32 s9, s11
	v_max_f32_e64 v167, v224, v225
	v_cmp_lt_f32_e32 vcc, s66, v167
	s_waitcnt lgkmcnt(4)
	v_mfma_f32_32x32x16_bf16 v[18:33], v[198:201], v[218:221], v[18:33]
	ds_read_b128 v[194:197], v229 offset:33312
	s_waitcnt lgkmcnt(3)
	s_barrier
	s_cbranch_scc1 .Lmla_exit_p7

; template <int VAR>
; __device__ __forceinline__ void attn_phase(LAS unsigned char* lds, const AttnP P, int vcu, int G, int wave_s) {
;     ...
;         for (int t = 0; t < nt; ++t) {
;             const bool hn = (t + 1 < nt);
;     ...
;                 if (ND0 == 6) {
;                     KR1(0); KR1(1); KR1(2); KR1(3); SB();
;                     QK1(0, negm); EX2(pc0, 0, w0.x); KR1(4); SB();
;                     QK1(1, negm); EX2(pc0, 2, w0.y); KR1(5); SB();
;                     QK1(2, pn0); EX2(pc0, 4, w0.z); KR1(6); SB();
;                     QK1(3, pn1); EX2(pc0, 6, w0.w); KR1(7); SB();
;                     QK1(4, pn0); EX2(pc0, 8, w1.x); KR1(8); SB();
;                     QK1(5, pn1); EX2(pc0, 10, w1.y); KR1(9); SB();
;                     QK1(6, pn0); EX2(pc0, 12, w1.z); KR1(10); SB();
;                     QK1(7, pn1); EX2(pc0, 14, w1.w); KR1(11); SB();
;                     QK1(8, pn0); EX2(pc1, 0, w2.x); VR1(0); SB();
;                     QK1(9, pn1); EX2(pc1, 2, w2.y); VR1(1); SB();
;                     QK1(10, pn0); EX2(pc1, 4, w2.z); VR1(2); SB();
;                     QK1(11, pn1); EX2(pc1, 6, w2.w); VR1(3); SB();
;                 } else {
;                     KR1(0); KR1(1); KR1(2); KR1(3); SB();
;                     QK1(0, negm); EX2(pc0, 0, w0.x); EX2(pc0, 2, w0.y); KR1(4); SB();
;                     QK1(1, negm); EX2(pc0, 4, w0.z); EX2(pc0, 6, w0.w); KR1(5); SB();
;                     QK1(2, pn0); EX2(pc0, 8, w1.x); EX2(pc0, 10, w1.y); KR1(6); SB();
;                     QK1(3, pn1); EX2(pc0, 12, w1.z); EX2(pc0, 14, w1.w); KR1(7); SB();
;                     QK1(4, pn0); EX2(pc1, 0, w2.x); VR1(0); SB();
;                     QK1(5, pn1); EX2(pc1, 2, w2.y); VR1(1); SB();
;                     QK1(6, pn0); EX2(pc1, 4, w2.z); VR1(2); SB();
;                     QK1(7, pn1); EX2(pc1, 6, w2.w); VR1(3); SB();
;                 }
;                 PV1(0, w0); EX2(pc1, 8, w3.x); VR1(4); SB();
;                 PV1(1, w0); EX2(pc1, 10, w3.y); VR1(5); SB();
;                 PV1(2, w1); EX2(pc1, 12, w3.z); VR1(6); SB();
;                 PV1(3, w1); EX2(pc1, 14, w3.w); VR1(7); SB();
;                 lrun += sacc;
;                 PV1(4, w2); MASK_TILE(pn0, pn1, t + 1); SB();
;                 PV1(5, w2); SB();
;                 PV1(6, w3); SB();
;                 PV1(7, w3); rmn = rowmax32(pn0, pn1); if (!USE_NEGM) rmn -= mref; SB();
.Lmla_p8_go:
	v_exp_f32_e32 v222, v34
	v_exp_f32_e32 v223, v35
	v_add_f32_e32 v164, 0, v222
	v_add_f32_e32 v164, v223, v164
	v_cvt_pk_bf16_f32 v206, v222, v223
	v_exp_f32_e32 v224, v36
	v_exp_f32_e32 v225, v37
	v_add_f32_e32 v164, v224, v164
	v_add_f32_e32 v164, v225, v164
	v_cvt_pk_bf16_f32 v207, v224, v225
	v_exp_f32_e32 v222, v38
	s_waitcnt lgkmcnt(3)
	v_mfma_f32_32x32x16_bf16 v[82:97], v[182:185], v[114:117], v[66:81]
	ds_read_b128 v[198:201], v229 offset:26688
	v_exp_f32_e32 v223, v39
	v_add_f32_e32 v164, v222, v164
	v_cvt_pk_bf16_f32 v208, v222, v223
	v_add_f32_e64 v164, v223, v164
	v_exp_f32_e32 v224, v40
	s_waitcnt lgkmcnt(3)
	v_mfma_f32_32x32x16_bf16 v[98:113], v[186:189], v[114:117], v[66:81]
	ds_read_b128 v[182:185], v229 offset:33344
	v_exp_f32_e32 v225, v41
	v_add_f32_e32 v164, v224, v164
	v_cvt_pk_bf16_f32 v209, v224, v225
	v_add_f32_e64 v164, v225, v164
	v_exp_f32_e32 v222, v42
	s_waitcnt lgkmcnt(3)
	v_mfma_f32_32x32x16_bf16 v[82:97], v[190:193], v[118:121], v[82:97]
	ds_read_b128 v[186:189], v229 offset:26720
	v_exp_f32_e32 v223, v43
	v_add_f32_e32 v164, v222, v164
	v_cvt_pk_bf16_f32 v210, v222, v223
	v_add_f32_e64 v164, v223, v164
	v_exp_f32_e32 v224, v44
	s_waitcnt lgkmcnt(3)
	v_mfma_f32_32x32x16_bf16 v[98:113], v[194:197], v[118:121], v[98:113]
	ds_read_b128 v[190:193], v229 offset:33376
	v_exp_f32_e32 v225, v45
	v_add_f32_e32 v164, v224, v164
	v_cvt_pk_bf16_f32 v211, v224, v225
	v_add_f32_e64 v164, v225, v164
	v_exp_f32_e32 v222, v46
	s_waitcnt lgkmcnt(3)
	v_mfma_f32_32x32x16_bf16 v[82:97], v[198:201], v[122:125], v[82:97]
	ds_read_b128 v[194:197], v229 offset:26752
	v_exp_f32_e32 v223, v47
	v_add_f32_e32 v164, v222, v164
	v_cvt_pk_bf16_f32 v212, v222, v223
	v_add_f32_e64 v164, v223, v164
	v_exp_f32_e32 v224, v48
	s_waitcnt lgkmcnt(3)
	v_mfma_f32_32x32x16_bf16 v[98:113], v[182:185], v[122:125], v[98:113]
	ds_read_b128 v[198:201], v229 offset:33408
	v_exp_f32_e32 v225, v49
	v_add_f32_e32 v164, v224, v164
	v_cvt_pk_bf16_f32 v213, v224, v225
	v_add_f32_e64 v164, v225, v164
	v_exp_f32_e32 v222, v50
	s_waitcnt lgkmcnt(3)
	v_mfma_f32_32x32x16_bf16 v[82:97], v[186:189], v[126:129], v[82:97]
	ds_read_b128 v[182:185], v229 offset:26784
	v_exp_f32_e32 v223, v51
	v_add_f32_e32 v164, v222, v164
	v_cvt_pk_bf16_f32 v214, v222, v223
	v_add_f32_e64 v164, v223, v164
	v_exp_f32_e32 v224, v52
	s_waitcnt lgkmcnt(3)
	v_mfma_f32_32x32x16_bf16 v[98:113], v[190:193], v[126:129], v[98:113]
	ds_read_b128 v[186:189], v229 offset:33440
	v_exp_f32_e32 v225, v53
	v_add_f32_e32 v164, v224, v164
	v_cvt_pk_bf16_f32 v215, v224, v225
	v_add_f32_e64 v164, v225, v164
	v_exp_f32_e32 v222, v54
	s_waitcnt lgkmcnt(3)
	v_mfma_f32_32x32x16_bf16 v[82:97], v[194:197], v[130:133], v[82:97]
	ds_read_b128 v[190:193], v228 offset:13312
	v_exp_f32_e32 v223, v55
	v_add_f32_e32 v164, v222, v164
	v_cvt_pk_bf16_f32 v216, v222, v223
	v_add_f32_e64 v164, v223, v164
	v_exp_f32_e32 v224, v56
	s_waitcnt lgkmcnt(3)
	v_mfma_f32_32x32x16_bf16 v[98:113], v[198:201], v[130:133], v[98:113]
	ds_read_b128 v[194:197], v228 offset:17920
	v_exp_f32_e32 v225, v57
	v_add_f32_e32 v164, v224, v164
	v_cvt_pk_bf16_f32 v217, v224, v225
	v_add_f32_e64 v164, v225, v164
	v_exp_f32_e32 v222, v58
	s_waitcnt lgkmcnt(3)
	v_mfma_f32_32x32x16_bf16 v[82:97], v[182:185], v[134:137], v[82:97]
	ds_read_b128 v[198:201], v228 offset:13344
	v_exp_f32_e32 v223, v59
	v_add_f32_e32 v164, v222, v164
	v_cvt_pk_bf16_f32 v218, v222, v223
	v_add_f32_e64 v164, v223, v164
	v_exp_f32_e32 v224, v60
	s_waitcnt lgkmcnt(3)
	v_mfma_f32_32x32x16_bf16 v[98:113], v[186:189], v[134:137], v[98:113]
	ds_read_b128 v[182:185], v228 offset:17952
	v_exp_f32_e32 v225, v61
	v_add_f32_e32 v164, v224, v164
	v_cvt_pk_bf16_f32 v219, v224, v225
	v_add_f32_e64 v164, v225, v164
	v_exp_f32_e32 v222, v62
	s_waitcnt lgkmcnt(3)
	v_mfma_f32_32x32x16_bf16 v[2:17], v[190:193], v[206:209], v[2:17]
	ds_read_b128 v[186:189], v228 offset:13376
	v_exp_f32_e32 v223, v63
	v_add_f32_e32 v164, v222, v164
	v_cvt_pk_bf16_f32 v220, v222, v223
	v_add_f32_e64 v164, v223, v164
	v_exp_f32_e32 v224, v64
	s_waitcnt lgkmcnt(3)
	v_mfma_f32_32x32x16_bf16 v[18:33], v[194:197], v[206:209], v[18:33]
	ds_read_b128 v[190:193], v228 offset:17984
	v_exp_f32_e32 v225, v65
	v_add_f32_e32 v164, v224, v164
	v_cvt_pk_bf16_f32 v221, v224, v225
	v_add_f32_e64 v164, v225, v164
	s_mov_b32 s13, s20
	s_mov_b32 s20, s19
	s_add_i32 s19, s19, 1
	s_cmp_eq_u32 s19, s9
	s_cselect_b32 s19, 0, s19
	s_nop 0
	s_waitcnt lgkmcnt(3)
	s_waitcnt vmcnt(2)
	v_mfma_f32_32x32x16_bf16 v[2:17], v[198:201], v[210:213], v[2:17]
	ds_read_b128 v[194:197], v228 offset:13408
	v_max3_f32 v224, v82, v83, v84
	v_max3_f32 v225, v98, v99, v100
	v_max3_f32 v224, v224, v85, v86
	v_max3_f32 v225, v225, v101, v102
	ds_write_b128 v172, v[146:149] offset:45056
	v_lshl_add_u32 v222, s19, 17, v178
	global_load_dwordx4 v[146:149], v222, s[52:53]
	s_waitcnt lgkmcnt(4)
	s_and_b64 vcc, exec, s[2:3]
	v_mfma_f32_32x32x16_bf16 v[18:33], v[182:185], v[210:213], v[18:33]
	ds_read_b128 v[198:201], v228 offset:18016
	v_max3_f32 v224, v224, v87, v88
	v_max3_f32 v225, v225, v103, v104
	v_max3_f32 v224, v224, v89, v90
	v_max3_f32 v225, v225, v105, v106
	s_cbranch_vccz .Lmla_p8_nope
	s_nop 0
	ds_write_b128 v176, v[138:141] offset:45184
	v_lshl_add_u32 v222, s19, 12, v179
	global_load_dwordx4 v[138:141], v222, s[62:63]
.Lmla_p8_nope:
	s_waitcnt lgkmcnt(4)
	s_nop 0
	v_mfma_f32_32x32x16_bf16 v[2:17], v[186:189], v[214:217], v[2:17]
	ds_read_b128 v[182:185], v174
	v_max3_f32 v224, v224, v91, v92
	v_max3_f32 v225, v225, v107, v108
	v_max3_f32 v224, v224, v93, v94
	v_max3_f32 v225, v225, v109, v110
	v_add_u32_e32 v222, 0xb000, v173
	ds_write_b128 v222, v[142:145] offset:39936
	v_lshl_add_u32 v222, s13, 7, v168
	global_load_dwordx4 v[142:145], v222, s[56:57]
	s_waitcnt lgkmcnt(5)
	s_nop 0
	v_mfma_f32_32x32x16_bf16 v[18:33], v[190:193], v[214:217], v[18:33]
	ds_read_b128 v[186:189], v174 offset:6656
	v_max3_f32 v224, v224, v95, v96
	v_max3_f32 v225, v225, v111, v112
	v_max3_f32 v224, v224, v97, v113
	v_max_f32_e64 v224, v224, v225
	s_waitcnt lgkmcnt(5)
	v_mov_b32_e32 v225, v224
	v_mfma_f32_32x32x16_bf16 v[2:17], v[194:197], v[218:221], v[2:17]
	ds_read_b128 v[190:193], v174 offset:32
	v_add_f32_e32 v1, v1, v164
	s_add_i32 s11, s11, 1
	v_permlane32_swap_b32_e32 v224, v225
	s_cmp_eq_u32 s9, s11
	v_max_f32_e64 v167, v224, v225
	v_cmp_lt_f32_e32 vcc, s66, v167
	s_waitcnt lgkmcnt(4)
	v_mfma_f32_32x32x16_bf16 v[18:33], v[198:201], v[218:221], v[18:33]
	ds_read_b128 v[194:197], v174 offset:6688
	s_cbranch_scc1 .Lmla_exit_p8

; template <int VAR>
; __device__ __forceinline__ void attn_phase(LAS unsigned char* lds, const AttnP P, int vcu, int G, int wave_s) {
;     ...
;         for (int t = 0; t < nt; ++t) {
;             const bool hn = (t + 1 < nt);
;     ...
;                 if (ND0 == 6) {
;                     KR1(0); KR1(1); KR1(2); KR1(3); SB();
;                     QK1(0, negm); EX2(pc0, 0, w0.x); KR1(4); SB();
;                     QK1(1, negm); EX2(pc0, 2, w0.y); KR1(5); SB();
;                     QK1(2, pn0); EX2(pc0, 4, w0.z); KR1(6); SB();
;                     QK1(3, pn1); EX2(pc0, 6, w0.w); KR1(7); SB();
;                     QK1(4, pn0); EX2(pc0, 8, w1.x); KR1(8); SB();
;                     QK1(5, pn1); EX2(pc0, 10, w1.y); KR1(9); SB();
;                     QK1(6, pn0); EX2(pc0, 12, w1.z); KR1(10); SB();
;                     QK1(7, pn1); EX2(pc0, 14, w1.w); KR1(11); SB();
;                     QK1(8, pn0); EX2(pc1, 0, w2.x); VR1(0); SB();
;                     QK1(9, pn1); EX2(pc1, 2, w2.y); VR1(1); SB();
;                     QK1(10, pn0); EX2(pc1, 4, w2.z); VR1(2); SB();
;                     QK1(11, pn1); EX2(pc1, 6, w2.w); VR1(3); SB();
;                 } else {
;                     KR1(0); KR1(1); KR1(2); KR1(3); SB();
;                     QK1(0, negm); EX2(pc0, 0, w0.x); EX2(pc0, 2, w0.y); KR1(4); SB();
;                     QK1(1, negm); EX2(pc0, 4, w0.z); EX2(pc0, 6, w0.w); KR1(5); SB();
;                     QK1(2, pn0); EX2(pc0, 8, w1.x); EX2(pc0, 10, w1.y); KR1(6); SB();
;                     QK1(3, pn1); EX2(pc0, 12, w1.z); EX2(pc0, 14, w1.w); KR1(7); SB();
;                     QK1(4, pn0); EX2(pc1, 0, w2.x); VR1(0); SB();
;                     QK1(5, pn1); EX2(pc1, 2, w2.y); VR1(1); SB();
;                     QK1(6, pn0); EX2(pc1, 4, w2.z); VR1(2); SB();
;                     QK1(7, pn1); EX2(pc1, 6, w2.w); VR1(3); SB();
;                 }
;                 PV1(0, w0); EX2(pc1, 8, w3.x); VR1(4); SB();
;                 PV1(1, w0); EX2(pc1, 10, w3.y); VR1(5); SB();
;                 PV1(2, w1); EX2(pc1, 12, w3.z); VR1(6); SB();
;                 PV1(3, w1); EX2(pc1, 14, w3.w); VR1(7); SB();
;                 lrun += sacc;
;                 PV1(4, w2); MASK_TILE(pn0, pn1, t + 1); SB();
;                 PV1(5, w2); SB();
;                 PV1(6, w3); SB();
;                 PV1(7, w3); rmn = rowmax32(pn0, pn1); if (!USE_NEGM) rmn -= mref; SB();
.Lmla_p9_go:
	v_exp_f32_e32 v222, v82
	v_exp_f32_e32 v223, v83
	v_add_f32_e32 v164, 0, v222
	v_add_f32_e32 v164, v223, v164
	v_cvt_pk_bf16_f32 v206, v222, v223
	v_exp_f32_e32 v224, v84
	v_exp_f32_e32 v225, v85
	v_add_f32_e32 v164, v224, v164
	v_add_f32_e32 v164, v225, v164
	v_cvt_pk_bf16_f32 v207, v224, v225
	v_exp_f32_e32 v222, v86
	s_waitcnt lgkmcnt(4)
	v_mfma_f32_32x32x16_bf16 v[34:49], v[182:185], v[114:117], v[66:81]
	ds_read_b128 v[198:201], v174 offset:64
	v_exp_f32_e32 v223, v87
	v_add_f32_e32 v164, v222, v164
	v_cvt_pk_bf16_f32 v208, v222, v223
	v_add_f32_e64 v164, v223, v164
	v_exp_f32_e32 v224, v88
	s_waitcnt lgkmcnt(3)
	v_mfma_f32_32x32x16_bf16 v[50:65], v[186:189], v[114:117], v[66:81]
	ds_read_b128 v[182:185], v174 offset:6720
	v_exp_f32_e32 v225, v89
	v_add_f32_e32 v164, v224, v164
	v_cvt_pk_bf16_f32 v209, v224, v225
	v_add_f32_e64 v164, v225, v164
	v_exp_f32_e32 v222, v90
	s_waitcnt lgkmcnt(3)
	v_mfma_f32_32x32x16_bf16 v[34:49], v[190:193], v[118:121], v[34:49]
	ds_read_b128 v[186:189], v174 offset:96
	v_exp_f32_e32 v223, v91
	v_add_f32_e32 v164, v222, v164
	v_cvt_pk_bf16_f32 v210, v222, v223
	v_add_f32_e64 v164, v223, v164
	v_exp_f32_e32 v224, v92
	s_waitcnt lgkmcnt(3)
	v_mfma_f32_32x32x16_bf16 v[50:65], v[194:197], v[118:121], v[50:65]
	ds_read_b128 v[190:193], v174 offset:6752
	v_exp_f32_e32 v225, v93
	v_add_f32_e32 v164, v224, v164
	v_cvt_pk_bf16_f32 v211, v224, v225
	v_add_f32_e64 v164, v225, v164
	v_exp_f32_e32 v222, v94
	s_waitcnt lgkmcnt(3)
	v_mfma_f32_32x32x16_bf16 v[34:49], v[198:201], v[122:125], v[34:49]
	ds_read_b128 v[194:197], v174 offset:128
	v_exp_f32_e32 v223, v95
	v_add_f32_e32 v164, v222, v164
	v_cvt_pk_bf16_f32 v212, v222, v223
	v_add_f32_e64 v164, v223, v164
	v_exp_f32_e32 v224, v96
	s_waitcnt lgkmcnt(3)
	v_mfma_f32_32x32x16_bf16 v[50:65], v[182:185], v[122:125], v[50:65]
	ds_read_b128 v[198:201], v174 offset:6784
	v_exp_f32_e32 v225, v97
	v_add_f32_e32 v164, v224, v164
	v_cvt_pk_bf16_f32 v213, v224, v225
	v_add_f32_e64 v164, v225, v164
	v_exp_f32_e32 v222, v98
	s_waitcnt lgkmcnt(3)
	v_mfma_f32_32x32x16_bf16 v[34:49], v[186:189], v[126:129], v[34:49]
	ds_read_b128 v[182:185], v174 offset:160
	v_exp_f32_e32 v223, v99
	v_add_f32_e32 v164, v222, v164
	v_cvt_pk_bf16_f32 v214, v222, v223
	v_add_f32_e64 v164, v223, v164
	v_exp_f32_e32 v224, v100
	s_waitcnt lgkmcnt(3)
	v_mfma_f32_32x32x16_bf16 v[50:65], v[190:193], v[126:129], v[50:65]
	ds_read_b128 v[186:189], v174 offset:6816
	v_exp_f32_e32 v225, v101
	v_add_f32_e32 v164, v224, v164
	v_cvt_pk_bf16_f32 v215, v224, v225
	v_add_f32_e64 v164, v225, v164
	v_exp_f32_e32 v222, v102
	s_waitcnt lgkmcnt(3)
	v_mfma_f32_32x32x16_bf16 v[34:49], v[194:197], v[130:133], v[34:49]
	ds_read_b128 v[190:193], v228 offset:35840
	v_exp_f32_e32 v223, v103
	v_add_f32_e32 v164, v222, v164
	v_cvt_pk_bf16_f32 v216, v222, v223
	v_add_f32_e64 v164, v223, v164
	v_exp_f32_e32 v224, v104
	s_waitcnt lgkmcnt(3)
	v_mfma_f32_32x32x16_bf16 v[50:65], v[198:201], v[130:133], v[50:65]
	ds_read_b128 v[194:197], v228 offset:40448
	v_exp_f32_e32 v225, v105
	v_add_f32_e32 v164, v224, v164
	v_cvt_pk_bf16_f32 v217, v224, v225
	v_add_f32_e64 v164, v225, v164
	v_exp_f32_e32 v222, v106
	s_waitcnt lgkmcnt(3)
	v_mfma_f32_32x32x16_bf16 v[34:49], v[182:185], v[134:137], v[34:49]
	ds_read_b128 v[198:201], v228 offset:35872
	v_exp_f32_e32 v223, v107
	v_add_f32_e32 v164, v222, v164
	v_cvt_pk_bf16_f32 v218, v222, v223
	v_add_f32_e64 v164, v223, v164
	v_exp_f32_e32 v224, v108
	s_waitcnt lgkmcnt(3)
	v_mfma_f32_32x32x16_bf16 v[50:65], v[186:189], v[134:137], v[50:65]
	ds_read_b128 v[182:185], v228 offset:40480
	v_exp_f32_e32 v225, v109
	v_add_f32_e32 v164, v224, v164
	v_cvt_pk_bf16_f32 v219, v224, v225
	v_add_f32_e64 v164, v225, v164
	v_exp_f32_e32 v222, v110
	s_waitcnt lgkmcnt(3)
	v_mfma_f32_32x32x16_bf16 v[2:17], v[190:193], v[206:209], v[2:17]
	ds_read_b128 v[186:189], v228 offset:35904
	v_exp_f32_e32 v223, v111
	v_add_f32_e32 v164, v222, v164
	v_cvt_pk_bf16_f32 v220, v222, v223
	v_add_f32_e64 v164, v223, v164
	v_exp_f32_e32 v224, v112
	s_waitcnt lgkmcnt(3)
	v_mfma_f32_32x32x16_bf16 v[18:33], v[194:197], v[206:209], v[18:33]
	ds_read_b128 v[190:193], v228 offset:40512
	v_exp_f32_e32 v225, v113
	v_add_f32_e32 v164, v224, v164
	v_cvt_pk_bf16_f32 v221, v224, v225
	v_add_f32_e64 v164, v225, v164
	s_mov_b32 s13, s20
	s_mov_b32 s20, s19
	s_add_i32 s19, s19, 1
	s_cmp_eq_u32 s19, s9
	s_cselect_b32 s19, 0, s19
	s_nop 0
	s_waitcnt lgkmcnt(3)
	s_waitcnt vmcnt(2)
	v_mfma_f32_32x32x16_bf16 v[2:17], v[198:201], v[210:213], v[2:17]
	ds_read_b128 v[194:197], v228 offset:35936
	v_max3_f32 v224, v34, v35, v36
	v_max3_f32 v225, v50, v51, v52
	v_max3_f32 v224, v224, v37, v38
	v_max3_f32 v225, v225, v53, v54
	ds_write_b128 v172, v[150:153] offset:58368
	v_lshl_add_u32 v222, s19, 17, v178
	global_load_dwordx4 v[150:153], v222, s[52:53]
	s_waitcnt lgkmcnt(4)
	s_and_b64 vcc, exec, s[2:3]
	v_mfma_f32_32x32x16_bf16 v[18:33], v[182:185], v[210:213], v[18:33]
	ds_read_b128 v[198:201], v228 offset:40544
	v_max3_f32 v224, v224, v39, v40
	v_max3_f32 v225, v225, v55, v56
	v_max3_f32 v224, v224, v41, v42
	v_max3_f32 v225, v225, v57, v58
	s_cbranch_vccz .Lmla_p9_nope
	s_nop 0
	ds_write_b128 v176, v[160:163] offset:58496
	v_lshl_add_u32 v222, s19, 12, v179
	global_load_dwordx4 v[160:163], v222, s[62:63]
.Lmla_p9_nope:
	s_waitcnt lgkmcnt(4)
	s_nop 0
	v_mfma_f32_32x32x16_bf16 v[2:17], v[186:189], v[214:217], v[2:17]
	ds_read_b128 v[182:185], v174 offset:22528
	v_max3_f32 v224, v224, v43, v44
	v_max3_f32 v225, v225, v59, v60
	v_max3_f32 v224, v224, v45, v46
	v_max3_f32 v225, v225, v61, v62
	v_add_u32_e32 v222, 0xb000, v173
	ds_write_b128 v222, v[202:205] offset:49152
	v_lshl_add_u32 v222, s13, 7, v168
	global_load_dwordx4 v[202:205], v222, s[56:57]
	s_waitcnt lgkmcnt(5)
	s_nop 0
	v_mfma_f32_32x32x16_bf16 v[18:33], v[190:193], v[214:217], v[18:33]
	ds_read_b128 v[186:189], v174 offset:29184
	v_max3_f32 v224, v224, v47, v48
	v_max3_f32 v225, v225, v63, v64
	v_max3_f32 v224, v224, v49, v65
	v_max_f32_e64 v224, v224, v225
	s_waitcnt lgkmcnt(5)
	v_mov_b32_e32 v225, v224
	v_mfma_f32_32x32x16_bf16 v[2:17], v[194:197], v[218:221], v[2:17]
	ds_read_b128 v[190:193], v174 offset:22560
	v_add_f32_e32 v1, v1, v164
	s_add_i32 s11, s11, 1
	v_permlane32_swap_b32_e32 v224, v225
	s_cmp_eq_u32 s9, s11
	v_max_f32_e64 v167, v224, v225
	v_cmp_lt_f32_e32 vcc, s66, v167
	s_waitcnt lgkmcnt(4)
	v_mfma_f32_32x32x16_bf16 v[18:33], v[198:201], v[218:221], v[18:33]
	ds_read_b128 v[194:197], v174 offset:29216
	s_waitcnt lgkmcnt(3)
	s_barrier
	s_cbranch_scc1 .Lmla_exit_p9

; template <int VAR>
; __device__ __forceinline__ void attn_phase(LAS unsigned char* lds, const AttnP P, int vcu, int G, int wave_s) {
;     ...
;         for (int t = 0; t < nt; ++t) {
;             const bool hn = (t + 1 < nt);
;     ...
;                 if (ND0 == 6) {
;                     KR1(0); KR1(1); KR1(2); KR1(3); SB();
;                     QK1(0, negm); EX2(pc0, 0, w0.x); KR1(4); SB();
;                     QK1(1, negm); EX2(pc0, 2, w0.y); KR1(5); SB();
;                     QK1(2, pn0); EX2(pc0, 4, w0.z); KR1(6); SB();
;                     QK1(3, pn1); EX2(pc0, 6, w0.w); KR1(7); SB();
;                     QK1(4, pn0); EX2(pc0, 8, w1.x); KR1(8); SB();
;                     QK1(5, pn1); EX2(pc0, 10, w1.y); KR1(9); SB();
;                     QK1(6, pn0); EX2(pc0, 12, w1.z); KR1(10); SB();
;                     QK1(7, pn1); EX2(pc0, 14, w1.w); KR1(11); SB();
;                     QK1(8, pn0); EX2(pc1, 0, w2.x); VR1(0); SB();
;                     QK1(9, pn1); EX2(pc1, 2, w2.y); VR1(1); SB();
;                     QK1(10, pn0); EX2(pc1, 4, w2.z); VR1(2); SB();
;                     QK1(11, pn1); EX2(pc1, 6, w2.w); VR1(3); SB();
;                 } else {
;                     KR1(0); KR1(1); KR1(2); KR1(3); SB();
;                     QK1(0, negm); EX2(pc0, 0, w0.x); EX2(pc0, 2, w0.y); KR1(4); SB();
;                     QK1(1, negm); EX2(pc0, 4, w0.z); EX2(pc0, 6, w0.w); KR1(5); SB();
;                     QK1(2, pn0); EX2(pc0, 8, w1.x); EX2(pc0, 10, w1.y); KR1(6); SB();
;                     QK1(3, pn1); EX2(pc0, 12, w1.z); EX2(pc0, 14, w1.w); KR1(7); SB();
;                     QK1(4, pn0); EX2(pc1, 0, w2.x); VR1(0); SB();
;                     QK1(5, pn1); EX2(pc1, 2, w2.y); VR1(1); SB();
;                     QK1(6, pn0); EX2(pc1, 4, w2.z); VR1(2); SB();
;                     QK1(7, pn1); EX2(pc1, 6, w2.w); VR1(3); SB();
;                 }
;                 PV1(0, w0); EX2(pc1, 8, w3.x); VR1(4); SB();
;                 PV1(1, w0); EX2(pc1, 10, w3.y); VR1(5); SB();
;                 PV1(2, w1); EX2(pc1, 12, w3.z); VR1(6); SB();
;                 PV1(3, w1); EX2(pc1, 14, w3.w); VR1(7); SB();
;                 lrun += sacc;
;                 PV1(4, w2); MASK_TILE(pn0, pn1, t + 1); SB();
;                 PV1(5, w2); SB();
;                 PV1(6, w3); SB();
;                 PV1(7, w3); rmn = rowmax32(pn0, pn1); if (!USE_NEGM) rmn -= mref; SB();
.Lmla_p10_go:
	v_exp_f32_e32 v222, v34
	v_exp_f32_e32 v223, v35
	v_add_f32_e32 v164, 0, v222
	v_add_f32_e32 v164, v223, v164
	v_cvt_pk_bf16_f32 v206, v222, v223
	v_exp_f32_e32 v224, v36
	v_exp_f32_e32 v225, v37
	v_add_f32_e32 v164, v224, v164
	v_add_f32_e32 v164, v225, v164
	v_cvt_pk_bf16_f32 v207, v224, v225
	v_exp_f32_e32 v222, v38
	s_waitcnt lgkmcnt(3)
	v_mfma_f32_32x32x16_bf16 v[82:97], v[182:185], v[114:117], v[66:81]
	ds_read_b128 v[198:201], v174 offset:22592
	v_exp_f32_e32 v223, v39
	v_add_f32_e32 v164, v222, v164
	v_cvt_pk_bf16_f32 v208, v222, v223
	v_add_f32_e64 v164, v223, v164
	v_exp_f32_e32 v224, v40
	s_waitcnt lgkmcnt(3)
	v_mfma_f32_32x32x16_bf16 v[98:113], v[186:189], v[114:117], v[66:81]
	ds_read_b128 v[182:185], v174 offset:29248
	v_exp_f32_e32 v225, v41
	v_add_f32_e32 v164, v224, v164
	v_cvt_pk_bf16_f32 v209, v224, v225
	v_add_f32_e64 v164, v225, v164
	v_exp_f32_e32 v222, v42
	s_waitcnt lgkmcnt(3)
	v_mfma_f32_32x32x16_bf16 v[82:97], v[190:193], v[118:121], v[82:97]
	ds_read_b128 v[186:189], v174 offset:22624
	v_exp_f32_e32 v223, v43
	v_add_f32_e32 v164, v222, v164
	v_cvt_pk_bf16_f32 v210, v222, v223
	v_add_f32_e64 v164, v223, v164
	v_exp_f32_e32 v224, v44
	s_waitcnt lgkmcnt(3)
	v_mfma_f32_32x32x16_bf16 v[98:113], v[194:197], v[118:121], v[98:113]
	ds_read_b128 v[190:193], v174 offset:29280
	v_exp_f32_e32 v225, v45
	v_add_f32_e32 v164, v224, v164
	v_cvt_pk_bf16_f32 v211, v224, v225
	v_add_f32_e64 v164, v225, v164
	v_exp_f32_e32 v222, v46
	s_waitcnt lgkmcnt(3)
	v_mfma_f32_32x32x16_bf16 v[82:97], v[198:201], v[122:125], v[82:97]
	ds_read_b128 v[194:197], v174 offset:22656
	v_exp_f32_e32 v223, v47
	v_add_f32_e32 v164, v222, v164
	v_cvt_pk_bf16_f32 v212, v222, v223
	v_add_f32_e64 v164, v223, v164
	v_exp_f32_e32 v224, v48
	s_waitcnt lgkmcnt(3)
	v_mfma_f32_32x32x16_bf16 v[98:113], v[182:185], v[122:125], v[98:113]
	ds_read_b128 v[198:201], v174 offset:29312
	v_exp_f32_e32 v225, v49
	v_add_f32_e32 v164, v224, v164
	v_cvt_pk_bf16_f32 v213, v224, v225
	v_add_f32_e64 v164, v225, v164
	v_exp_f32_e32 v222, v50
	s_waitcnt lgkmcnt(3)
	v_mfma_f32_32x32x16_bf16 v[82:97], v[186:189], v[126:129], v[82:97]
	ds_read_b128 v[182:185], v174 offset:22688
	v_exp_f32_e32 v223, v51
	v_add_f32_e32 v164, v222, v164
	v_cvt_pk_bf16_f32 v214, v222, v223
	v_add_f32_e64 v164, v223, v164
	v_exp_f32_e32 v224, v52
	s_waitcnt lgkmcnt(3)
	v_mfma_f32_32x32x16_bf16 v[98:113], v[190:193], v[126:129], v[98:113]
	ds_read_b128 v[186:189], v174 offset:29344
	v_exp_f32_e32 v225, v53
	v_add_f32_e32 v164, v224, v164
	v_cvt_pk_bf16_f32 v215, v224, v225
	v_add_f32_e64 v164, v225, v164
	v_exp_f32_e32 v222, v54
	s_waitcnt lgkmcnt(3)
	v_mfma_f32_32x32x16_bf16 v[82:97], v[194:197], v[130:133], v[82:97]
	ds_read_b128 v[190:193], v181 offset:39936
	v_exp_f32_e32 v223, v55
	v_add_f32_e32 v164, v222, v164
	v_cvt_pk_bf16_f32 v216, v222, v223
	v_add_f32_e64 v164, v223, v164
	v_exp_f32_e32 v224, v56
	s_waitcnt lgkmcnt(3)
	v_mfma_f32_32x32x16_bf16 v[98:113], v[198:201], v[130:133], v[98:113]
	ds_read_b128 v[194:197], v181 offset:44544
	v_exp_f32_e32 v225, v57
	v_add_f32_e32 v164, v224, v164
	v_cvt_pk_bf16_f32 v217, v224, v225
	v_add_f32_e64 v164, v225, v164
	v_exp_f32_e32 v222, v58
	s_waitcnt lgkmcnt(3)
	v_mfma_f32_32x32x16_bf16 v[82:97], v[182:185], v[134:137], v[82:97]
	ds_read_b128 v[198:201], v181 offset:39968
	v_exp_f32_e32 v223, v59
	v_add_f32_e32 v164, v222, v164
	v_cvt_pk_bf16_f32 v218, v222, v223
	v_add_f32_e64 v164, v223, v164
	v_exp_f32_e32 v224, v60
	s_waitcnt lgkmcnt(3)
	v_mfma_f32_32x32x16_bf16 v[98:113], v[186:189], v[134:137], v[98:113]
	ds_read_b128 v[182:185], v181 offset:44576
	v_exp_f32_e32 v225, v61
	v_add_f32_e32 v164, v224, v164
	v_cvt_pk_bf16_f32 v219, v224, v225
	v_add_f32_e64 v164, v225, v164
	v_exp_f32_e32 v222, v62
	s_waitcnt lgkmcnt(3)
	v_mfma_f32_32x32x16_bf16 v[2:17], v[190:193], v[206:209], v[2:17]
	ds_read_b128 v[186:189], v181 offset:40000
	v_exp_f32_e32 v223, v63
	v_add_f32_e32 v164, v222, v164
	v_cvt_pk_bf16_f32 v220, v222, v223
	v_add_f32_e64 v164, v223, v164
	v_exp_f32_e32 v224, v64
	s_waitcnt lgkmcnt(3)
	v_mfma_f32_32x32x16_bf16 v[18:33], v[194:197], v[206:209], v[18:33]
	ds_read_b128 v[190:193], v181 offset:44608
	v_exp_f32_e32 v225, v65
	v_add_f32_e32 v164, v224, v164
	v_cvt_pk_bf16_f32 v221, v224, v225
	v_add_f32_e64 v164, v225, v164
	s_mov_b32 s13, s20
	s_mov_b32 s20, s19
	s_add_i32 s19, s19, 1
	s_cmp_eq_u32 s19, s9
	s_cselect_b32 s19, 0, s19
	s_nop 0
	s_waitcnt lgkmcnt(3)
	s_waitcnt vmcnt(2)
	v_mfma_f32_32x32x16_bf16 v[2:17], v[198:201], v[210:213], v[2:17]
	ds_read_b128 v[194:197], v181 offset:40032
	v_max3_f32 v224, v82, v83, v84
	v_max3_f32 v225, v98, v99, v100
	v_max3_f32 v224, v224, v85, v86
	v_max3_f32 v225, v225, v101, v102
	v_add_u32_e32 v222, 0xb000, v172
	ds_write_b128 v222, v[146:149] offset:26624
	v_lshl_add_u32 v222, s19, 17, v178
	global_load_dwordx4 v[146:149], v222, s[52:53]
	s_waitcnt lgkmcnt(4)
	s_and_b64 vcc, exec, s[2:3]
	v_mfma_f32_32x32x16_bf16 v[18:33], v[182:185], v[210:213], v[18:33]
	ds_read_b128 v[198:201], v181 offset:44640
	v_max3_f32 v224, v224, v87, v88
	v_max3_f32 v225, v225, v103, v104
	v_max3_f32 v224, v224, v89, v90
	v_max3_f32 v225, v225, v105, v106
	s_cbranch_vccz .Lmla_p10_nope
	s_nop 0
	v_add_u32_e32 v222, 0xb000, v176
	ds_write_b128 v222, v[138:141] offset:26752
	v_lshl_add_u32 v222, s19, 12, v179
	global_load_dwordx4 v[138:141], v222, s[62:63]
.Lmla_p10_nope:
	s_waitcnt lgkmcnt(4)
	s_nop 0
	v_mfma_f32_32x32x16_bf16 v[2:17], v[186:189], v[214:217], v[2:17]
	ds_read_b128 v[182:185], v174 offset:45056
	v_max3_f32 v224, v224, v91, v92
	v_max3_f32 v225, v225, v107, v108
	v_max3_f32 v224, v224, v93, v94
	v_max3_f32 v225, v225, v109, v110
	ds_write_b128 v173, v[142:145] offset:13312
	v_lshl_add_u32 v222, s13, 7, v168
	global_load_dwordx4 v[142:145], v222, s[56:57]
	s_waitcnt lgkmcnt(5)
	s_nop 0
	v_mfma_f32_32x32x16_bf16 v[18:33], v[190:193], v[214:217], v[18:33]
	ds_read_b128 v[186:189], v174 offset:51712
	v_max3_f32 v224, v224, v95, v96
	v_max3_f32 v225, v225, v111, v112
	v_max3_f32 v224, v224, v97, v113
	v_max_f32_e64 v224, v224, v225
	s_waitcnt lgkmcnt(5)
	v_mov_b32_e32 v225, v224
	v_mfma_f32_32x32x16_bf16 v[2:17], v[194:197], v[218:221], v[2:17]
	ds_read_b128 v[190:193], v174 offset:45088
	v_add_f32_e32 v1, v1, v164
	s_add_i32 s11, s11, 1
	v_permlane32_swap_b32_e32 v224, v225
	s_cmp_eq_u32 s9, s11
	v_max_f32_e64 v167, v224, v225
	v_cmp_lt_f32_e32 vcc, s66, v167
	s_waitcnt lgkmcnt(4)
	v_mfma_f32_32x32x16_bf16 v[18:33], v[198:201], v[218:221], v[18:33]
	ds_read_b128 v[194:197], v174 offset:51744
	s_cbranch_scc1 .Lmla_exit_p10

; template <int VAR>
; __device__ __forceinline__ void attn_phase(LAS unsigned char* lds, const AttnP P, int vcu, int G, int wave_s) {
;     ...
;         for (int t = 0; t < nt; ++t) {
;             const bool hn = (t + 1 < nt);
;     ...
;                 if (ND0 == 6) {
;                     KR1(0); KR1(1); KR1(2); KR1(3); SB();
;                     QK1(0, negm); EX2(pc0, 0, w0.x); KR1(4); SB();
;                     QK1(1, negm); EX2(pc0, 2, w0.y); KR1(5); SB();
;                     QK1(2, pn0); EX2(pc0, 4, w0.z); KR1(6); SB();
;                     QK1(3, pn1); EX2(pc0, 6, w0.w); KR1(7); SB();
;                     QK1(4, pn0); EX2(pc0, 8, w1.x); KR1(8); SB();
;                     QK1(5, pn1); EX2(pc0, 10, w1.y); KR1(9); SB();
;                     QK1(6, pn0); EX2(pc0, 12, w1.z); KR1(10); SB();
;                     QK1(7, pn1); EX2(pc0, 14, w1.w); KR1(11); SB();
;                     QK1(8, pn0); EX2(pc1, 0, w2.x); VR1(0); SB();
;                     QK1(9, pn1); EX2(pc1, 2, w2.y); VR1(1); SB();
;                     QK1(10, pn0); EX2(pc1, 4, w2.z); VR1(2); SB();
;                     QK1(11, pn1); EX2(pc1, 6, w2.w); VR1(3); SB();
;                 } else {
;                     KR1(0); KR1(1); KR1(2); KR1(3); SB();
;                     QK1(0, negm); EX2(pc0, 0, w0.x); EX2(pc0, 2, w0.y); KR1(4); SB();
;                     QK1(1, negm); EX2(pc0, 4, w0.z); EX2(pc0, 6, w0.w); KR1(5); SB();
;                     QK1(2, pn0); EX2(pc0, 8, w1.x); EX2(pc0, 10, w1.y); KR1(6); SB();
;                     QK1(3, pn1); EX2(pc0, 12, w1.z); EX2(pc0, 14, w1.w); KR1(7); SB();
;                     QK1(4, pn0); EX2(pc1, 0, w2.x); VR1(0); SB();
;                     QK1(5, pn1); EX2(pc1, 2, w2.y); VR1(1); SB();
;                     QK1(6, pn0); EX2(pc1, 4, w2.z); VR1(2); SB();
;                     QK1(7, pn1); EX2(pc1, 6, w2.w); VR1(3); SB();
;                 }
;                 PV1(0, w0); EX2(pc1, 8, w3.x); VR1(4); SB();
;                 PV1(1, w0); EX2(pc1, 10, w3.y); VR1(5); SB();
;                 PV1(2, w1); EX2(pc1, 12, w3.z); VR1(6); SB();
;                 PV1(3, w1); EX2(pc1, 14, w3.w); VR1(7); SB();
;                 lrun += sacc;
;                 PV1(4, w2); MASK_TILE(pn0, pn1, t + 1); SB();
;                 PV1(5, w2); SB();
;                 PV1(6, w3); SB();
;                 PV1(7, w3); rmn = rowmax32(pn0, pn1); if (!USE_NEGM) rmn -= mref; SB();
.Lmla_p11_go:
	v_exp_f32_e32 v222, v82
	v_exp_f32_e32 v223, v83
	v_add_f32_e32 v164, 0, v222
	v_add_f32_e32 v164, v223, v164
	v_cvt_pk_bf16_f32 v206, v222, v223
	v_exp_f32_e32 v224, v84
	v_exp_f32_e32 v225, v85
	v_add_f32_e32 v164, v224, v164
	v_add_f32_e32 v164, v225, v164
	v_cvt_pk_bf16_f32 v207, v224, v225
	v_exp_f32_e32 v222, v86
	s_waitcnt lgkmcnt(4)
	v_mfma_f32_32x32x16_bf16 v[34:49], v[182:185], v[114:117], v[66:81]
	ds_read_b128 v[198:201], v174 offset:45120
	v_exp_f32_e32 v223, v87
	v_add_f32_e32 v164, v222, v164
	v_cvt_pk_bf16_f32 v208, v222, v223
	v_add_f32_e64 v164, v223, v164
	v_exp_f32_e32 v224, v88
	s_waitcnt lgkmcnt(3)
	v_mfma_f32_32x32x16_bf16 v[50:65], v[186:189], v[114:117], v[66:81]
	ds_read_b128 v[182:185], v174 offset:51776
	v_exp_f32_e32 v225, v89
	v_add_f32_e32 v164, v224, v164
	v_cvt_pk_bf16_f32 v209, v224, v225
	v_add_f32_e64 v164, v225, v164
	v_exp_f32_e32 v222, v90
	s_waitcnt lgkmcnt(3)
	v_mfma_f32_32x32x16_bf16 v[34:49], v[190:193], v[118:121], v[34:49]
	ds_read_b128 v[186:189], v174 offset:45152
	v_exp_f32_e32 v223, v91
	v_add_f32_e32 v164, v222, v164
	v_cvt_pk_bf16_f32 v210, v222, v223
	v_add_f32_e64 v164, v223, v164
	v_exp_f32_e32 v224, v92
	s_waitcnt lgkmcnt(3)
	v_mfma_f32_32x32x16_bf16 v[50:65], v[194:197], v[118:121], v[50:65]
	ds_read_b128 v[190:193], v174 offset:51808
	v_exp_f32_e32 v225, v93
	v_add_f32_e32 v164, v224, v164
	v_cvt_pk_bf16_f32 v211, v224, v225
	v_add_f32_e64 v164, v225, v164
	v_exp_f32_e32 v222, v94
	s_waitcnt lgkmcnt(3)
	v_mfma_f32_32x32x16_bf16 v[34:49], v[198:201], v[122:125], v[34:49]
	ds_read_b128 v[194:197], v174 offset:45184
	v_exp_f32_e32 v223, v95
	v_add_f32_e32 v164, v222, v164
	v_cvt_pk_bf16_f32 v212, v222, v223
	v_add_f32_e64 v164, v223, v164
	v_exp_f32_e32 v224, v96
	s_waitcnt lgkmcnt(3)
	v_mfma_f32_32x32x16_bf16 v[50:65], v[182:185], v[122:125], v[50:65]
	ds_read_b128 v[198:201], v174 offset:51840
	v_exp_f32_e32 v225, v97
	v_add_f32_e32 v164, v224, v164
	v_cvt_pk_bf16_f32 v213, v224, v225
	v_add_f32_e64 v164, v225, v164
	v_exp_f32_e32 v222, v98
	s_waitcnt lgkmcnt(3)
	v_mfma_f32_32x32x16_bf16 v[34:49], v[186:189], v[126:129], v[34:49]
	ds_read_b128 v[182:185], v174 offset:45216
	v_exp_f32_e32 v223, v99
	v_add_f32_e32 v164, v222, v164
	v_cvt_pk_bf16_f32 v214, v222, v223
	v_add_f32_e64 v164, v223, v164
	v_exp_f32_e32 v224, v100
	s_waitcnt lgkmcnt(3)
	v_mfma_f32_32x32x16_bf16 v[50:65], v[190:193], v[126:129], v[50:65]
	ds_read_b128 v[186:189], v174 offset:51872
	v_exp_f32_e32 v225, v101
	v_add_f32_e32 v164, v224, v164
	v_cvt_pk_bf16_f32 v215, v224, v225
	v_add_f32_e64 v164, v225, v164
	v_exp_f32_e32 v222, v102
	s_waitcnt lgkmcnt(3)
	v_mfma_f32_32x32x16_bf16 v[34:49], v[194:197], v[130:133], v[34:49]
	ds_read_b128 v[190:193], v181 offset:49152
	v_exp_f32_e32 v223, v103
	v_add_f32_e32 v164, v222, v164
	v_cvt_pk_bf16_f32 v216, v222, v223
	v_add_f32_e64 v164, v223, v164
	v_exp_f32_e32 v224, v104
	s_waitcnt lgkmcnt(3)
	v_mfma_f32_32x32x16_bf16 v[50:65], v[198:201], v[130:133], v[50:65]
	ds_read_b128 v[194:197], v181 offset:53760
	v_exp_f32_e32 v225, v105
	v_add_f32_e32 v164, v224, v164
	v_cvt_pk_bf16_f32 v217, v224, v225
	v_add_f32_e64 v164, v225, v164
	v_exp_f32_e32 v222, v106
	s_waitcnt lgkmcnt(3)
	v_mfma_f32_32x32x16_bf16 v[34:49], v[182:185], v[134:137], v[34:49]
	ds_read_b128 v[198:201], v181 offset:49184
	v_exp_f32_e32 v223, v107
	v_add_f32_e32 v164, v222, v164
	v_cvt_pk_bf16_f32 v218, v222, v223
	v_add_f32_e64 v164, v223, v164
	v_exp_f32_e32 v224, v108
	s_waitcnt lgkmcnt(3)
	v_mfma_f32_32x32x16_bf16 v[50:65], v[186:189], v[134:137], v[50:65]
	ds_read_b128 v[182:185], v181 offset:53792
	v_exp_f32_e32 v225, v109
	v_add_f32_e32 v164, v224, v164
	v_cvt_pk_bf16_f32 v219, v224, v225
	v_add_f32_e64 v164, v225, v164
	v_exp_f32_e32 v222, v110
	s_waitcnt lgkmcnt(3)
	v_mfma_f32_32x32x16_bf16 v[2:17], v[190:193], v[206:209], v[2:17]
	ds_read_b128 v[186:189], v181 offset:49216
	v_exp_f32_e32 v223, v111
	v_add_f32_e32 v164, v222, v164
	v_cvt_pk_bf16_f32 v220, v222, v223
	v_add_f32_e64 v164, v223, v164
	v_exp_f32_e32 v224, v112
	s_waitcnt lgkmcnt(3)
	v_mfma_f32_32x32x16_bf16 v[18:33], v[194:197], v[206:209], v[18:33]
	ds_read_b128 v[190:193], v181 offset:53824
	v_exp_f32_e32 v225, v113
	v_add_f32_e32 v164, v224, v164
	v_cvt_pk_bf16_f32 v221, v224, v225
	v_add_f32_e64 v164, v225, v164
	s_mov_b32 s13, s20
	s_mov_b32 s20, s19
	s_add_i32 s19, s19, 1
	s_cmp_eq_u32 s19, s9
	s_cselect_b32 s19, 0, s19
	s_nop 0
	s_waitcnt lgkmcnt(3)
	s_waitcnt vmcnt(2)
	v_mfma_f32_32x32x16_bf16 v[2:17], v[198:201], v[210:213], v[2:17]
	ds_read_b128 v[194:197], v181 offset:49248
	v_max3_f32 v224, v34, v35, v36
	v_max3_f32 v225, v50, v51, v52
	v_max3_f32 v224, v224, v37, v38
	v_max3_f32 v225, v225, v53, v54
	ds_write_b128 v172, v[150:153]
	v_lshl_add_u32 v222, s19, 17, v178
	global_load_dwordx4 v[150:153], v222, s[52:53]
	s_waitcnt lgkmcnt(4)
	s_and_b64 vcc, exec, s[2:3]
	v_mfma_f32_32x32x16_bf16 v[18:33], v[182:185], v[210:213], v[18:33]
	ds_read_b128 v[198:201], v181 offset:53856
	v_max3_f32 v224, v224, v39, v40
	v_max3_f32 v225, v225, v55, v56
	v_max3_f32 v224, v224, v41, v42
	v_max3_f32 v225, v225, v57, v58
	s_cbranch_vccz .Lmla_p11_nope
	s_nop 0
	ds_write_b128 v176, v[160:163] offset:128
	v_lshl_add_u32 v222, s19, 12, v179
	global_load_dwordx4 v[160:163], v222, s[62:63]
.Lmla_p11_nope:
	s_waitcnt lgkmcnt(4)
	s_nop 0
	v_mfma_f32_32x32x16_bf16 v[2:17], v[186:189], v[214:217], v[2:17]
	ds_read_b128 v[182:185], v229 offset:13312
	v_max3_f32 v224, v224, v43, v44
	v_max3_f32 v225, v225, v59, v60
	v_max3_f32 v224, v224, v45, v46
	v_max3_f32 v225, v225, v61, v62
	ds_write_b128 v173, v[202:205] offset:35840
	v_lshl_add_u32 v222, s13, 7, v168
	global_load_dwordx4 v[202:205], v222, s[56:57]
	s_waitcnt lgkmcnt(5)
	s_nop 0
	v_mfma_f32_32x32x16_bf16 v[18:33], v[190:193], v[214:217], v[18:33]
	ds_read_b128 v[186:189], v229 offset:19968
	v_max3_f32 v224, v224, v47, v48
	v_max3_f32 v225, v225, v63, v64
	v_max3_f32 v224, v224, v49, v65
	v_max_f32_e64 v224, v224, v225
	s_waitcnt lgkmcnt(5)
	v_mov_b32_e32 v225, v224
	v_mfma_f32_32x32x16_bf16 v[2:17], v[194:197], v[218:221], v[2:17]
	ds_read_b128 v[190:193], v229 offset:13344
	v_add_f32_e32 v1, v1, v164
	s_add_i32 s11, s11, 1
	v_permlane32_swap_b32_e32 v224, v225
	s_cmp_eq_u32 s9, s11
	v_max_f32_e64 v167, v224, v225
	v_cmp_lt_f32_e32 vcc, s66, v167
	s_waitcnt lgkmcnt(4)
	v_mfma_f32_32x32x16_bf16 v[18:33], v[198:201], v[218:221], v[18:33]
	ds_read_b128 v[194:197], v229 offset:20000
	s_waitcnt lgkmcnt(3)
	s_barrier
	s_cbranch_scc1 .Lmla_exit_p11

; template <int VAR>
; __device__ __forceinline__ void attn_phase(LAS unsigned char* lds, const AttnP P, int vcu, int G, int wave_s) {
;     ...
;         for (int t = 0; t < nt; ++t) {
;             const bool hn = (t + 1 < nt);
;     ...
;                 if (ND0 == 6) {
;                     KR1(0); KR1(1); KR1(2); KR1(3); SB();
;                     QK1(0, negm); EX2(pc0, 0, w0.x); KR1(4); SB();
;                     QK1(1, negm); EX2(pc0, 2, w0.y); KR1(5); SB();
;                     QK1(2, pn0); EX2(pc0, 4, w0.z); KR1(6); SB();
;                     QK1(3, pn1); EX2(pc0, 6, w0.w); KR1(7); SB();
;                     QK1(4, pn0); EX2(pc0, 8, w1.x); KR1(8); SB();
;                     QK1(5, pn1); EX2(pc0, 10, w1.y); KR1(9); SB();
;                     QK1(6, pn0); EX2(pc0, 12, w1.z); KR1(10); SB();
;                     QK1(7, pn1); EX2(pc0, 14, w1.w); KR1(11); SB();
;                     QK1(8, pn0); EX2(pc1, 0, w2.x); VR1(0); SB();
;                     QK1(9, pn1); EX2(pc1, 2, w2.y); VR1(1); SB();
;                     QK1(10, pn0); EX2(pc1, 4, w2.z); VR1(2); SB();
;                     QK1(11, pn1); EX2(pc1, 6, w2.w); VR1(3); SB();
;                 } else {
;                     KR1(0); KR1(1); KR1(2); KR1(3); SB();
;                     QK1(0, negm); EX2(pc0, 0, w0.x); EX2(pc0, 2, w0.y); KR1(4); SB();
;                     QK1(1, negm); EX2(pc0, 4, w0.z); EX2(pc0, 6, w0.w); KR1(5); SB();
;                     QK1(2, pn0); EX2(pc0, 8, w1.x); EX2(pc0, 10, w1.y); KR1(6); SB();
;                     QK1(3, pn1); EX2(pc0, 12, w1.z); EX2(pc0, 14, w1.w); KR1(7); SB();
;                     QK1(4, pn0); EX2(pc1, 0, w2.x); VR1(0); SB();
;                     QK1(5, pn1); EX2(pc1, 2, w2.y); VR1(1); SB();
;                     QK1(6, pn0); EX2(pc1, 4, w2.z); VR1(2); SB();
;                     QK1(7, pn1); EX2(pc1, 6, w2.w); VR1(3); SB();
;                 }
;                 PV1(0, w0); EX2(pc1, 8, w3.x); VR1(4); SB();
;                 PV1(1, w0); EX2(pc1, 10, w3.y); VR1(5); SB();
;                 PV1(2, w1); EX2(pc1, 12, w3.z); VR1(6); SB();
;                 PV1(3, w1); EX2(pc1, 14, w3.w); VR1(7); SB();
;                 lrun += sacc;
;                 PV1(4, w2); MASK_TILE(pn0, pn1, t + 1); SB();
;                 PV1(5, w2); SB();
;                 PV1(6, w3); SB();
;                 PV1(7, w3); rmn = rowmax32(pn0, pn1); if (!USE_NEGM) rmn -= mref; SB();
.Lmla_p12_go:
	v_exp_f32_e32 v222, v34
	v_exp_f32_e32 v223, v35
	v_add_f32_e32 v164, 0, v222
	v_add_f32_e32 v164, v223, v164
	v_cvt_pk_bf16_f32 v206, v222, v223
	v_exp_f32_e32 v224, v36
	v_exp_f32_e32 v225, v37
	v_add_f32_e32 v164, v224, v164
	v_add_f32_e32 v164, v225, v164
	v_cvt_pk_bf16_f32 v207, v224, v225
	v_exp_f32_e32 v222, v38
	s_waitcnt lgkmcnt(3)
	v_mfma_f32_32x32x16_bf16 v[82:97], v[182:185], v[114:117], v[66:81]
	ds_read_b128 v[198:201], v229 offset:13376
	v_exp_f32_e32 v223, v39
	v_add_f32_e32 v164, v222, v164
	v_cvt_pk_bf16_f32 v208, v222, v223
	v_add_f32_e64 v164, v223, v164
	v_exp_f32_e32 v224, v40
	s_waitcnt lgkmcnt(3)
	v_mfma_f32_32x32x16_bf16 v[98:113], v[186:189], v[114:117], v[66:81]
	ds_read_b128 v[182:185], v229 offset:20032
	v_exp_f32_e32 v225, v41
	v_add_f32_e32 v164, v224, v164
	v_cvt_pk_bf16_f32 v209, v224, v225
	v_add_f32_e64 v164, v225, v164
	v_exp_f32_e32 v222, v42
	s_waitcnt lgkmcnt(3)
	v_mfma_f32_32x32x16_bf16 v[82:97], v[190:193], v[118:121], v[82:97]
	ds_read_b128 v[186:189], v229 offset:13408
	v_exp_f32_e32 v223, v43
	v_add_f32_e32 v164, v222, v164
	v_cvt_pk_bf16_f32 v210, v222, v223
	v_add_f32_e64 v164, v223, v164
	v_exp_f32_e32 v224, v44
	s_waitcnt lgkmcnt(3)
	v_mfma_f32_32x32x16_bf16 v[98:113], v[194:197], v[118:121], v[98:113]
	ds_read_b128 v[190:193], v229 offset:20064
	v_exp_f32_e32 v225, v45
	v_add_f32_e32 v164, v224, v164
	v_cvt_pk_bf16_f32 v211, v224, v225
	v_add_f32_e64 v164, v225, v164
	v_exp_f32_e32 v222, v46
	s_waitcnt lgkmcnt(3)
	v_mfma_f32_32x32x16_bf16 v[82:97], v[198:201], v[122:125], v[82:97]
	ds_read_b128 v[194:197], v229 offset:13440
	v_exp_f32_e32 v223, v47
	v_add_f32_e32 v164, v222, v164
	v_cvt_pk_bf16_f32 v212, v222, v223
	v_add_f32_e64 v164, v223, v164
	v_exp_f32_e32 v224, v48
	s_waitcnt lgkmcnt(3)
	v_mfma_f32_32x32x16_bf16 v[98:113], v[182:185], v[122:125], v[98:113]
	ds_read_b128 v[198:201], v229 offset:20096
	v_exp_f32_e32 v225, v49
	v_add_f32_e32 v164, v224, v164
	v_cvt_pk_bf16_f32 v213, v224, v225
	v_add_f32_e64 v164, v225, v164
	v_exp_f32_e32 v222, v50
	s_waitcnt lgkmcnt(3)
	v_mfma_f32_32x32x16_bf16 v[82:97], v[186:189], v[126:129], v[82:97]
	ds_read_b128 v[182:185], v229 offset:13472
	v_exp_f32_e32 v223, v51
	v_add_f32_e32 v164, v222, v164
	v_cvt_pk_bf16_f32 v214, v222, v223
	v_add_f32_e64 v164, v223, v164
	v_exp_f32_e32 v224, v52
	s_waitcnt lgkmcnt(3)
	v_mfma_f32_32x32x16_bf16 v[98:113], v[190:193], v[126:129], v[98:113]
	ds_read_b128 v[186:189], v229 offset:20128
	v_exp_f32_e32 v225, v53
	v_add_f32_e32 v164, v224, v164
	v_cvt_pk_bf16_f32 v215, v224, v225
	v_add_f32_e64 v164, v225, v164
	v_exp_f32_e32 v222, v54
	s_waitcnt lgkmcnt(3)
	v_mfma_f32_32x32x16_bf16 v[82:97], v[194:197], v[130:133], v[82:97]
	ds_read_b128 v[190:193], v228 offset:13312
	v_exp_f32_e32 v223, v55
	v_add_f32_e32 v164, v222, v164
	v_cvt_pk_bf16_f32 v216, v222, v223
	v_add_f32_e64 v164, v223, v164
	v_exp_f32_e32 v224, v56
	s_waitcnt lgkmcnt(3)
	v_mfma_f32_32x32x16_bf16 v[98:113], v[198:201], v[130:133], v[98:113]
	ds_read_b128 v[194:197], v228 offset:17920
	v_exp_f32_e32 v225, v57
	v_add_f32_e32 v164, v224, v164
	v_cvt_pk_bf16_f32 v217, v224, v225
	v_add_f32_e64 v164, v225, v164
	v_exp_f32_e32 v222, v58
	s_waitcnt lgkmcnt(3)
	v_mfma_f32_32x32x16_bf16 v[82:97], v[182:185], v[134:137], v[82:97]
	ds_read_b128 v[198:201], v228 offset:13344
	v_exp_f32_e32 v223, v59
	v_add_f32_e32 v164, v222, v164
	v_cvt_pk_bf16_f32 v218, v222, v223
	v_add_f32_e64 v164, v223, v164
	v_exp_f32_e32 v224, v60
	s_waitcnt lgkmcnt(3)
	v_mfma_f32_32x32x16_bf16 v[98:113], v[186:189], v[134:137], v[98:113]
	ds_read_b128 v[182:185], v228 offset:17952
	v_exp_f32_e32 v225, v61
	v_add_f32_e32 v164, v224, v164
	v_cvt_pk_bf16_f32 v219, v224, v225
	v_add_f32_e64 v164, v225, v164
	v_exp_f32_e32 v222, v62
	s_waitcnt lgkmcnt(3)
	v_mfma_f32_32x32x16_bf16 v[2:17], v[190:193], v[206:209], v[2:17]
	ds_read_b128 v[186:189], v228 offset:13376
	v_exp_f32_e32 v223, v63
	v_add_f32_e32 v164, v222, v164
	v_cvt_pk_bf16_f32 v220, v222, v223
	v_add_f32_e64 v164, v223, v164
	v_exp_f32_e32 v224, v64
	s_waitcnt lgkmcnt(3)
	v_mfma_f32_32x32x16_bf16 v[18:33], v[194:197], v[206:209], v[18:33]
	ds_read_b128 v[190:193], v228 offset:17984
	v_exp_f32_e32 v225, v65
	v_add_f32_e32 v164, v224, v164
	v_cvt_pk_bf16_f32 v221, v224, v225
	v_add_f32_e64 v164, v225, v164
	s_mov_b32 s13, s20
	s_mov_b32 s20, s19
	s_add_i32 s19, s19, 1
	s_cmp_eq_u32 s19, s9
	s_cselect_b32 s19, 0, s19
	s_nop 0
	s_waitcnt lgkmcnt(3)
	s_waitcnt vmcnt(2)
	v_mfma_f32_32x32x16_bf16 v[2:17], v[198:201], v[210:213], v[2:17]
	ds_read_b128 v[194:197], v228 offset:13408
	v_max3_f32 v224, v82, v83, v84
	v_max3_f32 v225, v98, v99, v100
	v_max3_f32 v224, v224, v85, v86
	v_max3_f32 v225, v225, v101, v102
	ds_write_b128 v172, v[146:149] offset:22528
	v_lshl_add_u32 v222, s19, 17, v178
	global_load_dwordx4 v[146:149], v222, s[52:53]
	s_waitcnt lgkmcnt(4)
	s_and_b64 vcc, exec, s[2:3]
	v_mfma_f32_32x32x16_bf16 v[18:33], v[182:185], v[210:213], v[18:33]
	ds_read_b128 v[198:201], v228 offset:18016
	v_max3_f32 v224, v224, v87, v88
	v_max3_f32 v225, v225, v103, v104
	v_max3_f32 v224, v224, v89, v90
	v_max3_f32 v225, v225, v105, v106
	s_cbranch_vccz .Lmla_p12_nope
	s_nop 0
	ds_write_b128 v176, v[138:141] offset:22656
	v_lshl_add_u32 v222, s19, 12, v179
	global_load_dwordx4 v[138:141], v222, s[62:63]
.Lmla_p12_nope:
	s_waitcnt lgkmcnt(4)
	s_nop 0
	v_mfma_f32_32x32x16_bf16 v[2:17], v[186:189], v[214:217], v[2:17]
	ds_read_b128 v[182:185], v229 offset:26624
	v_max3_f32 v224, v224, v91, v92
	v_max3_f32 v225, v225, v107, v108
	v_max3_f32 v224, v224, v93, v94
	v_max3_f32 v225, v225, v109, v110
	v_add_u32_e32 v222, 0xb000, v173
	ds_write_b128 v222, v[142:145] offset:39936
	v_lshl_add_u32 v222, s13, 7, v168
	global_load_dwordx4 v[142:145], v222, s[56:57]
	s_waitcnt lgkmcnt(5)
	s_nop 0
	v_mfma_f32_32x32x16_bf16 v[18:33], v[190:193], v[214:217], v[18:33]
	ds_read_b128 v[186:189], v229 offset:33280
	v_max3_f32 v224, v224, v95, v96
	v_max3_f32 v225, v225, v111, v112
	v_max3_f32 v224, v224, v97, v113
	v_max_f32_e64 v224, v224, v225
	s_waitcnt lgkmcnt(5)
	v_mov_b32_e32 v225, v224
	v_mfma_f32_32x32x16_bf16 v[2:17], v[194:197], v[218:221], v[2:17]
	ds_read_b128 v[190:193], v229 offset:26656
	v_add_f32_e32 v1, v1, v164
	s_add_i32 s11, s11, 1
	v_permlane32_swap_b32_e32 v224, v225
	s_cmp_eq_u32 s9, s11
	v_max_f32_e64 v167, v224, v225
	v_cmp_lt_f32_e32 vcc, s66, v167
	s_waitcnt lgkmcnt(4)
	v_mfma_f32_32x32x16_bf16 v[18:33], v[198:201], v[218:221], v[18:33]
	ds_read_b128 v[194:197], v229 offset:33312
	s_cbranch_scc1 .Lmla_exit_p12

; template <int VAR>
; __device__ __forceinline__ void attn_phase(LAS unsigned char* lds, const AttnP P, int vcu, int G, int wave_s) {
;     ...
;         for (int t = 0; t < nt; ++t) {
;             const bool hn = (t + 1 < nt);
;     ...
;                 if (ND0 == 6) {
;                     KR1(0); KR1(1); KR1(2); KR1(3); SB();
;                     QK1(0, negm); EX2(pc0, 0, w0.x); KR1(4); SB();
;                     QK1(1, negm); EX2(pc0, 2, w0.y); KR1(5); SB();
;                     QK1(2, pn0); EX2(pc0, 4, w0.z); KR1(6); SB();
;                     QK1(3, pn1); EX2(pc0, 6, w0.w); KR1(7); SB();
;                     QK1(4, pn0); EX2(pc0, 8, w1.x); KR1(8); SB();
;                     QK1(5, pn1); EX2(pc0, 10, w1.y); KR1(9); SB();
;                     QK1(6, pn0); EX2(pc0, 12, w1.z); KR1(10); SB();
;                     QK1(7, pn1); EX2(pc0, 14, w1.w); KR1(11); SB();
;                     QK1(8, pn0); EX2(pc1, 0, w2.x); VR1(0); SB();
;                     QK1(9, pn1); EX2(pc1, 2, w2.y); VR1(1); SB();
;                     QK1(10, pn0); EX2(pc1, 4, w2.z); VR1(2); SB();
;                     QK1(11, pn1); EX2(pc1, 6, w2.w); VR1(3); SB();
;                 } else {
;                     KR1(0); KR1(1); KR1(2); KR1(3); SB();
;                     QK1(0, negm); EX2(pc0, 0, w0.x); EX2(pc0, 2, w0.y); KR1(4); SB();
;                     QK1(1, negm); EX2(pc0, 4, w0.z); EX2(pc0, 6, w0.w); KR1(5); SB();
;                     QK1(2, pn0); EX2(pc0, 8, w1.x); EX2(pc0, 10, w1.y); KR1(6); SB();
;                     QK1(3, pn1); EX2(pc0, 12, w1.z); EX2(pc0, 14, w1.w); KR1(7); SB();
;                     QK1(4, pn0); EX2(pc1, 0, w2.x); VR1(0); SB();
;                     QK1(5, pn1); EX2(pc1, 2, w2.y); VR1(1); SB();
;                     QK1(6, pn0); EX2(pc1, 4, w2.z); VR1(2); SB();
;                     QK1(7, pn1); EX2(pc1, 6, w2.w); VR1(3); SB();
;                 }
;                 PV1(0, w0); EX2(pc1, 8, w3.x); VR1(4); SB();
;                 PV1(1, w0); EX2(pc1, 10, w3.y); VR1(5); SB();
;                 PV1(2, w1); EX2(pc1, 12, w3.z); VR1(6); SB();
;                 PV1(3, w1); EX2(pc1, 14, w3.w); VR1(7); SB();
;                 lrun += sacc;
;                 PV1(4, w2); MASK_TILE(pn0, pn1, t + 1); SB();
;                 PV1(5, w2); SB();
;                 PV1(6, w3); SB();
;                 PV1(7, w3); rmn = rowmax32(pn0, pn1); if (!USE_NEGM) rmn -= mref; SB();
.Lmla_p13_go:
	v_exp_f32_e32 v222, v82
	v_exp_f32_e32 v223, v83
	v_add_f32_e32 v164, 0, v222
	v_add_f32_e32 v164, v223, v164
	v_cvt_pk_bf16_f32 v206, v222, v223
	v_exp_f32_e32 v224, v84
	v_exp_f32_e32 v225, v85
	v_add_f32_e32 v164, v224, v164
	v_add_f32_e32 v164, v225, v164
	v_cvt_pk_bf16_f32 v207, v224, v225
	v_exp_f32_e32 v222, v86
	s_waitcnt lgkmcnt(4)
	v_mfma_f32_32x32x16_bf16 v[34:49], v[182:185], v[114:117], v[66:81]
	ds_read_b128 v[198:201], v229 offset:26688
	v_exp_f32_e32 v223, v87
	v_add_f32_e32 v164, v222, v164
	v_cvt_pk_bf16_f32 v208, v222, v223
	v_add_f32_e64 v164, v223, v164
	v_exp_f32_e32 v224, v88
	s_waitcnt lgkmcnt(3)
	v_mfma_f32_32x32x16_bf16 v[50:65], v[186:189], v[114:117], v[66:81]
	ds_read_b128 v[182:185], v229 offset:33344
	v_exp_f32_e32 v225, v89
	v_add_f32_e32 v164, v224, v164
	v_cvt_pk_bf16_f32 v209, v224, v225
	v_add_f32_e64 v164, v225, v164
	v_exp_f32_e32 v222, v90
	s_waitcnt lgkmcnt(3)
	v_mfma_f32_32x32x16_bf16 v[34:49], v[190:193], v[118:121], v[34:49]
	ds_read_b128 v[186:189], v229 offset:26720
	v_exp_f32_e32 v223, v91
	v_add_f32_e32 v164, v222, v164
	v_cvt_pk_bf16_f32 v210, v222, v223
	v_add_f32_e64 v164, v223, v164
	v_exp_f32_e32 v224, v92
	s_waitcnt lgkmcnt(3)
	v_mfma_f32_32x32x16_bf16 v[50:65], v[194:197], v[118:121], v[50:65]
	ds_read_b128 v[190:193], v229 offset:33376
	v_exp_f32_e32 v225, v93
	v_add_f32_e32 v164, v224, v164
	v_cvt_pk_bf16_f32 v211, v224, v225
	v_add_f32_e64 v164, v225, v164
	v_exp_f32_e32 v222, v94
	s_waitcnt lgkmcnt(3)
	v_mfma_f32_32x32x16_bf16 v[34:49], v[198:201], v[122:125], v[34:49]
	ds_read_b128 v[194:197], v229 offset:26752
	v_exp_f32_e32 v223, v95
	v_add_f32_e32 v164, v222, v164
	v_cvt_pk_bf16_f32 v212, v222, v223
	v_add_f32_e64 v164, v223, v164
	v_exp_f32_e32 v224, v96
	s_waitcnt lgkmcnt(3)
	v_mfma_f32_32x32x16_bf16 v[50:65], v[182:185], v[122:125], v[50:65]
	ds_read_b128 v[198:201], v229 offset:33408
	v_exp_f32_e32 v225, v97
	v_add_f32_e32 v164, v224, v164
	v_cvt_pk_bf16_f32 v213, v224, v225
	v_add_f32_e64 v164, v225, v164
	v_exp_f32_e32 v222, v98
	s_waitcnt lgkmcnt(3)
	v_mfma_f32_32x32x16_bf16 v[34:49], v[186:189], v[126:129], v[34:49]
	ds_read_b128 v[182:185], v229 offset:26784
	v_exp_f32_e32 v223, v99
	v_add_f32_e32 v164, v222, v164
	v_cvt_pk_bf16_f32 v214, v222, v223
	v_add_f32_e64 v164, v223, v164
	v_exp_f32_e32 v224, v100
	s_waitcnt lgkmcnt(3)
	v_mfma_f32_32x32x16_bf16 v[50:65], v[190:193], v[126:129], v[50:65]
	ds_read_b128 v[186:189], v229 offset:33440
	v_exp_f32_e32 v225, v101
	v_add_f32_e32 v164, v224, v164
	v_cvt_pk_bf16_f32 v215, v224, v225
	v_add_f32_e64 v164, v225, v164
	v_exp_f32_e32 v222, v102
	s_waitcnt lgkmcnt(3)
	v_mfma_f32_32x32x16_bf16 v[34:49], v[194:197], v[130:133], v[34:49]
	ds_read_b128 v[190:193], v228 offset:35840
	v_exp_f32_e32 v223, v103
	v_add_f32_e32 v164, v222, v164
	v_cvt_pk_bf16_f32 v216, v222, v223
	v_add_f32_e64 v164, v223, v164
	v_exp_f32_e32 v224, v104
	s_waitcnt lgkmcnt(3)
	v_mfma_f32_32x32x16_bf16 v[50:65], v[198:201], v[130:133], v[50:65]
	ds_read_b128 v[194:197], v228 offset:40448
	v_exp_f32_e32 v225, v105
	v_add_f32_e32 v164, v224, v164
	v_cvt_pk_bf16_f32 v217, v224, v225
	v_add_f32_e64 v164, v225, v164
	v_exp_f32_e32 v222, v106
	s_waitcnt lgkmcnt(3)
	v_mfma_f32_32x32x16_bf16 v[34:49], v[182:185], v[134:137], v[34:49]
	ds_read_b128 v[198:201], v228 offset:35872
	v_exp_f32_e32 v223, v107
	v_add_f32_e32 v164, v222, v164
	v_cvt_pk_bf16_f32 v218, v222, v223
	v_add_f32_e64 v164, v223, v164
	v_exp_f32_e32 v224, v108
	s_waitcnt lgkmcnt(3)
	v_mfma_f32_32x32x16_bf16 v[50:65], v[186:189], v[134:137], v[50:65]
	ds_read_b128 v[182:185], v228 offset:40480
	v_exp_f32_e32 v225, v109
	v_add_f32_e32 v164, v224, v164
	v_cvt_pk_bf16_f32 v219, v224, v225
	v_add_f32_e64 v164, v225, v164
	v_exp_f32_e32 v222, v110
	s_waitcnt lgkmcnt(3)
	v_mfma_f32_32x32x16_bf16 v[2:17], v[190:193], v[206:209], v[2:17]
	ds_read_b128 v[186:189], v228 offset:35904
	v_exp_f32_e32 v223, v111
	v_add_f32_e32 v164, v222, v164
	v_cvt_pk_bf16_f32 v220, v222, v223
	v_add_f32_e64 v164, v223, v164
	v_exp_f32_e32 v224, v112
	s_waitcnt lgkmcnt(3)
	v_mfma_f32_32x32x16_bf16 v[18:33], v[194:197], v[206:209], v[18:33]
	ds_read_b128 v[190:193], v228 offset:40512
	v_exp_f32_e32 v225, v113
	v_add_f32_e32 v164, v224, v164
	v_cvt_pk_bf16_f32 v221, v224, v225
	v_add_f32_e64 v164, v225, v164
	s_mov_b32 s13, s20
	s_mov_b32 s20, s19
	s_add_i32 s19, s19, 1
	s_cmp_eq_u32 s19, s9
	s_cselect_b32 s19, 0, s19
	s_nop 0
	s_waitcnt lgkmcnt(3)
	s_waitcnt vmcnt(2)
	v_mfma_f32_32x32x16_bf16 v[2:17], v[198:201], v[210:213], v[2:17]
	ds_read_b128 v[194:197], v228 offset:35936
	v_max3_f32 v224, v34, v35, v36
	v_max3_f32 v225, v50, v51, v52
	v_max3_f32 v224, v224, v37, v38
	v_max3_f32 v225, v225, v53, v54
	ds_write_b128 v172, v[150:153] offset:45056
	v_lshl_add_u32 v222, s19, 17, v178
	global_load_dwordx4 v[150:153], v222, s[52:53]
	s_waitcnt lgkmcnt(4)
	s_and_b64 vcc, exec, s[2:3]
	v_mfma_f32_32x32x16_bf16 v[18:33], v[182:185], v[210:213], v[18:33]
	ds_read_b128 v[198:201], v228 offset:40544
	v_max3_f32 v224, v224, v39, v40
	v_max3_f32 v225, v225, v55, v56
	v_max3_f32 v224, v224, v41, v42
	v_max3_f32 v225, v225, v57, v58
	s_cbranch_vccz .Lmla_p13_nope
	s_nop 0
	ds_write_b128 v176, v[160:163] offset:45184
	v_lshl_add_u32 v222, s19, 12, v179
	global_load_dwordx4 v[160:163], v222, s[62:63]
.Lmla_p13_nope:
	s_waitcnt lgkmcnt(4)
	s_nop 0
	v_mfma_f32_32x32x16_bf16 v[2:17], v[186:189], v[214:217], v[2:17]
	ds_read_b128 v[182:185], v174
	v_max3_f32 v224, v224, v43, v44
	v_max3_f32 v225, v225, v59, v60
	v_max3_f32 v224, v224, v45, v46
	v_max3_f32 v225, v225, v61, v62
	v_add_u32_e32 v222, 0xb000, v173
	ds_write_b128 v222, v[202:205] offset:49152
	v_lshl_add_u32 v222, s13, 7, v168
	global_load_dwordx4 v[202:205], v222, s[56:57]
	s_waitcnt lgkmcnt(5)
	s_nop 0
	v_mfma_f32_32x32x16_bf16 v[18:33], v[190:193], v[214:217], v[18:33]
	ds_read_b128 v[186:189], v174 offset:6656
	v_max3_f32 v224, v224, v47, v48
	v_max3_f32 v225, v225, v63, v64
	v_max3_f32 v224, v224, v49, v65
	v_max_f32_e64 v224, v224, v225
	s_waitcnt lgkmcnt(5)
	v_mov_b32_e32 v225, v224
	v_mfma_f32_32x32x16_bf16 v[2:17], v[194:197], v[218:221], v[2:17]
	ds_read_b128 v[190:193], v174 offset:32
	v_add_f32_e32 v1, v1, v164
	s_add_i32 s11, s11, 1
	v_permlane32_swap_b32_e32 v224, v225
	s_cmp_eq_u32 s9, s11
	v_max_f32_e64 v167, v224, v225
	v_cmp_lt_f32_e32 vcc, s66, v167
	s_waitcnt lgkmcnt(4)
	v_mfma_f32_32x32x16_bf16 v[18:33], v[198:201], v[218:221], v[18:33]
	ds_read_b128 v[194:197], v174 offset:6688
	s_waitcnt lgkmcnt(3)
	s_barrier
	s_cbranch_scc1 .Lmla_exit_p13

; template <int VAR>
; __device__ __forceinline__ void attn_phase(LAS unsigned char* lds, const AttnP P, int vcu, int G, int wave_s) {
;     ...
;         for (int t = 0; t < nt; ++t) {
;             const bool hn = (t + 1 < nt);
;     ...
;                 if (ND0 == 6) {
;                     KR1(0); KR1(1); KR1(2); KR1(3); SB();
;                     QK1(0, negm); EX2(pc0, 0, w0.x); KR1(4); SB();
;                     QK1(1, negm); EX2(pc0, 2, w0.y); KR1(5); SB();
;                     QK1(2, pn0); EX2(pc0, 4, w0.z); KR1(6); SB();
;                     QK1(3, pn1); EX2(pc0, 6, w0.w); KR1(7); SB();
;                     QK1(4, pn0); EX2(pc0, 8, w1.x); KR1(8); SB();
;                     QK1(5, pn1); EX2(pc0, 10, w1.y); KR1(9); SB();
;                     QK1(6, pn0); EX2(pc0, 12, w1.z); KR1(10); SB();
;                     QK1(7, pn1); EX2(pc0, 14, w1.w); KR1(11); SB();
;                     QK1(8, pn0); EX2(pc1, 0, w2.x); VR1(0); SB();
;                     QK1(9, pn1); EX2(pc1, 2, w2.y); VR1(1); SB();
;                     QK1(10, pn0); EX2(pc1, 4, w2.z); VR1(2); SB();
;                     QK1(11, pn1); EX2(pc1, 6, w2.w); VR1(3); SB();
;                 } else {
;                     KR1(0); KR1(1); KR1(2); KR1(3); SB();
;                     QK1(0, negm); EX2(pc0, 0, w0.x); EX2(pc0, 2, w0.y); KR1(4); SB();
;                     QK1(1, negm); EX2(pc0, 4, w0.z); EX2(pc0, 6, w0.w); KR1(5); SB();
;                     QK1(2, pn0); EX2(pc0, 8, w1.x); EX2(pc0, 10, w1.y); KR1(6); SB();
;                     QK1(3, pn1); EX2(pc0, 12, w1.z); EX2(pc0, 14, w1.w); KR1(7); SB();
;                     QK1(4, pn0); EX2(pc1, 0, w2.x); VR1(0); SB();
;                     QK1(5, pn1); EX2(pc1, 2, w2.y); VR1(1); SB();
;                     QK1(6, pn0); EX2(pc1, 4, w2.z); VR1(2); SB();
;                     QK1(7, pn1); EX2(pc1, 6, w2.w); VR1(3); SB();
;                 }
;                 PV1(0, w0); EX2(pc1, 8, w3.x); VR1(4); SB();
;                 PV1(1, w0); EX2(pc1, 10, w3.y); VR1(5); SB();
;                 PV1(2, w1); EX2(pc1, 12, w3.z); VR1(6); SB();
;                 PV1(3, w1); EX2(pc1, 14, w3.w); VR1(7); SB();
;                 lrun += sacc;
;                 PV1(4, w2); MASK_TILE(pn0, pn1, t + 1); SB();
;                 PV1(5, w2); SB();
;                 PV1(6, w3); SB();
;                 PV1(7, w3); rmn = rowmax32(pn0, pn1); if (!USE_NEGM) rmn -= mref; SB();
.Lmla_p14_go:
	v_exp_f32_e32 v222, v34
	v_exp_f32_e32 v223, v35
	v_add_f32_e32 v164, 0, v222
	v_add_f32_e32 v164, v223, v164
	v_cvt_pk_bf16_f32 v206, v222, v223
	v_exp_f32_e32 v224, v36
	v_exp_f32_e32 v225, v37
	v_add_f32_e32 v164, v224, v164
	v_add_f32_e32 v164, v225, v164
	v_cvt_pk_bf16_f32 v207, v224, v225
	v_exp_f32_e32 v222, v38
	s_waitcnt lgkmcnt(3)
	v_mfma_f32_32x32x16_bf16 v[82:97], v[182:185], v[114:117], v[66:81]
	ds_read_b128 v[198:201], v174 offset:64
	v_exp_f32_e32 v223, v39
	v_add_f32_e32 v164, v222, v164
	v_cvt_pk_bf16_f32 v208, v222, v223
	v_add_f32_e64 v164, v223, v164
	v_exp_f32_e32 v224, v40
	s_waitcnt lgkmcnt(3)
	v_mfma_f32_32x32x16_bf16 v[98:113], v[186:189], v[114:117], v[66:81]
	ds_read_b128 v[182:185], v174 offset:6720
	v_exp_f32_e32 v225, v41
	v_add_f32_e32 v164, v224, v164
	v_cvt_pk_bf16_f32 v209, v224, v225
	v_add_f32_e64 v164, v225, v164
	v_exp_f32_e32 v222, v42
	s_waitcnt lgkmcnt(3)
	v_mfma_f32_32x32x16_bf16 v[82:97], v[190:193], v[118:121], v[82:97]
	ds_read_b128 v[186:189], v174 offset:96
	v_exp_f32_e32 v223, v43
	v_add_f32_e32 v164, v222, v164
	v_cvt_pk_bf16_f32 v210, v222, v223
	v_add_f32_e64 v164, v223, v164
	v_exp_f32_e32 v224, v44
	s_waitcnt lgkmcnt(3)
	v_mfma_f32_32x32x16_bf16 v[98:113], v[194:197], v[118:121], v[98:113]
	ds_read_b128 v[190:193], v174 offset:6752
	v_exp_f32_e32 v225, v45
	v_add_f32_e32 v164, v224, v164
	v_cvt_pk_bf16_f32 v211, v224, v225
	v_add_f32_e64 v164, v225, v164
	v_exp_f32_e32 v222, v46
	s_waitcnt lgkmcnt(3)
	v_mfma_f32_32x32x16_bf16 v[82:97], v[198:201], v[122:125], v[82:97]
	ds_read_b128 v[194:197], v174 offset:128
	v_exp_f32_e32 v223, v47
	v_add_f32_e32 v164, v222, v164
	v_cvt_pk_bf16_f32 v212, v222, v223
	v_add_f32_e64 v164, v223, v164
	v_exp_f32_e32 v224, v48
	s_waitcnt lgkmcnt(3)
	v_mfma_f32_32x32x16_bf16 v[98:113], v[182:185], v[122:125], v[98:113]
	ds_read_b128 v[198:201], v174 offset:6784
	v_exp_f32_e32 v225, v49
	v_add_f32_e32 v164, v224, v164
	v_cvt_pk_bf16_f32 v213, v224, v225
	v_add_f32_e64 v164, v225, v164
	v_exp_f32_e32 v222, v50
	s_waitcnt lgkmcnt(3)
	v_mfma_f32_32x32x16_bf16 v[82:97], v[186:189], v[126:129], v[82:97]
	ds_read_b128 v[182:185], v174 offset:160
	v_exp_f32_e32 v223, v51
	v_add_f32_e32 v164, v222, v164
	v_cvt_pk_bf16_f32 v214, v222, v223
	v_add_f32_e64 v164, v223, v164
	v_exp_f32_e32 v224, v52
	s_waitcnt lgkmcnt(3)
	v_mfma_f32_32x32x16_bf16 v[98:113], v[190:193], v[126:129], v[98:113]
	ds_read_b128 v[186:189], v174 offset:6816
	v_exp_f32_e32 v225, v53
	v_add_f32_e32 v164, v224, v164
	v_cvt_pk_bf16_f32 v215, v224, v225
	v_add_f32_e64 v164, v225, v164
	v_exp_f32_e32 v222, v54
	s_waitcnt lgkmcnt(3)
	v_mfma_f32_32x32x16_bf16 v[82:97], v[194:197], v[130:133], v[82:97]
	ds_read_b128 v[190:193], v181 offset:39936
	v_exp_f32_e32 v223, v55
	v_add_f32_e32 v164, v222, v164
	v_cvt_pk_bf16_f32 v216, v222, v223
	v_add_f32_e64 v164, v223, v164
	v_exp_f32_e32 v224, v56
	s_waitcnt lgkmcnt(3)
	v_mfma_f32_32x32x16_bf16 v[98:113], v[198:201], v[130:133], v[98:113]
	ds_read_b128 v[194:197], v181 offset:44544
	v_exp_f32_e32 v225, v57
	v_add_f32_e32 v164, v224, v164
	v_cvt_pk_bf16_f32 v217, v224, v225
	v_add_f32_e64 v164, v225, v164
	v_exp_f32_e32 v222, v58
	s_waitcnt lgkmcnt(3)
	v_mfma_f32_32x32x16_bf16 v[82:97], v[182:185], v[134:137], v[82:97]
	ds_read_b128 v[198:201], v181 offset:39968
	v_exp_f32_e32 v223, v59
	v_add_f32_e32 v164, v222, v164
	v_cvt_pk_bf16_f32 v218, v222, v223
	v_add_f32_e64 v164, v223, v164
	v_exp_f32_e32 v224, v60
	s_waitcnt lgkmcnt(3)
	v_mfma_f32_32x32x16_bf16 v[98:113], v[186:189], v[134:137], v[98:113]
	ds_read_b128 v[182:185], v181 offset:44576
	v_exp_f32_e32 v225, v61
	v_add_f32_e32 v164, v224, v164
	v_cvt_pk_bf16_f32 v219, v224, v225
	v_add_f32_e64 v164, v225, v164
	v_exp_f32_e32 v222, v62
	s_waitcnt lgkmcnt(3)
	v_mfma_f32_32x32x16_bf16 v[2:17], v[190:193], v[206:209], v[2:17]
	ds_read_b128 v[186:189], v181 offset:40000
	v_exp_f32_e32 v223, v63
	v_add_f32_e32 v164, v222, v164
	v_cvt_pk_bf16_f32 v220, v222, v223
	v_add_f32_e64 v164, v223, v164
	v_exp_f32_e32 v224, v64
	s_waitcnt lgkmcnt(3)
	v_mfma_f32_32x32x16_bf16 v[18:33], v[194:197], v[206:209], v[18:33]
	ds_read_b128 v[190:193], v181 offset:44608
	v_exp_f32_e32 v225, v65
	v_add_f32_e32 v164, v224, v164
	v_cvt_pk_bf16_f32 v221, v224, v225
	v_add_f32_e64 v164, v225, v164
	s_mov_b32 s13, s20
	s_mov_b32 s20, s19
	s_add_i32 s19, s19, 1
	s_cmp_eq_u32 s19, s9
	s_cselect_b32 s19, 0, s19
	s_nop 0
	s_waitcnt lgkmcnt(3)
	s_waitcnt vmcnt(2)
	v_mfma_f32_32x32x16_bf16 v[2:17], v[198:201], v[210:213], v[2:17]
	ds_read_b128 v[194:197], v181 offset:40032
	v_max3_f32 v224, v82, v83, v84
	v_max3_f32 v225, v98, v99, v100
	v_max3_f32 v224, v224, v85, v86
	v_max3_f32 v225, v225, v101, v102
	ds_write_b128 v172, v[146:149] offset:58368
	v_lshl_add_u32 v222, s19, 17, v178
	global_load_dwordx4 v[146:149], v222, s[52:53]
	s_waitcnt lgkmcnt(4)
	s_and_b64 vcc, exec, s[2:3]
	v_mfma_f32_32x32x16_bf16 v[18:33], v[182:185], v[210:213], v[18:33]
	ds_read_b128 v[198:201], v181 offset:44640
	v_max3_f32 v224, v224, v87, v88
	v_max3_f32 v225, v225, v103, v104
	v_max3_f32 v224, v224, v89, v90
	v_max3_f32 v225, v225, v105, v106
	s_cbranch_vccz .Lmla_p14_nope
	s_nop 0
	ds_write_b128 v176, v[138:141] offset:58496
	v_lshl_add_u32 v222, s19, 12, v179
	global_load_dwordx4 v[138:141], v222, s[62:63]
.Lmla_p14_nope:
	s_waitcnt lgkmcnt(4)
	s_nop 0
	v_mfma_f32_32x32x16_bf16 v[2:17], v[186:189], v[214:217], v[2:17]
	ds_read_b128 v[182:185], v174 offset:22528
	v_max3_f32 v224, v224, v91, v92
	v_max3_f32 v225, v225, v107, v108
	v_max3_f32 v224, v224, v93, v94
	v_max3_f32 v225, v225, v109, v110
	ds_write_b128 v173, v[142:145] offset:13312
	v_lshl_add_u32 v222, s13, 7, v168
	global_load_dwordx4 v[142:145], v222, s[56:57]
	s_waitcnt lgkmcnt(5)
	s_nop 0
	v_mfma_f32_32x32x16_bf16 v[18:33], v[190:193], v[214:217], v[18:33]
	ds_read_b128 v[186:189], v174 offset:29184
	v_max3_f32 v224, v224, v95, v96
	v_max3_f32 v225, v225, v111, v112
	v_max3_f32 v224, v224, v97, v113
	v_max_f32_e64 v224, v224, v225
	s_waitcnt lgkmcnt(5)
	v_mov_b32_e32 v225, v224
	v_mfma_f32_32x32x16_bf16 v[2:17], v[194:197], v[218:221], v[2:17]
	ds_read_b128 v[190:193], v174 offset:22560
	v_add_f32_e32 v1, v1, v164
	s_add_i32 s11, s11, 1
	v_permlane32_swap_b32_e32 v224, v225
	s_cmp_eq_u32 s9, s11
	v_max_f32_e64 v167, v224, v225
	v_cmp_lt_f32_e32 vcc, s66, v167
	s_waitcnt lgkmcnt(4)
	v_mfma_f32_32x32x16_bf16 v[18:33], v[198:201], v[218:221], v[18:33]
	ds_read_b128 v[194:197], v174 offset:29216
	s_cbranch_scc1 .Lmla_exit_p14

; template <int VAR>
; __device__ __forceinline__ void attn_phase(LAS unsigned char* lds, const AttnP P, int vcu, int G, int wave_s) {
;     ...
;         for (int t = 0; t < nt; ++t) {
;             const bool hn = (t + 1 < nt);
;     ...
;                 if (ND0 == 6) {
;                     KR1(0); KR1(1); KR1(2); KR1(3); SB();
;                     QK1(0, negm); EX2(pc0, 0, w0.x); KR1(4); SB();
;                     QK1(1, negm); EX2(pc0, 2, w0.y); KR1(5); SB();
;                     QK1(2, pn0); EX2(pc0, 4, w0.z); KR1(6); SB();
;                     QK1(3, pn1); EX2(pc0, 6, w0.w); KR1(7); SB();
;                     QK1(4, pn0); EX2(pc0, 8, w1.x); KR1(8); SB();
;                     QK1(5, pn1); EX2(pc0, 10, w1.y); KR1(9); SB();
;                     QK1(6, pn0); EX2(pc0, 12, w1.z); KR1(10); SB();
;                     QK1(7, pn1); EX2(pc0, 14, w1.w); KR1(11); SB();
;                     QK1(8, pn0); EX2(pc1, 0, w2.x); VR1(0); SB();
;                     QK1(9, pn1); EX2(pc1, 2, w2.y); VR1(1); SB();
;                     QK1(10, pn0); EX2(pc1, 4, w2.z); VR1(2); SB();
;                     QK1(11, pn1); EX2(pc1, 6, w2.w); VR1(3); SB();
;                 } else {
;                     KR1(0); KR1(1); KR1(2); KR1(3); SB();
;                     QK1(0, negm); EX2(pc0, 0, w0.x); EX2(pc0, 2, w0.y); KR1(4); SB();
;                     QK1(1, negm); EX2(pc0, 4, w0.z); EX2(pc0, 6, w0.w); KR1(5); SB();
;                     QK1(2, pn0); EX2(pc0, 8, w1.x); EX2(pc0, 10, w1.y); KR1(6); SB();
;                     QK1(3, pn1); EX2(pc0, 12, w1.z); EX2(pc0, 14, w1.w); KR1(7); SB();
;                     QK1(4, pn0); EX2(pc1, 0, w2.x); VR1(0); SB();
;                     QK1(5, pn1); EX2(pc1, 2, w2.y); VR1(1); SB();
;                     QK1(6, pn0); EX2(pc1, 4, w2.z); VR1(2); SB();
;                     QK1(7, pn1); EX2(pc1, 6, w2.w); VR1(3); SB();
;                 }
;                 PV1(0, w0); EX2(pc1, 8, w3.x); VR1(4); SB();
;                 PV1(1, w0); EX2(pc1, 10, w3.y); VR1(5); SB();
;                 PV1(2, w1); EX2(pc1, 12, w3.z); VR1(6); SB();
;                 PV1(3, w1); EX2(pc1, 14, w3.w); VR1(7); SB();
;                 lrun += sacc;
;                 PV1(4, w2); MASK_TILE(pn0, pn1, t + 1); SB();
;                 PV1(5, w2); SB();
;                 PV1(6, w3); SB();
;                 PV1(7, w3); rmn = rowmax32(pn0, pn1); if (!USE_NEGM) rmn -= mref; SB();
.Lmla_p15_go:
	v_exp_f32_e32 v222, v82
	v_exp_f32_e32 v223, v83
	v_add_f32_e32 v164, 0, v222
	v_add_f32_e32 v164, v223, v164
	v_cvt_pk_bf16_f32 v206, v222, v223
	v_exp_f32_e32 v224, v84
	v_exp_f32_e32 v225, v85
	v_add_f32_e32 v164, v224, v164
	v_add_f32_e32 v164, v225, v164
	v_cvt_pk_bf16_f32 v207, v224, v225
	v_exp_f32_e32 v222, v86
	s_waitcnt lgkmcnt(4)
	v_mfma_f32_32x32x16_bf16 v[34:49], v[182:185], v[114:117], v[66:81]
	ds_read_b128 v[198:201], v174 offset:22592
	v_exp_f32_e32 v223, v87
	v_add_f32_e32 v164, v222, v164
	v_cvt_pk_bf16_f32 v208, v222, v223
	v_add_f32_e64 v164, v223, v164
	v_exp_f32_e32 v224, v88
	s_waitcnt lgkmcnt(3)
	v_mfma_f32_32x32x16_bf16 v[50:65], v[186:189], v[114:117], v[66:81]
	ds_read_b128 v[182:185], v174 offset:29248
	v_exp_f32_e32 v225, v89
	v_add_f32_e32 v164, v224, v164
	v_cvt_pk_bf16_f32 v209, v224, v225
	v_add_f32_e64 v164, v225, v164
	v_exp_f32_e32 v222, v90
	s_waitcnt lgkmcnt(3)
	v_mfma_f32_32x32x16_bf16 v[34:49], v[190:193], v[118:121], v[34:49]
	ds_read_b128 v[186:189], v174 offset:22624
	v_exp_f32_e32 v223, v91
	v_add_f32_e32 v164, v222, v164
	v_cvt_pk_bf16_f32 v210, v222, v223
	v_add_f32_e64 v164, v223, v164
	v_exp_f32_e32 v224, v92
	s_waitcnt lgkmcnt(3)
	v_mfma_f32_32x32x16_bf16 v[50:65], v[194:197], v[118:121], v[50:65]
	ds_read_b128 v[190:193], v174 offset:29280
	v_exp_f32_e32 v225, v93
	v_add_f32_e32 v164, v224, v164
	v_cvt_pk_bf16_f32 v211, v224, v225
	v_add_f32_e64 v164, v225, v164
	v_exp_f32_e32 v222, v94
	s_waitcnt lgkmcnt(3)
	v_mfma_f32_32x32x16_bf16 v[34:49], v[198:201], v[122:125], v[34:49]
	ds_read_b128 v[194:197], v174 offset:22656
	v_exp_f32_e32 v223, v95
	v_add_f32_e32 v164, v222, v164
	v_cvt_pk_bf16_f32 v212, v222, v223
	v_add_f32_e64 v164, v223, v164
	v_exp_f32_e32 v224, v96
	s_waitcnt lgkmcnt(3)
	v_mfma_f32_32x32x16_bf16 v[50:65], v[182:185], v[122:125], v[50:65]
	ds_read_b128 v[198:201], v174 offset:29312
	v_exp_f32_e32 v225, v97
	v_add_f32_e32 v164, v224, v164
	v_cvt_pk_bf16_f32 v213, v224, v225
	v_add_f32_e64 v164, v225, v164
	v_exp_f32_e32 v222, v98
	s_waitcnt lgkmcnt(3)
	v_mfma_f32_32x32x16_bf16 v[34:49], v[186:189], v[126:129], v[34:49]
	ds_read_b128 v[182:185], v174 offset:22688
	v_exp_f32_e32 v223, v99
	v_add_f32_e32 v164, v222, v164
	v_cvt_pk_bf16_f32 v214, v222, v223
	v_add_f32_e64 v164, v223, v164
	v_exp_f32_e32 v224, v100
	s_waitcnt lgkmcnt(3)
	v_mfma_f32_32x32x16_bf16 v[50:65], v[190:193], v[126:129], v[50:65]
	ds_read_b128 v[186:189], v174 offset:29344
	v_exp_f32_e32 v225, v101
	v_add_f32_e32 v164, v224, v164
	v_cvt_pk_bf16_f32 v215, v224, v225
	v_add_f32_e64 v164, v225, v164
	v_exp_f32_e32 v222, v102
	s_waitcnt lgkmcnt(3)
	v_mfma_f32_32x32x16_bf16 v[34:49], v[194:197], v[130:133], v[34:49]
	ds_read_b128 v[190:193], v181 offset:49152
	v_exp_f32_e32 v223, v103
	v_add_f32_e32 v164, v222, v164
	v_cvt_pk_bf16_f32 v216, v222, v223
	v_add_f32_e64 v164, v223, v164
	v_exp_f32_e32 v224, v104
	s_waitcnt lgkmcnt(3)
	v_mfma_f32_32x32x16_bf16 v[50:65], v[198:201], v[130:133], v[50:65]
	ds_read_b128 v[194:197], v181 offset:53760
	v_exp_f32_e32 v225, v105
	v_add_f32_e32 v164, v224, v164
	v_cvt_pk_bf16_f32 v217, v224, v225
	v_add_f32_e64 v164, v225, v164
	v_exp_f32_e32 v222, v106
	s_waitcnt lgkmcnt(3)
	v_mfma_f32_32x32x16_bf16 v[34:49], v[182:185], v[134:137], v[34:49]
	ds_read_b128 v[198:201], v181 offset:49184
	v_exp_f32_e32 v223, v107
	v_add_f32_e32 v164, v222, v164
	v_cvt_pk_bf16_f32 v218, v222, v223
	v_add_f32_e64 v164, v223, v164
	v_exp_f32_e32 v224, v108
	s_waitcnt lgkmcnt(3)
	v_mfma_f32_32x32x16_bf16 v[50:65], v[186:189], v[134:137], v[50:65]
	ds_read_b128 v[182:185], v181 offset:53792
	v_exp_f32_e32 v225, v109
	v_add_f32_e32 v164, v224, v164
	v_cvt_pk_bf16_f32 v219, v224, v225
	v_add_f32_e64 v164, v225, v164
	v_exp_f32_e32 v222, v110
	s_waitcnt lgkmcnt(3)
	v_mfma_f32_32x32x16_bf16 v[2:17], v[190:193], v[206:209], v[2:17]
	ds_read_b128 v[186:189], v181 offset:49216
	v_exp_f32_e32 v223, v111
	v_add_f32_e32 v164, v222, v164
	v_cvt_pk_bf16_f32 v220, v222, v223
	v_add_f32_e64 v164, v223, v164
	v_exp_f32_e32 v224, v112
	s_waitcnt lgkmcnt(3)
	v_mfma_f32_32x32x16_bf16 v[18:33], v[194:197], v[206:209], v[18:33]
	ds_read_b128 v[190:193], v181 offset:53824
	v_exp_f32_e32 v225, v113
	v_add_f32_e32 v164, v224, v164
	v_cvt_pk_bf16_f32 v221, v224, v225
	v_add_f32_e64 v164, v225, v164
	s_mov_b32 s13, s20
	s_mov_b32 s20, s19
	s_add_i32 s19, s19, 1
	s_cmp_eq_u32 s19, s9
	s_cselect_b32 s19, 0, s19
	s_nop 0
	s_waitcnt lgkmcnt(3)
	s_waitcnt vmcnt(2)
	v_mfma_f32_32x32x16_bf16 v[2:17], v[198:201], v[210:213], v[2:17]
	ds_read_b128 v[194:197], v181 offset:49248
	v_max3_f32 v224, v34, v35, v36
	v_max3_f32 v225, v50, v51, v52
	v_max3_f32 v224, v224, v37, v38
	v_max3_f32 v225, v225, v53, v54
	v_add_u32_e32 v222, 0xb000, v172
	ds_write_b128 v222, v[150:153] offset:26624
	v_lshl_add_u32 v222, s19, 17, v178
	global_load_dwordx4 v[150:153], v222, s[52:53]
	s_waitcnt lgkmcnt(4)
	s_and_b64 vcc, exec, s[2:3]
	v_mfma_f32_32x32x16_bf16 v[18:33], v[182:185], v[210:213], v[18:33]
	ds_read_b128 v[198:201], v181 offset:53856
	v_max3_f32 v224, v224, v39, v40
	v_max3_f32 v225, v225, v55, v56
	v_max3_f32 v224, v224, v41, v42
	v_max3_f32 v225, v225, v57, v58
	s_cbranch_vccz .Lmla_p15_nope
	s_nop 0
	v_add_u32_e32 v222, 0xb000, v176
	ds_write_b128 v222, v[160:163] offset:26752
	v_lshl_add_u32 v222, s19, 12, v179
	global_load_dwordx4 v[160:163], v222, s[62:63]
.Lmla_p15_nope:
	s_waitcnt lgkmcnt(4)
	s_nop 0
	v_mfma_f32_32x32x16_bf16 v[2:17], v[186:189], v[214:217], v[2:17]
	ds_read_b128 v[182:185], v174 offset:45056
	v_max3_f32 v224, v224, v43, v44
	v_max3_f32 v225, v225, v59, v60
	v_max3_f32 v224, v224, v45, v46
	v_max3_f32 v225, v225, v61, v62
	ds_write_b128 v173, v[202:205] offset:35840
	v_lshl_add_u32 v222, s13, 7, v168
	global_load_dwordx4 v[202:205], v222, s[56:57]
	s_waitcnt lgkmcnt(5)
	s_nop 0
	v_mfma_f32_32x32x16_bf16 v[18:33], v[190:193], v[214:217], v[18:33]
	ds_read_b128 v[186:189], v174 offset:51712
	v_max3_f32 v224, v224, v47, v48
	v_max3_f32 v225, v225, v63, v64
	v_max3_f32 v224, v224, v49, v65
	v_max_f32_e64 v224, v224, v225
	s_waitcnt lgkmcnt(5)
	v_mov_b32_e32 v225, v224
	v_mfma_f32_32x32x16_bf16 v[2:17], v[194:197], v[218:221], v[2:17]
	ds_read_b128 v[190:193], v174 offset:45088
	v_add_f32_e32 v1, v1, v164
	s_add_i32 s11, s11, 1
	v_permlane32_swap_b32_e32 v224, v225
	s_cmp_eq_u32 s9, s11
	v_max_f32_e64 v167, v224, v225
	v_cmp_lt_f32_e32 vcc, s66, v167
	s_waitcnt lgkmcnt(4)
	v_mfma_f32_32x32x16_bf16 v[18:33], v[198:201], v[218:221], v[18:33]
	ds_read_b128 v[194:197], v174 offset:51744
	s_waitcnt lgkmcnt(3)
	s_barrier
	s_cbranch_scc1 .Lmla_exit_p15

; template <int VAR>
; __device__ __forceinline__ void attn_phase(LAS unsigned char* lds, const AttnP P, int vcu, int G, int wave_s) {
;     ...
;         for (int t = 0; t < nt; ++t) {
;             const bool hn = (t + 1 < nt);
;     ...
;                 if (ND0 == 6) {
;                     KR1(0); KR1(1); KR1(2); KR1(3); SB();
;                     QK1(0, negm); EX2(pc0, 0, w0.x); KR1(4); SB();
;                     QK1(1, negm); EX2(pc0, 2, w0.y); KR1(5); SB();
;                     QK1(2, pn0); EX2(pc0, 4, w0.z); KR1(6); SB();
;                     QK1(3, pn1); EX2(pc0, 6, w0.w); KR1(7); SB();
;                     QK1(4, pn0); EX2(pc0, 8, w1.x); KR1(8); SB();
;                     QK1(5, pn1); EX2(pc0, 10, w1.y); KR1(9); SB();
;                     QK1(6, pn0); EX2(pc0, 12, w1.z); KR1(10); SB();
;                     QK1(7, pn1); EX2(pc0, 14, w1.w); KR1(11); SB();
;                     QK1(8, pn0); EX2(pc1, 0, w2.x); VR1(0); SB();
;                     QK1(9, pn1); EX2(pc1, 2, w2.y); VR1(1); SB();
;                     QK1(10, pn0); EX2(pc1, 4, w2.z); VR1(2); SB();
;                     QK1(11, pn1); EX2(pc1, 6, w2.w); VR1(3); SB();
;                 } else {
;                     KR1(0); KR1(1); KR1(2); KR1(3); SB();
;                     QK1(0, negm); EX2(pc0, 0, w0.x); EX2(pc0, 2, w0.y); KR1(4); SB();
;                     QK1(1, negm); EX2(pc0, 4, w0.z); EX2(pc0, 6, w0.w); KR1(5); SB();
;                     QK1(2, pn0); EX2(pc0, 8, w1.x); EX2(pc0, 10, w1.y); KR1(6); SB();
;                     QK1(3, pn1); EX2(pc0, 12, w1.z); EX2(pc0, 14, w1.w); KR1(7); SB();
;                     QK1(4, pn0); EX2(pc1, 0, w2.x); VR1(0); SB();
;                     QK1(5, pn1); EX2(pc1, 2, w2.y); VR1(1); SB();
;                     QK1(6, pn0); EX2(pc1, 4, w2.z); VR1(2); SB();
;                     QK1(7, pn1); EX2(pc1, 6, w2.w); VR1(3); SB();
;                 }
;                 PV1(0, w0); EX2(pc1, 8, w3.x); VR1(4); SB();
;                 PV1(1, w0); EX2(pc1, 10, w3.y); VR1(5); SB();
;                 PV1(2, w1); EX2(pc1, 12, w3.z); VR1(6); SB();
;                 PV1(3, w1); EX2(pc1, 14, w3.w); VR1(7); SB();
;                 lrun += sacc;
;                 PV1(4, w2); MASK_TILE(pn0, pn1, t + 1); SB();
;                 PV1(5, w2); SB();
;                 PV1(6, w3); SB();
;                 PV1(7, w3); rmn = rowmax32(pn0, pn1); if (!USE_NEGM) rmn -= mref; SB();
.Lmla_p16_go:
	v_exp_f32_e32 v222, v34
	v_exp_f32_e32 v223, v35
	v_add_f32_e32 v164, 0, v222
	v_add_f32_e32 v164, v223, v164
	v_cvt_pk_bf16_f32 v206, v222, v223
	v_exp_f32_e32 v224, v36
	v_exp_f32_e32 v225, v37
	v_add_f32_e32 v164, v224, v164
	v_add_f32_e32 v164, v225, v164
	v_cvt_pk_bf16_f32 v207, v224, v225
	v_exp_f32_e32 v222, v38
	s_waitcnt lgkmcnt(3)
	v_mfma_f32_32x32x16_bf16 v[82:97], v[182:185], v[114:117], v[66:81]
	ds_read_b128 v[198:201], v174 offset:45120
	v_exp_f32_e32 v223, v39
	v_add_f32_e32 v164, v222, v164
	v_cvt_pk_bf16_f32 v208, v222, v223
	v_add_f32_e64 v164, v223, v164
	v_exp_f32_e32 v224, v40
	s_waitcnt lgkmcnt(3)
	v_mfma_f32_32x32x16_bf16 v[98:113], v[186:189], v[114:117], v[66:81]
	ds_read_b128 v[182:185], v174 offset:51776
	v_exp_f32_e32 v225, v41
	v_add_f32_e32 v164, v224, v164
	v_cvt_pk_bf16_f32 v209, v224, v225
	v_add_f32_e64 v164, v225, v164
	v_exp_f32_e32 v222, v42
	s_waitcnt lgkmcnt(3)
	v_mfma_f32_32x32x16_bf16 v[82:97], v[190:193], v[118:121], v[82:97]
	ds_read_b128 v[186:189], v174 offset:45152
	v_exp_f32_e32 v223, v43
	v_add_f32_e32 v164, v222, v164
	v_cvt_pk_bf16_f32 v210, v222, v223
	v_add_f32_e64 v164, v223, v164
	v_exp_f32_e32 v224, v44
	s_waitcnt lgkmcnt(3)
	v_mfma_f32_32x32x16_bf16 v[98:113], v[194:197], v[118:121], v[98:113]
	ds_read_b128 v[190:193], v174 offset:51808
	v_exp_f32_e32 v225, v45
	v_add_f32_e32 v164, v224, v164
	v_cvt_pk_bf16_f32 v211, v224, v225
	v_add_f32_e64 v164, v225, v164
	v_exp_f32_e32 v222, v46
	s_waitcnt lgkmcnt(3)
	v_mfma_f32_32x32x16_bf16 v[82:97], v[198:201], v[122:125], v[82:97]
	ds_read_b128 v[194:197], v174 offset:45184
	v_exp_f32_e32 v223, v47
	v_add_f32_e32 v164, v222, v164
	v_cvt_pk_bf16_f32 v212, v222, v223
	v_add_f32_e64 v164, v223, v164
	v_exp_f32_e32 v224, v48
	s_waitcnt lgkmcnt(3)
	v_mfma_f32_32x32x16_bf16 v[98:113], v[182:185], v[122:125], v[98:113]
	ds_read_b128 v[198:201], v174 offset:51840
	v_exp_f32_e32 v225, v49
	v_add_f32_e32 v164, v224, v164
	v_cvt_pk_bf16_f32 v213, v224, v225
	v_add_f32_e64 v164, v225, v164
	v_exp_f32_e32 v222, v50
	s_waitcnt lgkmcnt(3)
	v_mfma_f32_32x32x16_bf16 v[82:97], v[186:189], v[126:129], v[82:97]
	ds_read_b128 v[182:185], v174 offset:45216
	v_exp_f32_e32 v223, v51
	v_add_f32_e32 v164, v222, v164
	v_cvt_pk_bf16_f32 v214, v222, v223
	v_add_f32_e64 v164, v223, v164
	v_exp_f32_e32 v224, v52
	s_waitcnt lgkmcnt(3)
	v_mfma_f32_32x32x16_bf16 v[98:113], v[190:193], v[126:129], v[98:113]
	ds_read_b128 v[186:189], v174 offset:51872
	v_exp_f32_e32 v225, v53
	v_add_f32_e32 v164, v224, v164
	v_cvt_pk_bf16_f32 v215, v224, v225
	v_add_f32_e64 v164, v225, v164
	v_exp_f32_e32 v222, v54
	s_waitcnt lgkmcnt(3)
	v_mfma_f32_32x32x16_bf16 v[82:97], v[194:197], v[130:133], v[82:97]
	ds_read_b128 v[190:193], v228 offset:13312
	v_exp_f32_e32 v223, v55
	v_add_f32_e32 v164, v222, v164
	v_cvt_pk_bf16_f32 v216, v222, v223
	v_add_f32_e64 v164, v223, v164
	v_exp_f32_e32 v224, v56
	s_waitcnt lgkmcnt(3)
	v_mfma_f32_32x32x16_bf16 v[98:113], v[198:201], v[130:133], v[98:113]
	ds_read_b128 v[194:197], v228 offset:17920
	v_exp_f32_e32 v225, v57
	v_add_f32_e32 v164, v224, v164
	v_cvt_pk_bf16_f32 v217, v224, v225
	v_add_f32_e64 v164, v225, v164
	v_exp_f32_e32 v222, v58
	s_waitcnt lgkmcnt(3)
	v_mfma_f32_32x32x16_bf16 v[82:97], v[182:185], v[134:137], v[82:97]
	ds_read_b128 v[198:201], v228 offset:13344
	v_exp_f32_e32 v223, v59
	v_add_f32_e32 v164, v222, v164
	v_cvt_pk_bf16_f32 v218, v222, v223
	v_add_f32_e64 v164, v223, v164
	v_exp_f32_e32 v224, v60
	s_waitcnt lgkmcnt(3)
	v_mfma_f32_32x32x16_bf16 v[98:113], v[186:189], v[134:137], v[98:113]
	ds_read_b128 v[182:185], v228 offset:17952
	v_exp_f32_e32 v225, v61
	v_add_f32_e32 v164, v224, v164
	v_cvt_pk_bf16_f32 v219, v224, v225
	v_add_f32_e64 v164, v225, v164
	v_exp_f32_e32 v222, v62
	s_waitcnt lgkmcnt(3)
	v_mfma_f32_32x32x16_bf16 v[2:17], v[190:193], v[206:209], v[2:17]
	ds_read_b128 v[186:189], v228 offset:13376
	v_exp_f32_e32 v223, v63
	v_add_f32_e32 v164, v222, v164
	v_cvt_pk_bf16_f32 v220, v222, v223
	v_add_f32_e64 v164, v223, v164
	v_exp_f32_e32 v224, v64
	s_waitcnt lgkmcnt(3)
	v_mfma_f32_32x32x16_bf16 v[18:33], v[194:197], v[206:209], v[18:33]
	ds_read_b128 v[190:193], v228 offset:17984
	v_exp_f32_e32 v225, v65
	v_add_f32_e32 v164, v224, v164
	v_cvt_pk_bf16_f32 v221, v224, v225
	v_add_f32_e64 v164, v225, v164
	s_mov_b32 s13, s20
	s_mov_b32 s20, s19
	s_add_i32 s19, s19, 1
	s_cmp_eq_u32 s19, s9
	s_cselect_b32 s19, 0, s19
	s_nop 0
	s_waitcnt lgkmcnt(3)
	s_waitcnt vmcnt(2)
	v_mfma_f32_32x32x16_bf16 v[2:17], v[198:201], v[210:213], v[2:17]
	ds_read_b128 v[194:197], v228 offset:13408
	v_max3_f32 v224, v82, v83, v84
	v_max3_f32 v225, v98, v99, v100
	v_max3_f32 v224, v224, v85, v86
	v_max3_f32 v225, v225, v101, v102
	ds_write_b128 v172, v[146:149]
	v_lshl_add_u32 v222, s19, 17, v178
	global_load_dwordx4 v[146:149], v222, s[52:53]
	s_waitcnt lgkmcnt(4)
	s_and_b64 vcc, exec, s[2:3]
	v_mfma_f32_32x32x16_bf16 v[18:33], v[182:185], v[210:213], v[18:33]
	ds_read_b128 v[198:201], v228 offset:18016
	v_max3_f32 v224, v224, v87, v88
	v_max3_f32 v225, v225, v103, v104
	v_max3_f32 v224, v224, v89, v90
	v_max3_f32 v225, v225, v105, v106
	s_cbranch_vccz .Lmla_p16_nope
	s_nop 0
	ds_write_b128 v176, v[138:141] offset:128
	v_lshl_add_u32 v222, s19, 12, v179
	global_load_dwordx4 v[138:141], v222, s[62:63]
.Lmla_p16_nope:
	s_waitcnt lgkmcnt(4)
	s_nop 0
	v_mfma_f32_32x32x16_bf16 v[2:17], v[186:189], v[214:217], v[2:17]
	ds_read_b128 v[182:185], v229 offset:13312
	v_max3_f32 v224, v224, v91, v92
	v_max3_f32 v225, v225, v107, v108
	v_max3_f32 v224, v224, v93, v94
	v_max3_f32 v225, v225, v109, v110
	v_add_u32_e32 v222, 0xb000, v173
	ds_write_b128 v222, v[142:145] offset:39936
	v_lshl_add_u32 v222, s13, 7, v168
	global_load_dwordx4 v[142:145], v222, s[56:57]
	s_waitcnt lgkmcnt(5)
	s_nop 0
	v_mfma_f32_32x32x16_bf16 v[18:33], v[190:193], v[214:217], v[18:33]
	ds_read_b128 v[186:189], v229 offset:19968
	v_max3_f32 v224, v224, v95, v96
	v_max3_f32 v225, v225, v111, v112
	v_max3_f32 v224, v224, v97, v113
	v_max_f32_e64 v224, v224, v225
	s_waitcnt lgkmcnt(5)
	v_mov_b32_e32 v225, v224
	v_mfma_f32_32x32x16_bf16 v[2:17], v[194:197], v[218:221], v[2:17]
	ds_read_b128 v[190:193], v229 offset:13344
	v_add_f32_e32 v1, v1, v164
	s_add_i32 s11, s11, 1
	v_permlane32_swap_b32_e32 v224, v225
	s_cmp_eq_u32 s9, s11
	v_max_f32_e64 v167, v224, v225
	v_cmp_lt_f32_e32 vcc, s66, v167
	s_waitcnt lgkmcnt(4)
	v_mfma_f32_32x32x16_bf16 v[18:33], v[198:201], v[218:221], v[18:33]
	ds_read_b128 v[194:197], v229 offset:20000
	s_cbranch_scc1 .Lmla_exit_p16

; template <int VAR>
; __device__ __forceinline__ void attn_phase(LAS unsigned char* lds, const AttnP P, int vcu, int G, int wave_s) {
;     ...
;         for (int t = 0; t < nt; ++t) {
;             const bool hn = (t + 1 < nt);
;     ...
;                 if (ND0 == 6) {
;                     KR1(0); KR1(1); KR1(2); KR1(3); SB();
;                     QK1(0, negm); EX2(pc0, 0, w0.x); KR1(4); SB();
;                     QK1(1, negm); EX2(pc0, 2, w0.y); KR1(5); SB();
;                     QK1(2, pn0); EX2(pc0, 4, w0.z); KR1(6); SB();
;                     QK1(3, pn1); EX2(pc0, 6, w0.w); KR1(7); SB();
;                     QK1(4, pn0); EX2(pc0, 8, w1.x); KR1(8); SB();
;                     QK1(5, pn1); EX2(pc0, 10, w1.y); KR1(9); SB();
;                     QK1(6, pn0); EX2(pc0, 12, w1.z); KR1(10); SB();
;                     QK1(7, pn1); EX2(pc0, 14, w1.w); KR1(11); SB();
;                     QK1(8, pn0); EX2(pc1, 0, w2.x); VR1(0); SB();
;                     QK1(9, pn1); EX2(pc1, 2, w2.y); VR1(1); SB();
;                     QK1(10, pn0); EX2(pc1, 4, w2.z); VR1(2); SB();
;                     QK1(11, pn1); EX2(pc1, 6, w2.w); VR1(3); SB();
;                 } else {
;                     KR1(0); KR1(1); KR1(2); KR1(3); SB();
;                     QK1(0, negm); EX2(pc0, 0, w0.x); EX2(pc0, 2, w0.y); KR1(4); SB();
;                     QK1(1, negm); EX2(pc0, 4, w0.z); EX2(pc0, 6, w0.w); KR1(5); SB();
;                     QK1(2, pn0); EX2(pc0, 8, w1.x); EX2(pc0, 10, w1.y); KR1(6); SB();
;                     QK1(3, pn1); EX2(pc0, 12, w1.z); EX2(pc0, 14, w1.w); KR1(7); SB();
;                     QK1(4, pn0); EX2(pc1, 0, w2.x); VR1(0); SB();
;                     QK1(5, pn1); EX2(pc1, 2, w2.y); VR1(1); SB();
;                     QK1(6, pn0); EX2(pc1, 4, w2.z); VR1(2); SB();
;                     QK1(7, pn1); EX2(pc1, 6, w2.w); VR1(3); SB();
;                 }
;                 PV1(0, w0); EX2(pc1, 8, w3.x); VR1(4); SB();
;                 PV1(1, w0); EX2(pc1, 10, w3.y); VR1(5); SB();
;                 PV1(2, w1); EX2(pc1, 12, w3.z); VR1(6); SB();
;                 PV1(3, w1); EX2(pc1, 14, w3.w); VR1(7); SB();
;                 lrun += sacc;
;                 PV1(4, w2); MASK_TILE(pn0, pn1, t + 1); SB();
;                 PV1(5, w2); SB();
;                 PV1(6, w3); SB();
;                 PV1(7, w3); rmn = rowmax32(pn0, pn1); if (!USE_NEGM) rmn -= mref; SB();
.Lmla_p17_go:
	v_exp_f32_e32 v222, v82
	v_exp_f32_e32 v223, v83
	v_add_f32_e32 v164, 0, v222
	v_add_f32_e32 v164, v223, v164
	v_cvt_pk_bf16_f32 v206, v222, v223
	v_exp_f32_e32 v224, v84
	v_exp_f32_e32 v225, v85
	v_add_f32_e32 v164, v224, v164
	v_add_f32_e32 v164, v225, v164
	v_cvt_pk_bf16_f32 v207, v224, v225
	v_exp_f32_e32 v222, v86
	s_waitcnt lgkmcnt(4)
	v_mfma_f32_32x32x16_bf16 v[34:49], v[182:185], v[114:117], v[66:81]
	ds_read_b128 v[198:201], v229 offset:13376
	v_exp_f32_e32 v223, v87
	v_add_f32_e32 v164, v222, v164
	v_cvt_pk_bf16_f32 v208, v222, v223
	v_add_f32_e64 v164, v223, v164
	v_exp_f32_e32 v224, v88
	s_waitcnt lgkmcnt(3)
	v_mfma_f32_32x32x16_bf16 v[50:65], v[186:189], v[114:117], v[66:81]
	ds_read_b128 v[182:185], v229 offset:20032
	v_exp_f32_e32 v225, v89
	v_add_f32_e32 v164, v224, v164
	v_cvt_pk_bf16_f32 v209, v224, v225
	v_add_f32_e64 v164, v225, v164
	v_exp_f32_e32 v222, v90
	s_waitcnt lgkmcnt(3)
	v_mfma_f32_32x32x16_bf16 v[34:49], v[190:193], v[118:121], v[34:49]
	ds_read_b128 v[186:189], v229 offset:13408
	v_exp_f32_e32 v223, v91
	v_add_f32_e32 v164, v222, v164
	v_cvt_pk_bf16_f32 v210, v222, v223
	v_add_f32_e64 v164, v223, v164
	v_exp_f32_e32 v224, v92
	s_waitcnt lgkmcnt(3)
	v_mfma_f32_32x32x16_bf16 v[50:65], v[194:197], v[118:121], v[50:65]
	ds_read_b128 v[190:193], v229 offset:20064
	v_exp_f32_e32 v225, v93
	v_add_f32_e32 v164, v224, v164
	v_cvt_pk_bf16_f32 v211, v224, v225
	v_add_f32_e64 v164, v225, v164
	v_exp_f32_e32 v222, v94
	s_waitcnt lgkmcnt(3)
	v_mfma_f32_32x32x16_bf16 v[34:49], v[198:201], v[122:125], v[34:49]
	ds_read_b128 v[194:197], v229 offset:13440
	v_exp_f32_e32 v223, v95
	v_add_f32_e32 v164, v222, v164
	v_cvt_pk_bf16_f32 v212, v222, v223
	v_add_f32_e64 v164, v223, v164
	v_exp_f32_e32 v224, v96
	s_waitcnt lgkmcnt(3)
	v_mfma_f32_32x32x16_bf16 v[50:65], v[182:185], v[122:125], v[50:65]
	ds_read_b128 v[198:201], v229 offset:20096
	v_exp_f32_e32 v225, v97
	v_add_f32_e32 v164, v224, v164
	v_cvt_pk_bf16_f32 v213, v224, v225
	v_add_f32_e64 v164, v225, v164
	v_exp_f32_e32 v222, v98
	s_waitcnt lgkmcnt(3)
	v_mfma_f32_32x32x16_bf16 v[34:49], v[186:189], v[126:129], v[34:49]
	ds_read_b128 v[182:185], v229 offset:13472
	v_exp_f32_e32 v223, v99
	v_add_f32_e32 v164, v222, v164
	v_cvt_pk_bf16_f32 v214, v222, v223
	v_add_f32_e64 v164, v223, v164
	v_exp_f32_e32 v224, v100
	s_waitcnt lgkmcnt(3)
	v_mfma_f32_32x32x16_bf16 v[50:65], v[190:193], v[126:129], v[50:65]
	ds_read_b128 v[186:189], v229 offset:20128
	v_exp_f32_e32 v225, v101
	v_add_f32_e32 v164, v224, v164
	v_cvt_pk_bf16_f32 v215, v224, v225
	v_add_f32_e64 v164, v225, v164
	v_exp_f32_e32 v222, v102
	s_waitcnt lgkmcnt(3)
	v_mfma_f32_32x32x16_bf16 v[34:49], v[194:197], v[130:133], v[34:49]
	ds_read_b128 v[190:193], v228 offset:35840
	v_exp_f32_e32 v223, v103
	v_add_f32_e32 v164, v222, v164
	v_cvt_pk_bf16_f32 v216, v222, v223
	v_add_f32_e64 v164, v223, v164
	v_exp_f32_e32 v224, v104
	s_waitcnt lgkmcnt(3)
	v_mfma_f32_32x32x16_bf16 v[50:65], v[198:201], v[130:133], v[50:65]
	ds_read_b128 v[194:197], v228 offset:40448
	v_exp_f32_e32 v225, v105
	v_add_f32_e32 v164, v224, v164
	v_cvt_pk_bf16_f32 v217, v224, v225
	v_add_f32_e64 v164, v225, v164
	v_exp_f32_e32 v222, v106
	s_waitcnt lgkmcnt(3)
	v_mfma_f32_32x32x16_bf16 v[34:49], v[182:185], v[134:137], v[34:49]
	ds_read_b128 v[198:201], v228 offset:35872
	v_exp_f32_e32 v223, v107
	v_add_f32_e32 v164, v222, v164
	v_cvt_pk_bf16_f32 v218, v222, v223
	v_add_f32_e64 v164, v223, v164
	v_exp_f32_e32 v224, v108
	s_waitcnt lgkmcnt(3)
	v_mfma_f32_32x32x16_bf16 v[50:65], v[186:189], v[134:137], v[50:65]
	ds_read_b128 v[182:185], v228 offset:40480
	v_exp_f32_e32 v225, v109
	v_add_f32_e32 v164, v224, v164
	v_cvt_pk_bf16_f32 v219, v224, v225
	v_add_f32_e64 v164, v225, v164
	v_exp_f32_e32 v222, v110
	s_waitcnt lgkmcnt(3)
	v_mfma_f32_32x32x16_bf16 v[2:17], v[190:193], v[206:209], v[2:17]
	ds_read_b128 v[186:189], v228 offset:35904
	v_exp_f32_e32 v223, v111
	v_add_f32_e32 v164, v222, v164
	v_cvt_pk_bf16_f32 v220, v222, v223
	v_add_f32_e64 v164, v223, v164
	v_exp_f32_e32 v224, v112
	s_waitcnt lgkmcnt(3)
	v_mfma_f32_32x32x16_bf16 v[18:33], v[194:197], v[206:209], v[18:33]
	ds_read_b128 v[190:193], v228 offset:40512
	v_exp_f32_e32 v225, v113
	v_add_f32_e32 v164, v224, v164
	v_cvt_pk_bf16_f32 v221, v224, v225
	v_add_f32_e64 v164, v225, v164
	s_mov_b32 s13, s20
	s_mov_b32 s20, s19
	s_add_i32 s19, s19, 1
	s_cmp_eq_u32 s19, s9
	s_cselect_b32 s19, 0, s19
	s_nop 0
	s_waitcnt lgkmcnt(3)
	s_waitcnt vmcnt(2)
	v_mfma_f32_32x32x16_bf16 v[2:17], v[198:201], v[210:213], v[2:17]
	ds_read_b128 v[194:197], v228 offset:35936
	v_max3_f32 v224, v34, v35, v36
	v_max3_f32 v225, v50, v51, v52
	v_max3_f32 v224, v224, v37, v38
	v_max3_f32 v225, v225, v53, v54
	ds_write_b128 v172, v[150:153] offset:22528
	v_lshl_add_u32 v222, s19, 17, v178
	global_load_dwordx4 v[150:153], v222, s[52:53]
	s_waitcnt lgkmcnt(4)
	s_and_b64 vcc, exec, s[2:3]
	v_mfma_f32_32x32x16_bf16 v[18:33], v[182:185], v[210:213], v[18:33]
	ds_read_b128 v[198:201], v228 offset:40544
	v_max3_f32 v224, v224, v39, v40
	v_max3_f32 v225, v225, v55, v56
	v_max3_f32 v224, v224, v41, v42
	v_max3_f32 v225, v225, v57, v58
	s_cbranch_vccz .Lmla_p17_nope
	s_nop 0
	ds_write_b128 v176, v[160:163] offset:22656
	v_lshl_add_u32 v222, s19, 12, v179
	global_load_dwordx4 v[160:163], v222, s[62:63]
.Lmla_p17_nope:
	s_waitcnt lgkmcnt(4)
	s_nop 0
	v_mfma_f32_32x32x16_bf16 v[2:17], v[186:189], v[214:217], v[2:17]
	ds_read_b128 v[182:185], v229 offset:26624
	v_max3_f32 v224, v224, v43, v44
	v_max3_f32 v225, v225, v59, v60
	v_max3_f32 v224, v224, v45, v46
	v_max3_f32 v225, v225, v61, v62
	v_add_u32_e32 v222, 0xb000, v173
	ds_write_b128 v222, v[202:205] offset:49152
	v_lshl_add_u32 v222, s13, 7, v168
	global_load_dwordx4 v[202:205], v222, s[56:57]
	s_waitcnt lgkmcnt(5)
	s_nop 0
	v_mfma_f32_32x32x16_bf16 v[18:33], v[190:193], v[214:217], v[18:33]
	ds_read_b128 v[186:189], v229 offset:33280
	v_max3_f32 v224, v224, v47, v48
	v_max3_f32 v225, v225, v63, v64
	v_max3_f32 v224, v224, v49, v65
	v_max_f32_e64 v224, v224, v225
	s_waitcnt lgkmcnt(5)
	v_mov_b32_e32 v225, v224
	v_mfma_f32_32x32x16_bf16 v[2:17], v[194:197], v[218:221], v[2:17]
	ds_read_b128 v[190:193], v229 offset:26656
	v_add_f32_e32 v1, v1, v164
	s_add_i32 s11, s11, 1
	v_permlane32_swap_b32_e32 v224, v225
	s_cmp_eq_u32 s9, s11
	v_max_f32_e64 v167, v224, v225
	v_cmp_lt_f32_e32 vcc, s66, v167
	s_waitcnt lgkmcnt(4)
	v_mfma_f32_32x32x16_bf16 v[18:33], v[198:201], v[218:221], v[18:33]
	ds_read_b128 v[194:197], v229 offset:33312
	s_waitcnt lgkmcnt(3)
	s_barrier
	s_cbranch_scc1 .Lmla_exit_p17

; template <int VAR>
; __device__ __forceinline__ void attn_phase(LAS unsigned char* lds, const AttnP P, int vcu, int G, int wave_s) {
;     ...
;         for (int t = 0; t < nt; ++t) {
;             const bool hn = (t + 1 < nt);
;     ...
;                 if (ND0 == 6) {
;                     KR1(0); KR1(1); KR1(2); KR1(3); SB();
;                     QK1(0, negm); EX2(pc0, 0, w0.x); KR1(4); SB();
;                     QK1(1, negm); EX2(pc0, 2, w0.y); KR1(5); SB();
;                     QK1(2, pn0); EX2(pc0, 4, w0.z); KR1(6); SB();
;                     QK1(3, pn1); EX2(pc0, 6, w0.w); KR1(7); SB();
;                     QK1(4, pn0); EX2(pc0, 8, w1.x); KR1(8); SB();
;                     QK1(5, pn1); EX2(pc0, 10, w1.y); KR1(9); SB();
;                     QK1(6, pn0); EX2(pc0, 12, w1.z); KR1(10); SB();
;                     QK1(7, pn1); EX2(pc0, 14, w1.w); KR1(11); SB();
;                     QK1(8, pn0); EX2(pc1, 0, w2.x); VR1(0); SB();
;                     QK1(9, pn1); EX2(pc1, 2, w2.y); VR1(1); SB();
;                     QK1(10, pn0); EX2(pc1, 4, w2.z); VR1(2); SB();
;                     QK1(11, pn1); EX2(pc1, 6, w2.w); VR1(3); SB();
;                 } else {
;                     KR1(0); KR1(1); KR1(2); KR1(3); SB();
;                     QK1(0, negm); EX2(pc0, 0, w0.x); EX2(pc0, 2, w0.y); KR1(4); SB();
;                     QK1(1, negm); EX2(pc0, 4, w0.z); EX2(pc0, 6, w0.w); KR1(5); SB();
;                     QK1(2, pn0); EX2(pc0, 8, w1.x); EX2(pc0, 10, w1.y); KR1(6); SB();
;                     QK1(3, pn1); EX2(pc0, 12, w1.z); EX2(pc0, 14, w1.w); KR1(7); SB();
;                     QK1(4, pn0); EX2(pc1, 0, w2.x); VR1(0); SB();
;                     QK1(5, pn1); EX2(pc1, 2, w2.y); VR1(1); SB();
;                     QK1(6, pn0); EX2(pc1, 4, w2.z); VR1(2); SB();
;                     QK1(7, pn1); EX2(pc1, 6, w2.w); VR1(3); SB();
;                 }
;                 PV1(0, w0); EX2(pc1, 8, w3.x); VR1(4); SB();
;                 PV1(1, w0); EX2(pc1, 10, w3.y); VR1(5); SB();
;                 PV1(2, w1); EX2(pc1, 12, w3.z); VR1(6); SB();
;                 PV1(3, w1); EX2(pc1, 14, w3.w); VR1(7); SB();
;                 lrun += sacc;
;                 PV1(4, w2); MASK_TILE(pn0, pn1, t + 1); SB();
;                 PV1(5, w2); SB();
;                 PV1(6, w3); SB();
;                 PV1(7, w3); rmn = rowmax32(pn0, pn1); if (!USE_NEGM) rmn -= mref; SB();
.Lmla_p18_go:
	v_exp_f32_e32 v222, v34
	v_exp_f32_e32 v223, v35
	v_add_f32_e32 v164, 0, v222
	v_add_f32_e32 v164, v223, v164
	v_cvt_pk_bf16_f32 v206, v222, v223
	v_exp_f32_e32 v224, v36
	v_exp_f32_e32 v225, v37
	v_add_f32_e32 v164, v224, v164
	v_add_f32_e32 v164, v225, v164
	v_cvt_pk_bf16_f32 v207, v224, v225
	v_exp_f32_e32 v222, v38
	s_waitcnt lgkmcnt(3)
	v_mfma_f32_32x32x16_bf16 v[82:97], v[182:185], v[114:117], v[66:81]
	ds_read_b128 v[198:201], v229 offset:26688
	v_exp_f32_e32 v223, v39
	v_add_f32_e32 v164, v222, v164
	v_cvt_pk_bf16_f32 v208, v222, v223
	v_add_f32_e64 v164, v223, v164
	v_exp_f32_e32 v224, v40
	s_waitcnt lgkmcnt(3)
	v_mfma_f32_32x32x16_bf16 v[98:113], v[186:189], v[114:117], v[66:81]
	ds_read_b128 v[182:185], v229 offset:33344
	v_exp_f32_e32 v225, v41
	v_add_f32_e32 v164, v224, v164
	v_cvt_pk_bf16_f32 v209, v224, v225
	v_add_f32_e64 v164, v225, v164
	v_exp_f32_e32 v222, v42
	s_waitcnt lgkmcnt(3)
	v_mfma_f32_32x32x16_bf16 v[82:97], v[190:193], v[118:121], v[82:97]
	ds_read_b128 v[186:189], v229 offset:26720
	v_exp_f32_e32 v223, v43
	v_add_f32_e32 v164, v222, v164
	v_cvt_pk_bf16_f32 v210, v222, v223
	v_add_f32_e64 v164, v223, v164
	v_exp_f32_e32 v224, v44
	s_waitcnt lgkmcnt(3)
	v_mfma_f32_32x32x16_bf16 v[98:113], v[194:197], v[118:121], v[98:113]
	ds_read_b128 v[190:193], v229 offset:33376
	v_exp_f32_e32 v225, v45
	v_add_f32_e32 v164, v224, v164
	v_cvt_pk_bf16_f32 v211, v224, v225
	v_add_f32_e64 v164, v225, v164
	v_exp_f32_e32 v222, v46
	s_waitcnt lgkmcnt(3)
	v_mfma_f32_32x32x16_bf16 v[82:97], v[198:201], v[122:125], v[82:97]
	ds_read_b128 v[194:197], v229 offset:26752
	v_exp_f32_e32 v223, v47
	v_add_f32_e32 v164, v222, v164
	v_cvt_pk_bf16_f32 v212, v222, v223
	v_add_f32_e64 v164, v223, v164
	v_exp_f32_e32 v224, v48
	s_waitcnt lgkmcnt(3)
	v_mfma_f32_32x32x16_bf16 v[98:113], v[182:185], v[122:125], v[98:113]
	ds_read_b128 v[198:201], v229 offset:33408
	v_exp_f32_e32 v225, v49
	v_add_f32_e32 v164, v224, v164
	v_cvt_pk_bf16_f32 v213, v224, v225
	v_add_f32_e64 v164, v225, v164
	v_exp_f32_e32 v222, v50
	s_waitcnt lgkmcnt(3)
	v_mfma_f32_32x32x16_bf16 v[82:97], v[186:189], v[126:129], v[82:97]
	ds_read_b128 v[182:185], v229 offset:26784
	v_exp_f32_e32 v223, v51
	v_add_f32_e32 v164, v222, v164
	v_cvt_pk_bf16_f32 v214, v222, v223
	v_add_f32_e64 v164, v223, v164
	v_exp_f32_e32 v224, v52
	s_waitcnt lgkmcnt(3)
	v_mfma_f32_32x32x16_bf16 v[98:113], v[190:193], v[126:129], v[98:113]
	ds_read_b128 v[186:189], v229 offset:33440
	v_exp_f32_e32 v225, v53
	v_add_f32_e32 v164, v224, v164
	v_cvt_pk_bf16_f32 v215, v224, v225
	v_add_f32_e64 v164, v225, v164
	v_exp_f32_e32 v222, v54
	s_waitcnt lgkmcnt(3)
	v_mfma_f32_32x32x16_bf16 v[82:97], v[194:197], v[130:133], v[82:97]
	ds_read_b128 v[190:193], v181 offset:39936
	v_exp_f32_e32 v223, v55
	v_add_f32_e32 v164, v222, v164
	v_cvt_pk_bf16_f32 v216, v222, v223
	v_add_f32_e64 v164, v223, v164
	v_exp_f32_e32 v224, v56
	s_waitcnt lgkmcnt(3)
	v_mfma_f32_32x32x16_bf16 v[98:113], v[198:201], v[130:133], v[98:113]
	ds_read_b128 v[194:197], v181 offset:44544
	v_exp_f32_e32 v225, v57
	v_add_f32_e32 v164, v224, v164
	v_cvt_pk_bf16_f32 v217, v224, v225
	v_add_f32_e64 v164, v225, v164
	v_exp_f32_e32 v222, v58
	s_waitcnt lgkmcnt(3)
	v_mfma_f32_32x32x16_bf16 v[82:97], v[182:185], v[134:137], v[82:97]
	ds_read_b128 v[198:201], v181 offset:39968
	v_exp_f32_e32 v223, v59
	v_add_f32_e32 v164, v222, v164
	v_cvt_pk_bf16_f32 v218, v222, v223
	v_add_f32_e64 v164, v223, v164
	v_exp_f32_e32 v224, v60
	s_waitcnt lgkmcnt(3)
	v_mfma_f32_32x32x16_bf16 v[98:113], v[186:189], v[134:137], v[98:113]
	ds_read_b128 v[182:185], v181 offset:44576
	v_exp_f32_e32 v225, v61
	v_add_f32_e32 v164, v224, v164
	v_cvt_pk_bf16_f32 v219, v224, v225
	v_add_f32_e64 v164, v225, v164
	v_exp_f32_e32 v222, v62
	s_waitcnt lgkmcnt(3)
	v_mfma_f32_32x32x16_bf16 v[2:17], v[190:193], v[206:209], v[2:17]
	ds_read_b128 v[186:189], v181 offset:40000
	v_exp_f32_e32 v223, v63
	v_add_f32_e32 v164, v222, v164
	v_cvt_pk_bf16_f32 v220, v222, v223
	v_add_f32_e64 v164, v223, v164
	v_exp_f32_e32 v224, v64
	s_waitcnt lgkmcnt(3)
	v_mfma_f32_32x32x16_bf16 v[18:33], v[194:197], v[206:209], v[18:33]
	ds_read_b128 v[190:193], v181 offset:44608
	v_exp_f32_e32 v225, v65
	v_add_f32_e32 v164, v224, v164
	v_cvt_pk_bf16_f32 v221, v224, v225
	v_add_f32_e64 v164, v225, v164
	s_mov_b32 s13, s20
	s_mov_b32 s20, s19
	s_add_i32 s19, s19, 1
	s_cmp_eq_u32 s19, s9
	s_cselect_b32 s19, 0, s19
	s_nop 0
	s_waitcnt lgkmcnt(3)
	s_waitcnt vmcnt(2)
	v_mfma_f32_32x32x16_bf16 v[2:17], v[198:201], v[210:213], v[2:17]
	ds_read_b128 v[194:197], v181 offset:40032
	v_max3_f32 v224, v82, v83, v84
	v_max3_f32 v225, v98, v99, v100
	v_max3_f32 v224, v224, v85, v86
	v_max3_f32 v225, v225, v101, v102
	ds_write_b128 v172, v[146:149] offset:45056
	v_lshl_add_u32 v222, s19, 17, v178
	global_load_dwordx4 v[146:149], v222, s[52:53]
	s_waitcnt lgkmcnt(4)
	s_and_b64 vcc, exec, s[2:3]
	v_mfma_f32_32x32x16_bf16 v[18:33], v[182:185], v[210:213], v[18:33]
	ds_read_b128 v[198:201], v181 offset:44640
	v_max3_f32 v224, v224, v87, v88
	v_max3_f32 v225, v225, v103, v104
	v_max3_f32 v224, v224, v89, v90
	v_max3_f32 v225, v225, v105, v106
	s_cbranch_vccz .Lmla_p18_nope
	s_nop 0
	ds_write_b128 v176, v[138:141] offset:45184
	v_lshl_add_u32 v222, s19, 12, v179
	global_load_dwordx4 v[138:141], v222, s[62:63]
.Lmla_p18_nope:
	s_waitcnt lgkmcnt(4)
	s_nop 0
	v_mfma_f32_32x32x16_bf16 v[2:17], v[186:189], v[214:217], v[2:17]
	ds_read_b128 v[182:185], v174
	v_max3_f32 v224, v224, v91, v92
	v_max3_f32 v225, v225, v107, v108
	v_max3_f32 v224, v224, v93, v94
	v_max3_f32 v225, v225, v109, v110
	ds_write_b128 v173, v[142:145] offset:13312
	v_lshl_add_u32 v222, s13, 7, v168
	global_load_dwordx4 v[142:145], v222, s[56:57]
	s_waitcnt lgkmcnt(5)
	s_nop 0
	v_mfma_f32_32x32x16_bf16 v[18:33], v[190:193], v[214:217], v[18:33]
	ds_read_b128 v[186:189], v174 offset:6656
	v_max3_f32 v224, v224, v95, v96
	v_max3_f32 v225, v225, v111, v112
	v_max3_f32 v224, v224, v97, v113
	v_max_f32_e64 v224, v224, v225
	s_waitcnt lgkmcnt(5)
	v_mov_b32_e32 v225, v224
	v_mfma_f32_32x32x16_bf16 v[2:17], v[194:197], v[218:221], v[2:17]
	ds_read_b128 v[190:193], v174 offset:32
	v_add_f32_e32 v1, v1, v164
	s_add_i32 s11, s11, 1
	v_permlane32_swap_b32_e32 v224, v225
	s_cmp_eq_u32 s9, s11
	v_max_f32_e64 v167, v224, v225
	v_cmp_lt_f32_e32 vcc, s66, v167
	s_waitcnt lgkmcnt(4)
	v_mfma_f32_32x32x16_bf16 v[18:33], v[198:201], v[218:221], v[18:33]
	ds_read_b128 v[194:197], v174 offset:6688
	s_cbranch_scc1 .Lmla_exit_p18

; template <int VAR>
; __device__ __forceinline__ void attn_phase(LAS unsigned char* lds, const AttnP P, int vcu, int G, int wave_s) {
;     ...
;         for (int t = 0; t < nt; ++t) {
;             const bool hn = (t + 1 < nt);
;     ...
;                 if (ND0 == 6) {
;                     KR1(0); KR1(1); KR1(2); KR1(3); SB();
;                     QK1(0, negm); EX2(pc0, 0, w0.x); KR1(4); SB();
;                     QK1(1, negm); EX2(pc0, 2, w0.y); KR1(5); SB();
;                     QK1(2, pn0); EX2(pc0, 4, w0.z); KR1(6); SB();
;                     QK1(3, pn1); EX2(pc0, 6, w0.w); KR1(7); SB();
;                     QK1(4, pn0); EX2(pc0, 8, w1.x); KR1(8); SB();
;                     QK1(5, pn1); EX2(pc0, 10, w1.y); KR1(9); SB();
;                     QK1(6, pn0); EX2(pc0, 12, w1.z); KR1(10); SB();
;                     QK1(7, pn1); EX2(pc0, 14, w1.w); KR1(11); SB();
;                     QK1(8, pn0); EX2(pc1, 0, w2.x); VR1(0); SB();
;                     QK1(9, pn1); EX2(pc1, 2, w2.y); VR1(1); SB();
;                     QK1(10, pn0); EX2(pc1, 4, w2.z); VR1(2); SB();
;                     QK1(11, pn1); EX2(pc1, 6, w2.w); VR1(3); SB();
;                 } else {
;                     KR1(0); KR1(1); KR1(2); KR1(3); SB();
;                     QK1(0, negm); EX2(pc0, 0, w0.x); EX2(pc0, 2, w0.y); KR1(4); SB();
;                     QK1(1, negm); EX2(pc0, 4, w0.z); EX2(pc0, 6, w0.w); KR1(5); SB();
;                     QK1(2, pn0); EX2(pc0, 8, w1.x); EX2(pc0, 10, w1.y); KR1(6); SB();
;                     QK1(3, pn1); EX2(pc0, 12, w1.z); EX2(pc0, 14, w1.w); KR1(7); SB();
;                     QK1(4, pn0); EX2(pc1, 0, w2.x); VR1(0); SB();
;                     QK1(5, pn1); EX2(pc1, 2, w2.y); VR1(1); SB();
;                     QK1(6, pn0); EX2(pc1, 4, w2.z); VR1(2); SB();
;                     QK1(7, pn1); EX2(pc1, 6, w2.w); VR1(3); SB();
;                 }
;                 PV1(0, w0); EX2(pc1, 8, w3.x); VR1(4); SB();
;                 PV1(1, w0); EX2(pc1, 10, w3.y); VR1(5); SB();
;                 PV1(2, w1); EX2(pc1, 12, w3.z); VR1(6); SB();
;                 PV1(3, w1); EX2(pc1, 14, w3.w); VR1(7); SB();
;                 lrun += sacc;
;                 PV1(4, w2); MASK_TILE(pn0, pn1, t + 1); SB();
;                 PV1(5, w2); SB();
;                 PV1(6, w3); SB();
;                 PV1(7, w3); rmn = rowmax32(pn0, pn1); if (!USE_NEGM) rmn -= mref; SB();
.Lmla_p19_go:
	v_exp_f32_e32 v222, v82
	v_exp_f32_e32 v223, v83
	v_add_f32_e32 v164, 0, v222
	v_add_f32_e32 v164, v223, v164
	v_cvt_pk_bf16_f32 v206, v222, v223
	v_exp_f32_e32 v224, v84
	v_exp_f32_e32 v225, v85
	v_add_f32_e32 v164, v224, v164
	v_add_f32_e32 v164, v225, v164
	v_cvt_pk_bf16_f32 v207, v224, v225
	v_exp_f32_e32 v222, v86
	s_waitcnt lgkmcnt(4)
	v_mfma_f32_32x32x16_bf16 v[34:49], v[182:185], v[114:117], v[66:81]
	ds_read_b128 v[198:201], v174 offset:64
	v_exp_f32_e32 v223, v87
	v_add_f32_e32 v164, v222, v164
	v_cvt_pk_bf16_f32 v208, v222, v223
	v_add_f32_e64 v164, v223, v164
	v_exp_f32_e32 v224, v88
	s_waitcnt lgkmcnt(3)
	v_mfma_f32_32x32x16_bf16 v[50:65], v[186:189], v[114:117], v[66:81]
	ds_read_b128 v[182:185], v174 offset:6720
	v_exp_f32_e32 v225, v89
	v_add_f32_e32 v164, v224, v164
	v_cvt_pk_bf16_f32 v209, v224, v225
	v_add_f32_e64 v164, v225, v164
	v_exp_f32_e32 v222, v90
	s_waitcnt lgkmcnt(3)
	v_mfma_f32_32x32x16_bf16 v[34:49], v[190:193], v[118:121], v[34:49]
	ds_read_b128 v[186:189], v174 offset:96
	v_exp_f32_e32 v223, v91
	v_add_f32_e32 v164, v222, v164
	v_cvt_pk_bf16_f32 v210, v222, v223
	v_add_f32_e64 v164, v223, v164
	v_exp_f32_e32 v224, v92
	s_waitcnt lgkmcnt(3)
	v_mfma_f32_32x32x16_bf16 v[50:65], v[194:197], v[118:121], v[50:65]
	ds_read_b128 v[190:193], v174 offset:6752
	v_exp_f32_e32 v225, v93
	v_add_f32_e32 v164, v224, v164
	v_cvt_pk_bf16_f32 v211, v224, v225
	v_add_f32_e64 v164, v225, v164
	v_exp_f32_e32 v222, v94
	s_waitcnt lgkmcnt(3)
	v_mfma_f32_32x32x16_bf16 v[34:49], v[198:201], v[122:125], v[34:49]
	ds_read_b128 v[194:197], v174 offset:128
	v_exp_f32_e32 v223, v95
	v_add_f32_e32 v164, v222, v164
	v_cvt_pk_bf16_f32 v212, v222, v223
	v_add_f32_e64 v164, v223, v164
	v_exp_f32_e32 v224, v96
	s_waitcnt lgkmcnt(3)
	v_mfma_f32_32x32x16_bf16 v[50:65], v[182:185], v[122:125], v[50:65]
	ds_read_b128 v[198:201], v174 offset:6784
	v_exp_f32_e32 v225, v97
	v_add_f32_e32 v164, v224, v164
	v_cvt_pk_bf16_f32 v213, v224, v225
	v_add_f32_e64 v164, v225, v164
	v_exp_f32_e32 v222, v98
	s_waitcnt lgkmcnt(3)
	v_mfma_f32_32x32x16_bf16 v[34:49], v[186:189], v[126:129], v[34:49]
	ds_read_b128 v[182:185], v174 offset:160
	v_exp_f32_e32 v223, v99
	v_add_f32_e32 v164, v222, v164
	v_cvt_pk_bf16_f32 v214, v222, v223
	v_add_f32_e64 v164, v223, v164
	v_exp_f32_e32 v224, v100
	s_waitcnt lgkmcnt(3)
	v_mfma_f32_32x32x16_bf16 v[50:65], v[190:193], v[126:129], v[50:65]
	ds_read_b128 v[186:189], v174 offset:6816
	v_exp_f32_e32 v225, v101
	v_add_f32_e32 v164, v224, v164
	v_cvt_pk_bf16_f32 v215, v224, v225
	v_add_f32_e64 v164, v225, v164
	v_exp_f32_e32 v222, v102
	s_waitcnt lgkmcnt(3)
	v_mfma_f32_32x32x16_bf16 v[34:49], v[194:197], v[130:133], v[34:49]
	ds_read_b128 v[190:193], v181 offset:49152
	v_exp_f32_e32 v223, v103
	v_add_f32_e32 v164, v222, v164
	v_cvt_pk_bf16_f32 v216, v222, v223
	v_add_f32_e64 v164, v223, v164
	v_exp_f32_e32 v224, v104
	s_waitcnt lgkmcnt(3)
	v_mfma_f32_32x32x16_bf16 v[50:65], v[198:201], v[130:133], v[50:65]
	ds_read_b128 v[194:197], v181 offset:53760
	v_exp_f32_e32 v225, v105
	v_add_f32_e32 v164, v224, v164
	v_cvt_pk_bf16_f32 v217, v224, v225
	v_add_f32_e64 v164, v225, v164
	v_exp_f32_e32 v222, v106
	s_waitcnt lgkmcnt(3)
	v_mfma_f32_32x32x16_bf16 v[34:49], v[182:185], v[134:137], v[34:49]
	ds_read_b128 v[198:201], v181 offset:49184
	v_exp_f32_e32 v223, v107
	v_add_f32_e32 v164, v222, v164
	v_cvt_pk_bf16_f32 v218, v222, v223
	v_add_f32_e64 v164, v223, v164
	v_exp_f32_e32 v224, v108
	s_waitcnt lgkmcnt(3)
	v_mfma_f32_32x32x16_bf16 v[50:65], v[186:189], v[134:137], v[50:65]
	ds_read_b128 v[182:185], v181 offset:53792
	v_exp_f32_e32 v225, v109
	v_add_f32_e32 v164, v224, v164
	v_cvt_pk_bf16_f32 v219, v224, v225
	v_add_f32_e64 v164, v225, v164
	v_exp_f32_e32 v222, v110
	s_waitcnt lgkmcnt(3)
	v_mfma_f32_32x32x16_bf16 v[2:17], v[190:193], v[206:209], v[2:17]
	ds_read_b128 v[186:189], v181 offset:49216
	v_exp_f32_e32 v223, v111
	v_add_f32_e32 v164, v222, v164
	v_cvt_pk_bf16_f32 v220, v222, v223
	v_add_f32_e64 v164, v223, v164
	v_exp_f32_e32 v224, v112
	s_waitcnt lgkmcnt(3)
	v_mfma_f32_32x32x16_bf16 v[18:33], v[194:197], v[206:209], v[18:33]
	ds_read_b128 v[190:193], v181 offset:53824
	v_exp_f32_e32 v225, v113
	v_add_f32_e32 v164, v224, v164
	v_cvt_pk_bf16_f32 v221, v224, v225
	v_add_f32_e64 v164, v225, v164
	s_mov_b32 s13, s20
	s_mov_b32 s20, s19
	s_add_i32 s19, s19, 1
	s_cmp_eq_u32 s19, s9
	s_cselect_b32 s19, 0, s19
	s_nop 0
	s_waitcnt lgkmcnt(3)
	s_waitcnt vmcnt(2)
	v_mfma_f32_32x32x16_bf16 v[2:17], v[198:201], v[210:213], v[2:17]
	ds_read_b128 v[194:197], v181 offset:49248
	v_max3_f32 v224, v34, v35, v36
	v_max3_f32 v225, v50, v51, v52
	v_max3_f32 v224, v224, v37, v38
	v_max3_f32 v225, v225, v53, v54
	ds_write_b128 v172, v[150:153] offset:58368
	v_lshl_add_u32 v222, s19, 17, v178
	global_load_dwordx4 v[150:153], v222, s[52:53]
	s_waitcnt lgkmcnt(4)
	s_and_b64 vcc, exec, s[2:3]
	v_mfma_f32_32x32x16_bf16 v[18:33], v[182:185], v[210:213], v[18:33]
	ds_read_b128 v[198:201], v181 offset:53856
	v_max3_f32 v224, v224, v39, v40
	v_max3_f32 v225, v225, v55, v56
	v_max3_f32 v224, v224, v41, v42
	v_max3_f32 v225, v225, v57, v58
	s_cbranch_vccz .Lmla_p19_nope
	s_nop 0
	ds_write_b128 v176, v[160:163] offset:58496
	v_lshl_add_u32 v222, s19, 12, v179
	global_load_dwordx4 v[160:163], v222, s[62:63]
.Lmla_p19_nope:
	s_waitcnt lgkmcnt(4)
	s_nop 0
	v_mfma_f32_32x32x16_bf16 v[2:17], v[186:189], v[214:217], v[2:17]
	ds_read_b128 v[182:185], v174 offset:22528
	v_max3_f32 v224, v224, v43, v44
	v_max3_f32 v225, v225, v59, v60
	v_max3_f32 v224, v224, v45, v46
	v_max3_f32 v225, v225, v61, v62
	ds_write_b128 v173, v[202:205] offset:35840
	v_lshl_add_u32 v222, s13, 7, v168
	global_load_dwordx4 v[202:205], v222, s[56:57]
	s_waitcnt lgkmcnt(5)
	s_nop 0
	v_mfma_f32_32x32x16_bf16 v[18:33], v[190:193], v[214:217], v[18:33]
	ds_read_b128 v[186:189], v174 offset:29184
	v_max3_f32 v224, v224, v47, v48
	v_max3_f32 v225, v225, v63, v64
	v_max3_f32 v224, v224, v49, v65
	v_max_f32_e64 v224, v224, v225
	s_waitcnt lgkmcnt(5)
	v_mov_b32_e32 v225, v224
	v_mfma_f32_32x32x16_bf16 v[2:17], v[194:197], v[218:221], v[2:17]
	ds_read_b128 v[190:193], v174 offset:22560
	v_add_f32_e32 v1, v1, v164
	s_add_i32 s11, s11, 1
	v_permlane32_swap_b32_e32 v224, v225
	s_cmp_eq_u32 s9, s11
	v_max_f32_e64 v167, v224, v225
	v_cmp_lt_f32_e32 vcc, s66, v167
	s_waitcnt lgkmcnt(4)
	v_mfma_f32_32x32x16_bf16 v[18:33], v[198:201], v[218:221], v[18:33]
	ds_read_b128 v[194:197], v174 offset:29216
	s_waitcnt lgkmcnt(3)
	s_barrier
	s_cbranch_scc1 .Lmla_exit_p19
	s_branch .Lmla_p0
